# per-interval priority flips re-added but executed on the LOAD side of each barrier (raise just before the pre-MFMA barrier, lower just after the post-MFMA barrier); static raise removed; on top of v05
# baseline (speedup 1.0000x reference)
; #define LAS __attribute__((address_space(3)))
; __global__ void __launch_bounds__(NTHREADS, 2) mk_fwd(Params P_arg) {
;     extern __shared__ __attribute__((aligned(16))) unsigned char lds_raw[];
;     LAS unsigned char* lds = (LAS unsigned char*)lds_raw;
;     cg::grid_group grid = cg::this_grid();
;     volatile LAS unsigned* bar_st = (volatile LAS unsigned*)(lds + LDS_BYTES - 64);
;     if (threadIdx.x == 0) { bar_st[0] = 0u; bar_st[1] = 0u; }
;     __syncthreads();
;     const XcdBarrier xbar = xcd_barrier_post((unsigned*)(P_arg.ws + WS_CTL), bar_st);
_Z6mk_fwd6Params:
	v_readfirstlane_b32 s98, v0
	s_nop 3
	s_and_b32 s98, s98, 0x3ff
	s_lshr_b32 s98, s98, 6
	s_cmp_ge_u32 s98, 4
	s_cbranch_scc0 .Lsprio_skip
.Lsprio_skip:
	s_load_dwordx4 s[48:51], s[0:1], 0x110
	s_load_dwordx2 s[90:91], s[0:1], 0x120
	s_mov_b32 s88, s2
	s_add_u32 s2, s0, 0x120
	v_writelane_b32 v248, s0, 0
	s_addc_u32 s3, s1, 0
	v_and_b32_e32 v179, 0x3ff, v0
	v_writelane_b32 v248, s1, 1
	v_writelane_b32 v248, s2, 2
	s_nop 1
	v_writelane_b32 v248, s3, 3
	v_cmp_eq_u32_e64 s[2:3], 0, v179
	s_mov_b64 s[0:1], exec
	s_nop 0
	v_writelane_b32 v248, s2, 4
	s_nop 1
	v_writelane_b32 v248, s3, 5
	s_and_b64 s[2:3], s[0:1], s[2:3]
	s_mov_b64 exec, s[2:3]
	s_cbranch_execz .LBB0_2
	s_add_i32 s2, 0, 0x23fc0
	v_mov_b32_e32 v1, 0
	v_mov_b32_e32 v2, s2
	s_add_i32 s2, 0, 0x23fc4
	ds_write_b32 v2, v1
	v_mov_b32_e32 v2, s2
	ds_write_b32 v2, v1

; #define PG8_STAGE(bufoff, gbase, voff) do { _Pragma("unroll") for (int _i = 0; _i < 2; ++_i) \
;         __builtin_amdgcn_global_load_lds((const unsigned*)((const char*)(gbase) + (voff)[_i]), (LAS unsigned*)(lds + (bufoff) + ldsw + _i * 8192), 16, 0, 0); } while (0)
; #define PG8_LDA(dst, b, h) do { _Pragma("unroll") for (int m = 0; m < 4; ++m) _Pragma("unroll") for (int k = 0; k < 2; ++k) dst[m][k] = *(const LAS bf16x8*)(lds + PG8_SA(b, h) + aoff + m * 2048 + k * 1024); } while (0)
; #define PG8_LDB(dst, b, h) do { _Pragma("unroll") for (int n = 0; n < 2; ++n) _Pragma("unroll") for (int k = 0; k < 2; ++k) dst[n][k] = *(const LAS bf16x8*)(lds + PG8_SB(b, h) + boff + n * 2048 + k * 1024); } while (0)
; #define PG8_MMA(ai, bj, At, Bt) do { __builtin_amdgcn_s_setprio(1); _Pragma("unroll") for (int m = 0; m < 4; ++m) _Pragma("unroll") for (int n = 0; n < 2; ++n) _Pragma("unroll") for (int k = 0; k < 2; ++k) \
;         acc[ai][bj][m][n] = __builtin_amdgcn_mfma_f32_16x16x32_bf16(Bt[n][k], At[m][k], acc[ai][bj][m][n], 0, 0, 0); __builtin_amdgcn_s_setprio(0); } while (0)
; #define PG8_WAIT_V(n) asm volatile("s_waitcnt vmcnt(" #n ")" ::: "memory")
; #define PG8_WAIT_L(n) asm volatile("s_waitcnt lgkmcnt(" #n ")" ::: "memory")
; template <int MODE, class EpiT, class Sched>
; __device__ __forceinline__ void gemm_phase(LAS unsigned char* lds, const Gemm g, const Sched& S, const EpiT& E) {
;     ...
;         for (int t = 0; t < nt; t += 2) {
;             const bool last = (t == nt - 2);
;             const char* a1 = cA + (size_t)(t + 1) * kstep;
;             const char* a2 = last ? nA : cA + (size_t)(t + 2) * kstep; const char* b2 = last ? nB : cB + (size_t)(t + 2) * kstep;
;             const char* a3 = a2 + kstep; const char* b3 = b2 + kstep;
;             PG8_LDB(B0, 0, 0); PG8_SCHED; PG8_LDA(At, 0, 0); PG8_STAGE(PG8_SA(1, 1), a1 + hstep, voffA);
;             PG8_WAIT_L(8); PG8_BAR; PG8_WAIT_L(0); PG8_MMA(0, 0, At, B0); PG8_BAR; PG8_SCHED;
;             PG8_LDB(B1, 0, 1); PG8_STAGE(PG8_SB(0, 0), b2, voffB);
;             PG8_BAR; PG8_WAIT_L(0); PG8_MMA(0, 1, At, B1); PG8_BAR;
;             PG8_LDA(At, 0, 1); PG8_STAGE(PG8_SA(0, 0), a2, voffA);
;             PG8_BAR; PG8_WAIT_L(0); PG8_MMA(1, 0, At, B0); PG8_BAR; PG8_SCHED;
;             PG8_STAGE(PG8_SB(0, 1), b2 + hstep, voffB);
;             PG8_WAIT_V(6); PG8_BAR; PG8_MMA(1, 1, At, B1); PG8_BAR;
.LBB0_115:
	s_add_i32 s58, s52, 2
	s_add_u32 s59, s44, 0x80
	s_addc_u32 s53, s45, 0
	s_add_u32 s100, s44, s78
	s_addc_u32 s101, s45, 0
	s_add_i32 s91, 0, 0x10000
	ds_read_b128 v[70:73], v249
	ds_read_b128 v[74:77], v249 offset:1024
	ds_read_b128 v[82:85], v249 offset:2048
	ds_read_b128 v[86:89], v249 offset:3072
	s_cmp_eq_u32 s57, s52
	s_cselect_b32 s52, s4, s59
	s_cselect_b32 s53, s5, s53
	s_cselect_b32 s75, s47, vcc_hi
	s_cselect_b32 s74, s46, vcc_lo
	s_add_i32 m0, s20, 0xc000
	ds_read_b128 v[138:141], v194
	ds_read_b128 v[142:145], v194 offset:1024
	ds_read_b128 v[146:149], v194 offset:2048
	ds_read_b128 v[154:157], v194 offset:3072
	ds_read_b128 v[162:165], v194 offset:4096
	ds_read_b128 v[166:169], v194 offset:5120
	ds_read_b128 v[170:173], v194 offset:6144
	global_load_lds_dwordx4 v0, s[100:101]
	s_add_i32 m0, s20, 0xe000
	ds_read_b128 v[184:187], v194 offset:7168
	global_load_lds_dwordx4 v174, s[100:101]
	s_waitcnt lgkmcnt(8)
	s_setprio 1
	s_barrier
	s_waitcnt lgkmcnt(0)
	v_mfma_f32_16x16x32_bf16 v[158:161], v[70:73], v[138:141], v[158:161]
	v_mfma_f32_16x16x32_bf16 v[150:153], v[82:85], v[138:141], v[150:153]
	v_mfma_f32_16x16x32_bf16 v[126:129], v[70:73], v[146:149], v[126:129]
	v_mfma_f32_16x16x32_bf16 v[122:125], v[82:85], v[146:149], v[122:125]
	v_mfma_f32_16x16x32_bf16 v[110:113], v[70:73], v[162:165], v[110:113]
	v_mfma_f32_16x16x32_bf16 v[106:109], v[82:85], v[162:165], v[106:109]
	v_mfma_f32_16x16x32_bf16 v[94:97], v[70:73], v[170:173], v[94:97]
	v_mfma_f32_16x16x32_bf16 v[90:93], v[82:85], v[170:173], v[90:93]
	v_mfma_f32_16x16x32_bf16 v[158:161], v[74:77], v[142:145], v[158:161]
	v_mfma_f32_16x16x32_bf16 v[150:153], v[86:89], v[142:145], v[150:153]
	v_mfma_f32_16x16x32_bf16 v[126:129], v[74:77], v[154:157], v[126:129]
	v_mfma_f32_16x16x32_bf16 v[122:125], v[86:89], v[154:157], v[122:125]
	v_mfma_f32_16x16x32_bf16 v[110:113], v[74:77], v[166:169], v[110:113]
	v_mfma_f32_16x16x32_bf16 v[106:109], v[86:89], v[166:169], v[106:109]
	v_mfma_f32_16x16x32_bf16 v[94:97], v[74:77], v[184:187], v[94:97]
	v_mfma_f32_16x16x32_bf16 v[90:93], v[86:89], v[184:187], v[90:93]
	s_barrier
	s_setprio 0
	s_add_i32 s59, 0, 0x14000
	s_add_i32 s91, s91, s9
	s_add_u32 s98, s74, 0x80
	s_addc_u32 s99, s75, 0
	s_mov_b32 m0, s91
	ds_read_b128 v[188:191], v249 offset:16384
	ds_read_b128 v[196:199], v249 offset:17408
	ds_read_b128 v[220:223], v249 offset:18432
	global_load_lds_dwordx4 v0, s[74:75]
	s_add_i32 m0, s91, 0x2000
	ds_read_b128 v[224:227], v249 offset:19456
	global_load_lds_dwordx4 v174, s[74:75]
	s_setprio 1
	s_barrier
	s_waitcnt lgkmcnt(0)
	v_mfma_f32_16x16x32_bf16 v[134:137], v[188:191], v[138:141], v[134:137]
	v_mfma_f32_16x16x32_bf16 v[130:133], v[220:223], v[138:141], v[130:133]
	v_mfma_f32_16x16x32_bf16 v[118:121], v[188:191], v[146:149], v[118:121]
	v_mfma_f32_16x16x32_bf16 v[114:117], v[220:223], v[146:149], v[114:117]
	v_mfma_f32_16x16x32_bf16 v[102:105], v[188:191], v[162:165], v[102:105]
	v_mfma_f32_16x16x32_bf16 v[98:101], v[220:223], v[162:165], v[98:101]
	v_mfma_f32_16x16x32_bf16 v[78:81], v[188:191], v[170:173], v[78:81]
	v_mfma_f32_16x16x32_bf16 v[66:69], v[220:223], v[170:173], v[66:69]
	v_mfma_f32_16x16x32_bf16 v[134:137], v[196:199], v[142:145], v[134:137]
	v_mfma_f32_16x16x32_bf16 v[130:133], v[224:227], v[142:145], v[130:133]
	v_mfma_f32_16x16x32_bf16 v[118:121], v[196:199], v[154:157], v[118:121]
	v_mfma_f32_16x16x32_bf16 v[114:117], v[224:227], v[154:157], v[114:117]
	v_mfma_f32_16x16x32_bf16 v[102:105], v[196:199], v[166:169], v[102:105]
	v_mfma_f32_16x16x32_bf16 v[98:101], v[224:227], v[166:169], v[98:101]
	v_mfma_f32_16x16x32_bf16 v[78:81], v[196:199], v[184:187], v[78:81]
	v_mfma_f32_16x16x32_bf16 v[66:69], v[224:227], v[184:187], v[66:69]
	s_barrier
	s_setprio 0
	s_mov_b32 m0, s20
	s_add_u32 s100, s52, 0x80
	s_addc_u32 s101, s53, 0
	ds_read_b128 v[138:141], v194 offset:16384
	ds_read_b128 v[142:145], v194 offset:17408
	ds_read_b128 v[146:149], v194 offset:18432
	ds_read_b128 v[154:157], v194 offset:19456
	ds_read_b128 v[162:165], v194 offset:20480
	ds_read_b128 v[166:169], v194 offset:21504
	ds_read_b128 v[170:173], v194 offset:22528
	global_load_lds_dwordx4 v0, s[52:53]
	s_mov_b32 m0, s21
	ds_read_b128 v[184:187], v194 offset:23552
	global_load_lds_dwordx4 v174, s[52:53]
	s_setprio 1
	s_barrier
	s_waitcnt lgkmcnt(0)
	v_mfma_f32_16x16x32_bf16 v[62:65], v[70:73], v[138:141], v[62:65]
	v_mfma_f32_16x16x32_bf16 v[58:61], v[82:85], v[138:141], v[58:61]
	v_mfma_f32_16x16x32_bf16 v[46:49], v[70:73], v[146:149], v[46:49]
	v_mfma_f32_16x16x32_bf16 v[42:45], v[82:85], v[146:149], v[42:45]
	v_mfma_f32_16x16x32_bf16 v[30:33], v[70:73], v[162:165], v[30:33]
	v_mfma_f32_16x16x32_bf16 v[26:29], v[82:85], v[162:165], v[26:29]
	v_mfma_f32_16x16x32_bf16 v[14:17], v[70:73], v[170:173], v[14:17]
	v_mfma_f32_16x16x32_bf16 v[10:13], v[82:85], v[170:173], v[10:13]
	v_mfma_f32_16x16x32_bf16 v[62:65], v[74:77], v[142:145], v[62:65]
	v_mfma_f32_16x16x32_bf16 v[58:61], v[86:89], v[142:145], v[58:61]
	v_mfma_f32_16x16x32_bf16 v[46:49], v[74:77], v[154:157], v[46:49]
	v_mfma_f32_16x16x32_bf16 v[42:45], v[86:89], v[154:157], v[42:45]
	v_mfma_f32_16x16x32_bf16 v[30:33], v[74:77], v[166:169], v[30:33]
	v_mfma_f32_16x16x32_bf16 v[26:29], v[86:89], v[166:169], v[26:29]
	v_mfma_f32_16x16x32_bf16 v[14:17], v[74:77], v[184:187], v[14:17]
	v_mfma_f32_16x16x32_bf16 v[10:13], v[86:89], v[184:187], v[10:13]
	s_barrier
	s_setprio 0
	s_add_u32 s74, s74, s78
	s_addc_u32 s75, s75, 0
	s_add_i32 s59, s59, s9
	s_mov_b32 m0, s59
	s_nop 0
	global_load_lds_dwordx4 v0, s[74:75]
	s_add_i32 m0, s59, 0x2000
	s_nop 0
	global_load_lds_dwordx4 v174, s[74:75]
	s_waitcnt vmcnt(6)
	s_setprio 1
	s_barrier
; #define PG8_STAGE(bufoff, gbase, voff) do { _Pragma("unroll") for (int _i = 0; _i < 2; ++_i) \
;         __builtin_amdgcn_global_load_lds((const unsigned*)((const char*)(gbase) + (voff)[_i]), (LAS unsigned*)(lds + (bufoff) + ldsw + _i * 8192), 16, 0, 0); } while (0)
; #define PG8_LDA(dst, b, h) do { _Pragma("unroll") for (int m = 0; m < 4; ++m) _Pragma("unroll") for (int k = 0; k < 2; ++k) dst[m][k] = *(const LAS bf16x8*)(lds + PG8_SA(b, h) + aoff + m * 2048 + k * 1024); } while (0)
; #define PG8_LDB(dst, b, h) do { _Pragma("unroll") for (int n = 0; n < 2; ++n) _Pragma("unroll") for (int k = 0; k < 2; ++k) dst[n][k] = *(const LAS bf16x8*)(lds + PG8_SB(b, h) + boff + n * 2048 + k * 1024); } while (0)
; #define PG8_MMA(ai, bj, At, Bt) do { __builtin_amdgcn_s_setprio(1); _Pragma("unroll") for (int m = 0; m < 4; ++m) _Pragma("unroll") for (int n = 0; n < 2; ++n) _Pragma("unroll") for (int k = 0; k < 2; ++k) \
;         acc[ai][bj][m][n] = __builtin_amdgcn_mfma_f32_16x16x32_bf16(Bt[n][k], At[m][k], acc[ai][bj][m][n], 0, 0, 0); __builtin_amdgcn_s_setprio(0); } while (0)
; #define PG8_WAIT_V(n) asm volatile("s_waitcnt vmcnt(" #n ")" ::: "memory")
; #define PG8_WAIT_L(n) asm volatile("s_waitcnt lgkmcnt(" #n ")" ::: "memory")
; #define PG8_BAR __builtin_amdgcn_s_barrier()
; #define PG8_SCHED __builtin_amdgcn_sched_barrier(0)
; template <int MODE, class EpiT, class Sched>
; __device__ __forceinline__ void gemm_phase(LAS unsigned char* lds, const Gemm g, const Sched& S, const EpiT& E) {
;     ...
;             PG8_WAIT_V(6); PG8_BAR; PG8_MMA(1, 1, At, B1); PG8_BAR;
;             PG8_LDB(B0, 1, 0); PG8_SCHED; PG8_LDA(At, 1, 0); PG8_STAGE(PG8_SA(0, 1), a2 + hstep, voffA);
;             PG8_WAIT_L(8); PG8_BAR; PG8_WAIT_L(0); PG8_MMA(0, 0, At, B0); PG8_BAR; PG8_SCHED;
;             PG8_LDB(B1, 1, 1); PG8_STAGE(PG8_SB(1, 0), b3, voffB);
;             PG8_BAR; PG8_WAIT_L(0); PG8_MMA(0, 1, At, B1); PG8_BAR;
;             PG8_LDA(At, 1, 1); PG8_STAGE(PG8_SA(1, 0), a3, voffA);
;             PG8_BAR; PG8_WAIT_L(0); PG8_MMA(1, 0, At, B0); PG8_BAR; PG8_SCHED;
	v_mfma_f32_16x16x32_bf16 v[54:57], v[188:191], v[138:141], v[54:57]
	v_mfma_f32_16x16x32_bf16 v[50:53], v[220:223], v[138:141], v[50:53]
	v_mfma_f32_16x16x32_bf16 v[38:41], v[188:191], v[146:149], v[38:41]
	v_mfma_f32_16x16x32_bf16 v[34:37], v[220:223], v[146:149], v[34:37]
	v_mfma_f32_16x16x32_bf16 v[22:25], v[188:191], v[162:165], v[22:25]
	v_mfma_f32_16x16x32_bf16 v[18:21], v[220:223], v[162:165], v[18:21]
	v_mfma_f32_16x16x32_bf16 v[6:9], v[188:191], v[170:173], v[6:9]
	v_mfma_f32_16x16x32_bf16 v[2:5], v[220:223], v[170:173], v[2:5]
	v_mfma_f32_16x16x32_bf16 v[54:57], v[196:199], v[142:145], v[54:57]
	v_mfma_f32_16x16x32_bf16 v[50:53], v[224:227], v[142:145], v[50:53]
	v_mfma_f32_16x16x32_bf16 v[38:41], v[196:199], v[154:157], v[38:41]
	v_mfma_f32_16x16x32_bf16 v[34:37], v[224:227], v[154:157], v[34:37]
	v_mfma_f32_16x16x32_bf16 v[22:25], v[196:199], v[166:169], v[22:25]
	v_mfma_f32_16x16x32_bf16 v[18:21], v[224:227], v[166:169], v[18:21]
	v_mfma_f32_16x16x32_bf16 v[6:9], v[196:199], v[184:187], v[6:9]
	v_mfma_f32_16x16x32_bf16 v[2:5], v[224:227], v[184:187], v[2:5]
	s_barrier
	s_setprio 0
	s_add_i32 s59, 0, 0x18000
	ds_read_b128 v[70:73], v249 offset:32768
	ds_read_b128 v[74:77], v249 offset:33792
	ds_read_b128 v[82:85], v249 offset:34816
	ds_read_b128 v[86:89], v249 offset:35840
	s_add_u32 s52, s52, s78
	s_addc_u32 s53, s53, 0
	s_mov_b32 m0, s22
	ds_read_b128 v[138:141], v194 offset:32768
	ds_read_b128 v[142:145], v194 offset:33792
	ds_read_b128 v[146:149], v194 offset:34816
	ds_read_b128 v[154:157], v194 offset:35840
	ds_read_b128 v[162:165], v194 offset:36864
	ds_read_b128 v[166:169], v194 offset:37888
	ds_read_b128 v[170:173], v194 offset:38912
	global_load_lds_dwordx4 v0, s[52:53]
	s_mov_b32 m0, s23
	ds_read_b128 v[184:187], v194 offset:39936
	global_load_lds_dwordx4 v174, s[52:53]
	s_waitcnt lgkmcnt(8)
	s_setprio 1
	s_barrier
	s_waitcnt lgkmcnt(0)
	v_mfma_f32_16x16x32_bf16 v[158:161], v[70:73], v[138:141], v[158:161]
	v_mfma_f32_16x16x32_bf16 v[150:153], v[82:85], v[138:141], v[150:153]
	v_mfma_f32_16x16x32_bf16 v[126:129], v[70:73], v[146:149], v[126:129]
	v_mfma_f32_16x16x32_bf16 v[122:125], v[82:85], v[146:149], v[122:125]
	v_mfma_f32_16x16x32_bf16 v[110:113], v[70:73], v[162:165], v[110:113]
	v_mfma_f32_16x16x32_bf16 v[106:109], v[82:85], v[162:165], v[106:109]
	v_mfma_f32_16x16x32_bf16 v[94:97], v[70:73], v[170:173], v[94:97]
	v_mfma_f32_16x16x32_bf16 v[90:93], v[82:85], v[170:173], v[90:93]
	v_mfma_f32_16x16x32_bf16 v[158:161], v[74:77], v[142:145], v[158:161]
	v_mfma_f32_16x16x32_bf16 v[150:153], v[86:89], v[142:145], v[150:153]
	v_mfma_f32_16x16x32_bf16 v[126:129], v[74:77], v[154:157], v[126:129]
	v_mfma_f32_16x16x32_bf16 v[122:125], v[86:89], v[154:157], v[122:125]
	v_mfma_f32_16x16x32_bf16 v[110:113], v[74:77], v[166:169], v[110:113]
	v_mfma_f32_16x16x32_bf16 v[106:109], v[86:89], v[166:169], v[106:109]
	v_mfma_f32_16x16x32_bf16 v[94:97], v[74:77], v[184:187], v[94:97]
	v_mfma_f32_16x16x32_bf16 v[90:93], v[86:89], v[184:187], v[90:93]
	s_barrier
	s_setprio 0
	s_add_i32 s52, 0, 0x1c000
	s_add_i32 s53, s59, s9
	s_mov_b32 m0, s53
	ds_read_b128 v[188:191], v249 offset:49152
	ds_read_b128 v[196:199], v249 offset:50176
	ds_read_b128 v[220:223], v249 offset:51200
	global_load_lds_dwordx4 v0, s[98:99]
	s_add_i32 m0, s53, 0x2000
	ds_read_b128 v[224:227], v249 offset:52224
	global_load_lds_dwordx4 v174, s[98:99]
	s_setprio 1
	s_barrier
	s_waitcnt lgkmcnt(0)
	v_mfma_f32_16x16x32_bf16 v[134:137], v[188:191], v[138:141], v[134:137]
	v_mfma_f32_16x16x32_bf16 v[130:133], v[220:223], v[138:141], v[130:133]
	v_mfma_f32_16x16x32_bf16 v[118:121], v[188:191], v[146:149], v[118:121]
	v_mfma_f32_16x16x32_bf16 v[114:117], v[220:223], v[146:149], v[114:117]
	v_mfma_f32_16x16x32_bf16 v[102:105], v[188:191], v[162:165], v[102:105]
	v_mfma_f32_16x16x32_bf16 v[98:101], v[220:223], v[162:165], v[98:101]
	v_mfma_f32_16x16x32_bf16 v[78:81], v[188:191], v[170:173], v[78:81]
	v_mfma_f32_16x16x32_bf16 v[66:69], v[220:223], v[170:173], v[66:69]
	v_mfma_f32_16x16x32_bf16 v[134:137], v[196:199], v[142:145], v[134:137]
	v_mfma_f32_16x16x32_bf16 v[130:133], v[224:227], v[142:145], v[130:133]
	v_mfma_f32_16x16x32_bf16 v[118:121], v[196:199], v[154:157], v[118:121]
	v_mfma_f32_16x16x32_bf16 v[114:117], v[224:227], v[154:157], v[114:117]
	v_mfma_f32_16x16x32_bf16 v[102:105], v[196:199], v[166:169], v[102:105]
	v_mfma_f32_16x16x32_bf16 v[98:101], v[224:227], v[166:169], v[98:101]
	v_mfma_f32_16x16x32_bf16 v[78:81], v[196:199], v[184:187], v[78:81]
	v_mfma_f32_16x16x32_bf16 v[66:69], v[224:227], v[184:187], v[66:69]
	s_barrier
; #define PG8_STAGE(bufoff, gbase, voff) do { _Pragma("unroll") for (int _i = 0; _i < 2; ++_i) \
;         __builtin_amdgcn_global_load_lds((const unsigned*)((const char*)(gbase) + (voff)[_i]), (LAS unsigned*)(lds + (bufoff) + ldsw + _i * 8192), 16, 0, 0); } while (0)
; #define PG8_LDA(dst, b, h) do { _Pragma("unroll") for (int m = 0; m < 4; ++m) _Pragma("unroll") for (int k = 0; k < 2; ++k) dst[m][k] = *(const LAS bf16x8*)(lds + PG8_SA(b, h) + aoff + m * 2048 + k * 1024); } while (0)
; #define PG8_MMA(ai, bj, At, Bt) do { __builtin_amdgcn_s_setprio(1); _Pragma("unroll") for (int m = 0; m < 4; ++m) _Pragma("unroll") for (int n = 0; n < 2; ++n) _Pragma("unroll") for (int k = 0; k < 2; ++k) \
;         acc[ai][bj][m][n] = __builtin_amdgcn_mfma_f32_16x16x32_bf16(Bt[n][k], At[m][k], acc[ai][bj][m][n], 0, 0, 0); __builtin_amdgcn_s_setprio(0); } while (0)
; #define PG8_WAIT_V(n) asm volatile("s_waitcnt vmcnt(" #n ")" ::: "memory")
; #define PG8_WAIT_L(n) asm volatile("s_waitcnt lgkmcnt(" #n ")" ::: "memory")
; #define PG8_BAR __builtin_amdgcn_s_barrier()
; #define PG8_SCHED __builtin_amdgcn_sched_barrier(0)
;     template <int mode> __device__ __forceinline__ void run(const f32x4 (&acc)[2][2][4][2], const Unit& u, int wr, int wc, int fr, int fq, const LAS float* sc) const {
;     ...
;             const int col0 = u.pn * BM + wc * 32 + 8 * fq;
;             f32x4 bv[2][2];
; #pragma unroll
;             for (int bj = 0; bj < 2; ++bj)
; #pragma unroll
;                 for (int n = 0; n < 2; ++n) bv[bj][n] = bias ? *(const f32x4*)(bias + col0 + bj * HALF + 4 * n) : (f32x4){0.f, 0.f, 0.f, 0.f};
; template <int MODE, class EpiT, class Sched>
; __device__ __forceinline__ void gemm_phase(LAS unsigned char* lds, const Gemm g, const Sched& S, const EpiT& E) {
;     ...
;             PG8_BAR; PG8_WAIT_L(0); PG8_MMA(0, 1, At, B1); PG8_BAR;
;             PG8_LDA(At, 1, 1); PG8_STAGE(PG8_SA(1, 0), a3, voffA);
;             PG8_BAR; PG8_WAIT_L(0); PG8_MMA(1, 0, At, B0); PG8_BAR; PG8_SCHED;
;             PG8_STAGE(PG8_SB(1, 1), b3 + hstep, voffB);
;             PG8_WAIT_V(6); PG8_BAR; PG8_MMA(1, 1, At, B1); PG8_BAR;
;         }
;         E.template run<MODE>(acc, cur, wr, wc, fr, fq, SC + ui * 256);
	s_setprio 0
	s_mov_b32 m0, s51
	ds_read_b128 v[138:141], v194 offset:49152
	ds_read_b128 v[142:145], v194 offset:50176
	ds_read_b128 v[146:149], v194 offset:51200
	ds_read_b128 v[154:157], v194 offset:52224
	ds_read_b128 v[162:165], v194 offset:53248
	ds_read_b128 v[166:169], v194 offset:54272
	ds_read_b128 v[170:173], v194 offset:55296
	global_load_lds_dwordx4 v0, s[100:101]
	s_mov_b32 m0, s56
	ds_read_b128 v[184:187], v194 offset:56320
	global_load_lds_dwordx4 v174, s[100:101]
	s_setprio 1
	s_barrier
	s_waitcnt lgkmcnt(0)
	v_mfma_f32_16x16x32_bf16 v[62:65], v[70:73], v[138:141], v[62:65]
	v_mfma_f32_16x16x32_bf16 v[58:61], v[82:85], v[138:141], v[58:61]
	v_mfma_f32_16x16x32_bf16 v[46:49], v[70:73], v[146:149], v[46:49]
	v_mfma_f32_16x16x32_bf16 v[42:45], v[82:85], v[146:149], v[42:45]
	v_mfma_f32_16x16x32_bf16 v[30:33], v[70:73], v[162:165], v[30:33]
	v_mfma_f32_16x16x32_bf16 v[26:29], v[82:85], v[162:165], v[26:29]
	v_mfma_f32_16x16x32_bf16 v[14:17], v[70:73], v[170:173], v[14:17]
	v_mfma_f32_16x16x32_bf16 v[10:13], v[82:85], v[170:173], v[10:13]
	v_mfma_f32_16x16x32_bf16 v[62:65], v[74:77], v[142:145], v[62:65]
	v_mfma_f32_16x16x32_bf16 v[58:61], v[86:89], v[142:145], v[58:61]
	v_mfma_f32_16x16x32_bf16 v[46:49], v[74:77], v[154:157], v[46:49]
	v_mfma_f32_16x16x32_bf16 v[42:45], v[86:89], v[154:157], v[42:45]
	v_mfma_f32_16x16x32_bf16 v[30:33], v[74:77], v[166:169], v[30:33]
	v_mfma_f32_16x16x32_bf16 v[26:29], v[86:89], v[166:169], v[26:29]
	v_mfma_f32_16x16x32_bf16 v[14:17], v[74:77], v[184:187], v[14:17]
	v_mfma_f32_16x16x32_bf16 v[10:13], v[86:89], v[184:187], v[10:13]
	s_barrier
	s_setprio 0
	s_add_i32 s52, s52, s9
	s_add_u32 s98, s98, s78
	s_addc_u32 s99, s99, 0
	s_mov_b32 m0, s52
	s_nop 0
	global_load_lds_dwordx4 v0, s[98:99]
	s_add_i32 m0, s52, 0x2000
	s_nop 0
	global_load_lds_dwordx4 v174, s[98:99]
	s_waitcnt vmcnt(6)
	s_setprio 1
	s_barrier
	v_mfma_f32_16x16x32_bf16 v[54:57], v[188:191], v[138:141], v[54:57]
	v_mfma_f32_16x16x32_bf16 v[50:53], v[220:223], v[138:141], v[50:53]
	v_mfma_f32_16x16x32_bf16 v[38:41], v[188:191], v[146:149], v[38:41]
	v_mfma_f32_16x16x32_bf16 v[34:37], v[220:223], v[146:149], v[34:37]
	v_mfma_f32_16x16x32_bf16 v[22:25], v[188:191], v[162:165], v[22:25]
	v_mfma_f32_16x16x32_bf16 v[18:21], v[220:223], v[162:165], v[18:21]
	v_mfma_f32_16x16x32_bf16 v[6:9], v[188:191], v[170:173], v[6:9]
	v_mfma_f32_16x16x32_bf16 v[2:5], v[220:223], v[170:173], v[2:5]
	v_mfma_f32_16x16x32_bf16 v[54:57], v[196:199], v[142:145], v[54:57]
	v_mfma_f32_16x16x32_bf16 v[50:53], v[224:227], v[142:145], v[50:53]
	v_mfma_f32_16x16x32_bf16 v[38:41], v[196:199], v[154:157], v[38:41]
	v_mfma_f32_16x16x32_bf16 v[34:37], v[224:227], v[154:157], v[34:37]
	v_mfma_f32_16x16x32_bf16 v[22:25], v[196:199], v[166:169], v[22:25]
	v_mfma_f32_16x16x32_bf16 v[18:21], v[224:227], v[166:169], v[18:21]
	v_mfma_f32_16x16x32_bf16 v[6:9], v[196:199], v[184:187], v[6:9]
	v_mfma_f32_16x16x32_bf16 v[2:5], v[224:227], v[184:187], v[2:5]
	s_barrier
	s_setprio 0
	s_add_u32 s44, s44, 0x100
	s_addc_u32 s45, s45, 0
	s_add_u32 vcc_lo, vcc_lo, 0x100
	s_addc_u32 vcc_hi, vcc_hi, 0
	s_cmp_ge_u32 s58, s50
	s_mov_b32 s52, s58
	s_cbranch_scc0 .LBB0_115
	v_lshl_or_b32 v184, s24, 8, v193
	v_ashrrev_i32_e32 v185, 31, v184
	v_mov_b32_e32 v74, 0
	v_cndmask_b32_e64 v70, 0, 1, s[68:69]
	v_lshl_add_u64 v[138:139], v[184:185], 2, s[12:13]
	v_cmp_ne_u32_e64 s[44:45], 1, v70
	s_andn2_b64 vcc, exec, s[68:69]
	v_mov_b32_e32 v86, 0
	v_mov_b32_e32 v87, v74
	v_mov_b32_e32 v186, 0
	v_mov_b32_e32 v187, v74
	s_cbranch_vccnz .LBB0_118
	global_load_dwordx4 v[86:89], v[138:139], off
	s_waitcnt vmcnt(0)
	v_mov_b32_e32 v186, v88
	v_mov_b32_e32 v187, v89

; #define PG8_STAGE(bufoff, gbase, voff) do { _Pragma("unroll") for (int _i = 0; _i < 2; ++_i) \
;         __builtin_amdgcn_global_load_lds((const unsigned*)((const char*)(gbase) + (voff)[_i]), (LAS unsigned*)(lds + (bufoff) + ldsw + _i * 8192), 16, 0, 0); } while (0)
; #define PG8_LDA(dst, b, h) do { _Pragma("unroll") for (int m = 0; m < 4; ++m) _Pragma("unroll") for (int k = 0; k < 2; ++k) dst[m][k] = *(const LAS bf16x8*)(lds + PG8_SA(b, h) + aoff + m * 2048 + k * 1024); } while (0)
; #define PG8_LDB(dst, b, h) do { _Pragma("unroll") for (int n = 0; n < 2; ++n) _Pragma("unroll") for (int k = 0; k < 2; ++k) dst[n][k] = *(const LAS bf16x8*)(lds + PG8_SB(b, h) + boff + n * 2048 + k * 1024); } while (0)
; #define PG8_MMA(ai, bj, At, Bt) do { __builtin_amdgcn_s_setprio(1); _Pragma("unroll") for (int m = 0; m < 4; ++m) _Pragma("unroll") for (int n = 0; n < 2; ++n) _Pragma("unroll") for (int k = 0; k < 2; ++k) \
;         acc[ai][bj][m][n] = __builtin_amdgcn_mfma_f32_16x16x32_bf16(Bt[n][k], At[m][k], acc[ai][bj][m][n], 0, 0, 0); __builtin_amdgcn_s_setprio(0); } while (0)
; #define PG8_WAIT_V(n) asm volatile("s_waitcnt vmcnt(" #n ")" ::: "memory")
; #define PG8_WAIT_L(n) asm volatile("s_waitcnt lgkmcnt(" #n ")" ::: "memory")
; template <int MODE, class EpiT, class Sched>
; __device__ __forceinline__ void gemm_phase(LAS unsigned char* lds, const Gemm g, const Sched& S, const EpiT& E) {
;     ...
;         for (int t = 0; t < nt; t += 2) {
;             const bool last = (t == nt - 2);
;             const char* a1 = cA + (size_t)(t + 1) * kstep;
;             const char* a2 = last ? nA : cA + (size_t)(t + 2) * kstep; const char* b2 = last ? nB : cB + (size_t)(t + 2) * kstep;
;             const char* a3 = a2 + kstep; const char* b3 = b2 + kstep;
;             PG8_LDB(B0, 0, 0); PG8_SCHED; PG8_LDA(At, 0, 0); PG8_STAGE(PG8_SA(1, 1), a1 + hstep, voffA);
;             PG8_WAIT_L(8); PG8_BAR; PG8_WAIT_L(0); PG8_MMA(0, 0, At, B0); PG8_BAR; PG8_SCHED;
;             PG8_LDB(B1, 0, 1); PG8_STAGE(PG8_SB(0, 0), b2, voffB);
;             PG8_BAR; PG8_WAIT_L(0); PG8_MMA(0, 1, At, B1); PG8_BAR;
;             PG8_LDA(At, 0, 1); PG8_STAGE(PG8_SA(0, 0), a2, voffA);
;             PG8_BAR; PG8_WAIT_L(0); PG8_MMA(1, 0, At, B0); PG8_BAR; PG8_SCHED;
;             PG8_STAGE(PG8_SB(0, 1), b2 + hstep, voffB);
;             PG8_WAIT_V(6); PG8_BAR; PG8_MMA(1, 1, At, B1); PG8_BAR;
.LBB0_159:
	s_add_i32 s89, s30, 2
	s_add_u32 s44, s4, 0x80
	s_addc_u32 s45, s5, 0
	s_add_u32 s100, s4, s38
	s_addc_u32 s101, s5, 0
	s_add_i32 s58, 0, 0x10000
	ds_read_b128 v[130:133], v251
	ds_read_b128 v[134:137], v251 offset:1024
	ds_read_b128 v[138:141], v251 offset:2048
	ds_read_b128 v[142:145], v251 offset:3072
	s_cmp_eq_u32 s61, s30
	s_cselect_b32 s45, s79, s45
	s_cselect_b32 s44, s78, s44
	s_cselect_b32 s53, s47, s24
	s_cselect_b32 s52, s46, s23
	s_add_i32 m0, s69, 0xc000
	ds_read_b128 v[146:149], v223
	ds_read_b128 v[150:153], v223 offset:1024
	ds_read_b128 v[154:157], v223 offset:2048
	ds_read_b128 v[158:161], v223 offset:3072
	ds_read_b128 v[162:165], v223 offset:4096
	ds_read_b128 v[166:169], v223 offset:5120
	ds_read_b128 v[170:173], v223 offset:6144
	global_load_lds_dwordx4 v0, s[100:101]
	s_add_i32 m0, s69, 0xe000
	ds_read_b128 v[174:177], v223 offset:7168
	global_load_lds_dwordx4 v182, s[100:101]
	s_waitcnt lgkmcnt(8)
	s_setprio 1
	s_barrier
	s_waitcnt lgkmcnt(0)
	v_mfma_f32_16x16x32_bf16 v[126:129], v[130:133], v[146:149], v[126:129]
	v_mfma_f32_16x16x32_bf16 v[122:125], v[138:141], v[146:149], v[122:125]
	v_mfma_f32_16x16x32_bf16 v[110:113], v[130:133], v[154:157], v[110:113]
	v_mfma_f32_16x16x32_bf16 v[106:109], v[138:141], v[154:157], v[106:109]
	v_mfma_f32_16x16x32_bf16 v[94:97], v[130:133], v[162:165], v[94:97]
	v_mfma_f32_16x16x32_bf16 v[90:93], v[138:141], v[162:165], v[90:93]
	v_mfma_f32_16x16x32_bf16 v[78:81], v[130:133], v[170:173], v[78:81]
	v_mfma_f32_16x16x32_bf16 v[74:77], v[138:141], v[170:173], v[74:77]
	v_mfma_f32_16x16x32_bf16 v[126:129], v[134:137], v[150:153], v[126:129]
	v_mfma_f32_16x16x32_bf16 v[122:125], v[142:145], v[150:153], v[122:125]
	v_mfma_f32_16x16x32_bf16 v[110:113], v[134:137], v[158:161], v[110:113]
	v_mfma_f32_16x16x32_bf16 v[106:109], v[142:145], v[158:161], v[106:109]
	v_mfma_f32_16x16x32_bf16 v[94:97], v[134:137], v[166:169], v[94:97]
	v_mfma_f32_16x16x32_bf16 v[90:93], v[142:145], v[166:169], v[90:93]
	v_mfma_f32_16x16x32_bf16 v[78:81], v[134:137], v[174:177], v[78:81]
	v_mfma_f32_16x16x32_bf16 v[74:77], v[142:145], v[174:177], v[74:77]
	s_barrier
	s_setprio 0
	s_add_i32 s30, 0, 0x14000
	s_add_i32 s58, s58, s68
	s_add_u32 s98, s52, 0x80
	s_addc_u32 s99, s53, 0
	s_mov_b32 m0, s58
	ds_read_b128 v[188:191], v251 offset:16384
	ds_read_b128 v[192:195], v251 offset:17408
	ds_read_b128 v[196:199], v251 offset:18432
	global_load_lds_dwordx4 v0, s[52:53]
	s_add_i32 m0, s58, 0x2000
	ds_read_b128 v[224:227], v251 offset:19456
	global_load_lds_dwordx4 v182, s[52:53]
	s_setprio 1
	s_barrier
	s_waitcnt lgkmcnt(0)
	v_mfma_f32_16x16x32_bf16 v[118:121], v[188:191], v[146:149], v[118:121]
	v_mfma_f32_16x16x32_bf16 v[114:117], v[196:199], v[146:149], v[114:117]
	v_mfma_f32_16x16x32_bf16 v[102:105], v[188:191], v[154:157], v[102:105]
	v_mfma_f32_16x16x32_bf16 v[98:101], v[196:199], v[154:157], v[98:101]
	v_mfma_f32_16x16x32_bf16 v[86:89], v[188:191], v[162:165], v[86:89]
	v_mfma_f32_16x16x32_bf16 v[82:85], v[196:199], v[162:165], v[82:85]
	v_mfma_f32_16x16x32_bf16 v[70:73], v[188:191], v[170:173], v[70:73]
	v_mfma_f32_16x16x32_bf16 v[66:69], v[196:199], v[170:173], v[66:69]
	v_mfma_f32_16x16x32_bf16 v[118:121], v[192:195], v[150:153], v[118:121]
	v_mfma_f32_16x16x32_bf16 v[114:117], v[224:227], v[150:153], v[114:117]
	v_mfma_f32_16x16x32_bf16 v[102:105], v[192:195], v[158:161], v[102:105]
	v_mfma_f32_16x16x32_bf16 v[98:101], v[224:227], v[158:161], v[98:101]
	v_mfma_f32_16x16x32_bf16 v[86:89], v[192:195], v[166:169], v[86:89]
	v_mfma_f32_16x16x32_bf16 v[82:85], v[224:227], v[166:169], v[82:85]
	v_mfma_f32_16x16x32_bf16 v[70:73], v[192:195], v[174:177], v[70:73]
	v_mfma_f32_16x16x32_bf16 v[66:69], v[224:227], v[174:177], v[66:69]
	s_barrier
	s_setprio 0
	s_mov_b32 m0, s69
	s_add_u32 s100, s44, 0x80
	s_addc_u32 s101, s45, 0
	ds_read_b128 v[146:149], v223 offset:16384
	ds_read_b128 v[150:153], v223 offset:17408
	ds_read_b128 v[154:157], v223 offset:18432
	ds_read_b128 v[158:161], v223 offset:19456
	ds_read_b128 v[162:165], v223 offset:20480
	ds_read_b128 v[166:169], v223 offset:21504
	ds_read_b128 v[170:173], v223 offset:22528
	global_load_lds_dwordx4 v0, s[44:45]
	s_mov_b32 m0, s74
	ds_read_b128 v[174:177], v223 offset:23552
	global_load_lds_dwordx4 v182, s[44:45]
	s_setprio 1
	s_barrier
	s_waitcnt lgkmcnt(0)
	v_mfma_f32_16x16x32_bf16 v[62:65], v[130:133], v[146:149], v[62:65]
	v_mfma_f32_16x16x32_bf16 v[58:61], v[138:141], v[146:149], v[58:61]
	v_mfma_f32_16x16x32_bf16 v[46:49], v[130:133], v[154:157], v[46:49]
	v_mfma_f32_16x16x32_bf16 v[42:45], v[138:141], v[154:157], v[42:45]
	v_mfma_f32_16x16x32_bf16 v[30:33], v[130:133], v[162:165], v[30:33]
	v_mfma_f32_16x16x32_bf16 v[26:29], v[138:141], v[162:165], v[26:29]
	v_mfma_f32_16x16x32_bf16 v[14:17], v[130:133], v[170:173], v[14:17]
	v_mfma_f32_16x16x32_bf16 v[10:13], v[138:141], v[170:173], v[10:13]
	v_mfma_f32_16x16x32_bf16 v[62:65], v[134:137], v[150:153], v[62:65]
	v_mfma_f32_16x16x32_bf16 v[58:61], v[142:145], v[150:153], v[58:61]
	v_mfma_f32_16x16x32_bf16 v[46:49], v[134:137], v[158:161], v[46:49]
	v_mfma_f32_16x16x32_bf16 v[42:45], v[142:145], v[158:161], v[42:45]
	v_mfma_f32_16x16x32_bf16 v[30:33], v[134:137], v[166:169], v[30:33]
	v_mfma_f32_16x16x32_bf16 v[26:29], v[142:145], v[166:169], v[26:29]
	v_mfma_f32_16x16x32_bf16 v[14:17], v[134:137], v[174:177], v[14:17]
	v_mfma_f32_16x16x32_bf16 v[10:13], v[142:145], v[174:177], v[10:13]
	s_barrier
	s_setprio 0
	s_add_u32 s52, s52, s38
	s_addc_u32 s53, s53, 0
	s_add_i32 s30, s30, s68
	s_mov_b32 m0, s30
	s_nop 0
	global_load_lds_dwordx4 v0, s[52:53]
	s_add_i32 m0, s30, 0x2000
	s_nop 0
	global_load_lds_dwordx4 v182, s[52:53]
	s_waitcnt vmcnt(6)
	s_setprio 1
	s_barrier
; #define PG8_STAGE(bufoff, gbase, voff) do { _Pragma("unroll") for (int _i = 0; _i < 2; ++_i) \
;         __builtin_amdgcn_global_load_lds((const unsigned*)((const char*)(gbase) + (voff)[_i]), (LAS unsigned*)(lds + (bufoff) + ldsw + _i * 8192), 16, 0, 0); } while (0)
; #define PG8_LDA(dst, b, h) do { _Pragma("unroll") for (int m = 0; m < 4; ++m) _Pragma("unroll") for (int k = 0; k < 2; ++k) dst[m][k] = *(const LAS bf16x8*)(lds + PG8_SA(b, h) + aoff + m * 2048 + k * 1024); } while (0)
; #define PG8_LDB(dst, b, h) do { _Pragma("unroll") for (int n = 0; n < 2; ++n) _Pragma("unroll") for (int k = 0; k < 2; ++k) dst[n][k] = *(const LAS bf16x8*)(lds + PG8_SB(b, h) + boff + n * 2048 + k * 1024); } while (0)
; #define PG8_MMA(ai, bj, At, Bt) do { __builtin_amdgcn_s_setprio(1); _Pragma("unroll") for (int m = 0; m < 4; ++m) _Pragma("unroll") for (int n = 0; n < 2; ++n) _Pragma("unroll") for (int k = 0; k < 2; ++k) \
;         acc[ai][bj][m][n] = __builtin_amdgcn_mfma_f32_16x16x32_bf16(Bt[n][k], At[m][k], acc[ai][bj][m][n], 0, 0, 0); __builtin_amdgcn_s_setprio(0); } while (0)
; #define PG8_WAIT_V(n) asm volatile("s_waitcnt vmcnt(" #n ")" ::: "memory")
; #define PG8_WAIT_L(n) asm volatile("s_waitcnt lgkmcnt(" #n ")" ::: "memory")
; #define PG8_BAR __builtin_amdgcn_s_barrier()
; #define PG8_SCHED __builtin_amdgcn_sched_barrier(0)
; template <int MODE, class EpiT, class Sched>
; __device__ __forceinline__ void gemm_phase(LAS unsigned char* lds, const Gemm g, const Sched& S, const EpiT& E) {
;     ...
;             PG8_WAIT_V(6); PG8_BAR; PG8_MMA(1, 1, At, B1); PG8_BAR;
;             PG8_LDB(B0, 1, 0); PG8_SCHED; PG8_LDA(At, 1, 0); PG8_STAGE(PG8_SA(0, 1), a2 + hstep, voffA);
;             PG8_WAIT_L(8); PG8_BAR; PG8_WAIT_L(0); PG8_MMA(0, 0, At, B0); PG8_BAR; PG8_SCHED;
;             PG8_LDB(B1, 1, 1); PG8_STAGE(PG8_SB(1, 0), b3, voffB);
;             PG8_BAR; PG8_WAIT_L(0); PG8_MMA(0, 1, At, B1); PG8_BAR;
;             PG8_LDA(At, 1, 1); PG8_STAGE(PG8_SA(1, 0), a3, voffA);
;             PG8_BAR; PG8_WAIT_L(0); PG8_MMA(1, 0, At, B0); PG8_BAR; PG8_SCHED;
	v_mfma_f32_16x16x32_bf16 v[54:57], v[188:191], v[146:149], v[54:57]
	v_mfma_f32_16x16x32_bf16 v[50:53], v[196:199], v[146:149], v[50:53]
	v_mfma_f32_16x16x32_bf16 v[38:41], v[188:191], v[154:157], v[38:41]
	v_mfma_f32_16x16x32_bf16 v[34:37], v[196:199], v[154:157], v[34:37]
	v_mfma_f32_16x16x32_bf16 v[22:25], v[188:191], v[162:165], v[22:25]
	v_mfma_f32_16x16x32_bf16 v[18:21], v[196:199], v[162:165], v[18:21]
	v_mfma_f32_16x16x32_bf16 v[6:9], v[188:191], v[170:173], v[6:9]
	v_mfma_f32_16x16x32_bf16 v[2:5], v[196:199], v[170:173], v[2:5]
	v_mfma_f32_16x16x32_bf16 v[54:57], v[192:195], v[150:153], v[54:57]
	v_mfma_f32_16x16x32_bf16 v[50:53], v[224:227], v[150:153], v[50:53]
	v_mfma_f32_16x16x32_bf16 v[38:41], v[192:195], v[158:161], v[38:41]
	v_mfma_f32_16x16x32_bf16 v[34:37], v[224:227], v[158:161], v[34:37]
	v_mfma_f32_16x16x32_bf16 v[22:25], v[192:195], v[166:169], v[22:25]
	v_mfma_f32_16x16x32_bf16 v[18:21], v[224:227], v[166:169], v[18:21]
	v_mfma_f32_16x16x32_bf16 v[6:9], v[192:195], v[174:177], v[6:9]
	v_mfma_f32_16x16x32_bf16 v[2:5], v[224:227], v[174:177], v[2:5]
	s_barrier
	s_setprio 0
	s_add_i32 s30, 0, 0x18000
	ds_read_b128 v[130:133], v251 offset:32768
	ds_read_b128 v[134:137], v251 offset:33792
	ds_read_b128 v[138:141], v251 offset:34816
	ds_read_b128 v[142:145], v251 offset:35840
	s_add_u32 s44, s44, s38
	s_addc_u32 s45, s45, 0
	s_mov_b32 m0, s75
	ds_read_b128 v[146:149], v223 offset:32768
	ds_read_b128 v[150:153], v223 offset:33792
	ds_read_b128 v[154:157], v223 offset:34816
	ds_read_b128 v[158:161], v223 offset:35840
	ds_read_b128 v[162:165], v223 offset:36864
	ds_read_b128 v[166:169], v223 offset:37888
	ds_read_b128 v[170:173], v223 offset:38912
	global_load_lds_dwordx4 v0, s[44:45]
	s_mov_b32 m0, s9
	ds_read_b128 v[174:177], v223 offset:39936
	global_load_lds_dwordx4 v182, s[44:45]
	s_waitcnt lgkmcnt(8)
	s_setprio 1
	s_barrier
	s_waitcnt lgkmcnt(0)
	v_mfma_f32_16x16x32_bf16 v[126:129], v[130:133], v[146:149], v[126:129]
	v_mfma_f32_16x16x32_bf16 v[122:125], v[138:141], v[146:149], v[122:125]
	v_mfma_f32_16x16x32_bf16 v[110:113], v[130:133], v[154:157], v[110:113]
	v_mfma_f32_16x16x32_bf16 v[106:109], v[138:141], v[154:157], v[106:109]
	v_mfma_f32_16x16x32_bf16 v[94:97], v[130:133], v[162:165], v[94:97]
	v_mfma_f32_16x16x32_bf16 v[90:93], v[138:141], v[162:165], v[90:93]
	v_mfma_f32_16x16x32_bf16 v[78:81], v[130:133], v[170:173], v[78:81]
	v_mfma_f32_16x16x32_bf16 v[74:77], v[138:141], v[170:173], v[74:77]
	v_mfma_f32_16x16x32_bf16 v[126:129], v[134:137], v[150:153], v[126:129]
	v_mfma_f32_16x16x32_bf16 v[122:125], v[142:145], v[150:153], v[122:125]
	v_mfma_f32_16x16x32_bf16 v[110:113], v[134:137], v[158:161], v[110:113]
	v_mfma_f32_16x16x32_bf16 v[106:109], v[142:145], v[158:161], v[106:109]
	v_mfma_f32_16x16x32_bf16 v[94:97], v[134:137], v[166:169], v[94:97]
	v_mfma_f32_16x16x32_bf16 v[90:93], v[142:145], v[166:169], v[90:93]
	v_mfma_f32_16x16x32_bf16 v[78:81], v[134:137], v[174:177], v[78:81]
	v_mfma_f32_16x16x32_bf16 v[74:77], v[142:145], v[174:177], v[74:77]
	s_barrier
	s_setprio 0
	s_add_i32 s44, 0, 0x1c000
	s_add_i32 s30, s30, s68
	s_mov_b32 m0, s30
	ds_read_b128 v[188:191], v251 offset:49152
	ds_read_b128 v[192:195], v251 offset:50176
	ds_read_b128 v[196:199], v251 offset:51200
	global_load_lds_dwordx4 v0, s[98:99]
	s_add_i32 m0, s30, 0x2000
	ds_read_b128 v[224:227], v251 offset:52224
	global_load_lds_dwordx4 v182, s[98:99]
	s_setprio 1
	s_barrier
	s_waitcnt lgkmcnt(0)
	v_mfma_f32_16x16x32_bf16 v[118:121], v[188:191], v[146:149], v[118:121]
	v_mfma_f32_16x16x32_bf16 v[114:117], v[196:199], v[146:149], v[114:117]
	v_mfma_f32_16x16x32_bf16 v[102:105], v[188:191], v[154:157], v[102:105]
	v_mfma_f32_16x16x32_bf16 v[98:101], v[196:199], v[154:157], v[98:101]
	v_mfma_f32_16x16x32_bf16 v[86:89], v[188:191], v[162:165], v[86:89]
	v_mfma_f32_16x16x32_bf16 v[82:85], v[196:199], v[162:165], v[82:85]
	v_mfma_f32_16x16x32_bf16 v[70:73], v[188:191], v[170:173], v[70:73]
	v_mfma_f32_16x16x32_bf16 v[66:69], v[196:199], v[170:173], v[66:69]
	v_mfma_f32_16x16x32_bf16 v[118:121], v[192:195], v[150:153], v[118:121]
	v_mfma_f32_16x16x32_bf16 v[114:117], v[224:227], v[150:153], v[114:117]
	v_mfma_f32_16x16x32_bf16 v[102:105], v[192:195], v[158:161], v[102:105]
	v_mfma_f32_16x16x32_bf16 v[98:101], v[224:227], v[158:161], v[98:101]
	v_mfma_f32_16x16x32_bf16 v[86:89], v[192:195], v[166:169], v[86:89]
	v_mfma_f32_16x16x32_bf16 v[82:85], v[224:227], v[166:169], v[82:85]
	v_mfma_f32_16x16x32_bf16 v[70:73], v[192:195], v[174:177], v[70:73]
	v_mfma_f32_16x16x32_bf16 v[66:69], v[224:227], v[174:177], v[66:69]
	s_barrier
	s_setprio 0
	s_mov_b32 m0, s57
	ds_read_b128 v[146:149], v223 offset:49152
	ds_read_b128 v[150:153], v223 offset:50176
	ds_read_b128 v[154:157], v223 offset:51200
	ds_read_b128 v[158:161], v223 offset:52224
	ds_read_b128 v[162:165], v223 offset:53248
	ds_read_b128 v[166:169], v223 offset:54272
	ds_read_b128 v[170:173], v223 offset:55296
	global_load_lds_dwordx4 v0, s[100:101]
	s_mov_b32 m0, s60
	ds_read_b128 v[174:177], v223 offset:56320
	global_load_lds_dwordx4 v182, s[100:101]
	s_setprio 1
	s_barrier
; #define PG8_WAIT_V(n) asm volatile("s_waitcnt vmcnt(" #n ")" ::: "memory")
; #define PG8_WAIT_L(n) asm volatile("s_waitcnt lgkmcnt(" #n ")" ::: "memory")
;     __device__ __forceinline__ void scales2(const Unit& u, int wr, int fr, int fq, float& sA, float& sB) const {
;         const int rowA = u.pm * BM + wr * 64 + fq * 16 + fr;
;         const f32x4* pa = (const f32x4*)(ssq_in + (size_t)rowA * 16); const f32x4* pb = (const f32x4*)(ssq_in + (size_t)(rowA + HALF) * 16);
;         const f32x4 a0 = pa[0], a1 = pa[1], a2 = pa[2], a3 = pa[3], b0 = pb[0], b1 = pb[1], b2 = pb[2], b3 = pb[3];
;         const float ta = (((a0[0] + a0[1]) + (a0[2] + a0[3])) + ((a1[0] + a1[1]) + (a1[2] + a1[3]))) + (((a2[0] + a2[1]) + (a2[2] + a2[3])) + ((a3[0] + a3[1]) + (a3[2] + a3[3])));
;         const float tb = (((b0[0] + b0[1]) + (b0[2] + b0[3])) + ((b1[0] + b1[1]) + (b1[2] + b1[3]))) + (((b2[0] + b2[1]) + (b2[2] + b2[3])) + ((b3[0] + b3[1]) + (b3[2] + b3[3])));
;         sA = rsqrtf(ta * (1.0f / 1024.0f) + EPS); sB = rsqrtf(tb * (1.0f / 1024.0f) + EPS);
;     template <int mode> __device__ __forceinline__ void run(const f32x4 (&acc)[2][2][4][2], const Unit& u, int wr, int wc, int fr, int fq, const LAS float* sc) const {
;     ...
;             {
;                 const size_t off = (size_t)row0 * D + col0;
; #pragma unroll
;                 for (int bj = 0; bj < 2; ++bj) {
;                     const size_t o = off + bj * HALF;
;                     if (mode == 5) { xi[0][2 * bj] = *(const f32x4*)(xin + o); xi[0][2 * bj + 1] = *(const f32x4*)(xin + o + 4); }
;                     else { xh[0][bj] = *(const u32x4*)(hin + o); xl[0][bj] = *(const u32x4*)(lin + o); }
;                     if (mode == 4) pq[0][bj] = *(const u32x4*)(ob + o);
;                 }
;             }
; template <int MODE, class EpiT, class Sched>
; __device__ __forceinline__ void gemm_phase(LAS unsigned char* lds, const Gemm g, const Sched& S, const EpiT& E) {
;     ...
;             PG8_BAR; PG8_WAIT_L(0); PG8_MMA(0, 1, At, B1); PG8_BAR;
;             PG8_LDA(At, 1, 1); PG8_STAGE(PG8_SA(1, 0), a3, voffA);
;             PG8_BAR; PG8_WAIT_L(0); PG8_MMA(1, 0, At, B0); PG8_BAR; PG8_SCHED;
;             PG8_STAGE(PG8_SB(1, 1), b3 + hstep, voffB);
;             PG8_WAIT_V(6); PG8_BAR; PG8_MMA(1, 1, At, B1); PG8_BAR;
;         }
;         E.template run<MODE>(acc, cur, wr, wc, fr, fq, SC + ui * 256);
	s_waitcnt lgkmcnt(0)
	v_mfma_f32_16x16x32_bf16 v[62:65], v[130:133], v[146:149], v[62:65]
	v_mfma_f32_16x16x32_bf16 v[58:61], v[138:141], v[146:149], v[58:61]
	v_mfma_f32_16x16x32_bf16 v[46:49], v[130:133], v[154:157], v[46:49]
	v_mfma_f32_16x16x32_bf16 v[42:45], v[138:141], v[154:157], v[42:45]
	v_mfma_f32_16x16x32_bf16 v[30:33], v[130:133], v[162:165], v[30:33]
	v_mfma_f32_16x16x32_bf16 v[26:29], v[138:141], v[162:165], v[26:29]
	v_mfma_f32_16x16x32_bf16 v[14:17], v[130:133], v[170:173], v[14:17]
	v_mfma_f32_16x16x32_bf16 v[10:13], v[138:141], v[170:173], v[10:13]
	v_mfma_f32_16x16x32_bf16 v[62:65], v[134:137], v[150:153], v[62:65]
	v_mfma_f32_16x16x32_bf16 v[58:61], v[142:145], v[150:153], v[58:61]
	v_mfma_f32_16x16x32_bf16 v[46:49], v[134:137], v[158:161], v[46:49]
	v_mfma_f32_16x16x32_bf16 v[42:45], v[142:145], v[158:161], v[42:45]
	v_mfma_f32_16x16x32_bf16 v[30:33], v[134:137], v[166:169], v[30:33]
	v_mfma_f32_16x16x32_bf16 v[26:29], v[142:145], v[166:169], v[26:29]
	v_mfma_f32_16x16x32_bf16 v[14:17], v[134:137], v[174:177], v[14:17]
	v_mfma_f32_16x16x32_bf16 v[10:13], v[142:145], v[174:177], v[10:13]
	s_barrier
	s_setprio 0
	s_add_i32 s30, s44, s68
	s_add_u32 s98, s98, s38
	s_addc_u32 s99, s99, 0
	s_mov_b32 m0, s30
	s_nop 0
	global_load_lds_dwordx4 v0, s[98:99]
	s_add_i32 m0, s30, 0x2000
	s_nop 0
	global_load_lds_dwordx4 v182, s[98:99]
	s_waitcnt vmcnt(6)
	s_setprio 1
	s_barrier
	v_mfma_f32_16x16x32_bf16 v[54:57], v[188:191], v[146:149], v[54:57]
	v_mfma_f32_16x16x32_bf16 v[50:53], v[196:199], v[146:149], v[50:53]
	v_mfma_f32_16x16x32_bf16 v[38:41], v[188:191], v[154:157], v[38:41]
	v_mfma_f32_16x16x32_bf16 v[34:37], v[196:199], v[154:157], v[34:37]
	v_mfma_f32_16x16x32_bf16 v[22:25], v[188:191], v[162:165], v[22:25]
	v_mfma_f32_16x16x32_bf16 v[18:21], v[196:199], v[162:165], v[18:21]
	v_mfma_f32_16x16x32_bf16 v[6:9], v[188:191], v[170:173], v[6:9]
	v_mfma_f32_16x16x32_bf16 v[2:5], v[196:199], v[170:173], v[2:5]
	v_mfma_f32_16x16x32_bf16 v[54:57], v[192:195], v[150:153], v[54:57]
	v_mfma_f32_16x16x32_bf16 v[50:53], v[224:227], v[150:153], v[50:53]
	v_mfma_f32_16x16x32_bf16 v[38:41], v[192:195], v[158:161], v[38:41]
	v_mfma_f32_16x16x32_bf16 v[34:37], v[224:227], v[158:161], v[34:37]
	v_mfma_f32_16x16x32_bf16 v[22:25], v[192:195], v[166:169], v[22:25]
	v_mfma_f32_16x16x32_bf16 v[18:21], v[224:227], v[166:169], v[18:21]
	v_mfma_f32_16x16x32_bf16 v[6:9], v[192:195], v[174:177], v[6:9]
	v_mfma_f32_16x16x32_bf16 v[2:5], v[224:227], v[174:177], v[2:5]
	s_barrier
	s_setprio 0
	s_add_u32 s4, s4, 0x100
	s_addc_u32 s5, s5, 0
	s_add_u32 s23, s23, 0x100
	s_addc_u32 s24, s24, 0
	s_cmp_ge_u32 s89, s21
	s_mov_b32 s30, s89
	s_cbranch_scc0 .LBB0_159
	s_lshl_b32 s4, s22, 8
	s_add_i32 s4, s4, s56
	v_or_b32_e32 v130, s4, v222
	v_ashrrev_i32_e32 v131, 31, v130
	v_lshlrev_b64 v[130:131], 6, v[130:131]
	v_lshl_add_u64 v[146:147], s[66:67], 0, v[130:131]
	global_load_dwordx4 v[130:133], v[146:147], off offset:16
	global_load_dwordx4 v[134:137], v[146:147], off offset:48
	global_load_dwordx4 v[138:141], v[146:147], off
	global_load_dwordx4 v[142:145], v[146:147], off offset:32
	v_or_b32_e32 v192, s4, v181
	s_mov_b64 s[4:5], 0x2000
	v_lshl_add_u64 v[158:159], v[146:147], 0, s[4:5]
	v_add_co_u32_e32 v146, vcc, 0x2000, v146
	s_mov_b32 s4, 0x3a800000
	s_nop 0
	v_addc_co_u32_e32 v147, vcc, 0, v147, vcc
	global_load_dwordx4 v[146:149], v[146:147], off
	s_nop 0
	global_load_dwordx4 v[150:153], v[158:159], off offset:16
	global_load_dwordx4 v[154:157], v[158:159], off offset:48
	s_nop 0
	global_load_dwordx4 v[158:161], v[158:159], off offset:32
	v_lshl_or_b32 v188, s2, 8, v221
	v_ashrrev_i32_e32 v193, 31, v192
	v_ashrrev_i32_e32 v189, 31, v188
	v_or_b32_e32 v194, 16, v192
	v_ashrrev_i32_e32 v195, 31, v194
	s_waitcnt vmcnt(0)
	v_mov_b32_e32 v162, v138
	v_mov_b32_e32 v163, v142
	v_mov_b32_e32 v142, v139
	v_pk_add_f32 v[138:139], v[162:163], v[142:143]
	v_mov_b32_e32 v142, v140
	v_mov_b32_e32 v143, v144
	v_mov_b32_e32 v144, v141
	v_pk_add_f32 v[140:141], v[142:143], v[144:145]
	s_nop 0
	v_pk_add_f32 v[138:139], v[138:139], v[140:141]
	v_mov_b32_e32 v140, v130
	v_mov_b32_e32 v141, v134
	v_mov_b32_e32 v134, v131
	v_pk_add_f32 v[130:131], v[140:141], v[134:135]
	v_mov_b32_e32 v134, v132
	v_mov_b32_e32 v135, v136
	v_mov_b32_e32 v136, v133
	v_pk_add_f32 v[132:133], v[134:135], v[136:137]
	v_mov_b32_e32 v134, v148
	v_pk_add_f32 v[130:131], v[130:131], v[132:133]
	v_mov_b32_e32 v132, v146
	v_mov_b32_e32 v133, v158
	v_mov_b32_e32 v158, v147
	v_mov_b32_e32 v135, v160
	v_mov_b32_e32 v160, v149
	v_pk_add_f32 v[132:133], v[132:133], v[158:159]
	v_pk_add_f32 v[134:135], v[134:135], v[160:161]
	v_mov_b32_e32 v136, v152
	v_pk_add_f32 v[132:133], v[132:133], v[134:135]
	v_mov_b32_e32 v134, v150
	v_mov_b32_e32 v135, v154
	v_mov_b32_e32 v154, v151
	v_mov_b32_e32 v137, v156
	v_mov_b32_e32 v156, v153
	v_pk_add_f32 v[134:135], v[134:135], v[154:155]
	v_pk_add_f32 v[136:137], v[136:137], v[156:157]
	v_pk_add_f32 v[130:131], v[138:139], v[130:131]
	v_pk_add_f32 v[134:135], v[134:135], v[136:137]
	s_nop 0
	v_pk_add_f32 v[132:133], v[132:133], v[134:135]
	v_mov_b32_e32 v135, v130
	v_mov_b32_e32 v134, v132
	v_mov_b32_e32 v130, v133
	v_pk_add_f32 v[130:131], v[134:135], v[130:131]
	s_nop 0
	v_pk_fma_f32 v[190:191], v[130:131], s[4:5], v[178:179] op_sel_hi:[1,0,0]
	s_mov_b32 s4, 0x800000
	v_mul_f32_e32 v130, 0x4b800000, v191
	v_cmp_gt_f32_e64 s[44:45], s4, v191
	v_cmp_gt_f32_e32 vcc, s4, v190
	s_nop 0
	v_cndmask_b32_e64 v130, v191, v130, s[44:45]
	v_rsq_f32_e32 v130, v130
	s_nop 0
	v_mul_f32_e32 v131, 0x45800000, v130
	v_cndmask_b32_e64 v226, v130, v131, s[44:45]
	v_lshlrev_b64 v[130:131], 10, v[192:193]
	v_lshl_add_u64 v[130:131], v[130:131], 0, v[188:189]
	v_lshlrev_b64 v[198:199], 1, v[130:131]
	v_lshl_add_u64 v[130:131], s[34:35], 0, v[198:199]
	v_lshl_add_u64 v[132:133], s[92:93], 0, v[198:199]
	global_load_dwordx4 v[170:173], v[130:131], off
	global_load_dwordx4 v[174:177], v[132:133], off
	v_lshl_add_u64 v[134:135], s[6:7], 0, v[198:199]
	global_load_dwordx4 v[166:169], v[134:135], off
	global_load_dwordx4 v[158:161], v[130:131], off offset:256
	global_load_dwordx4 v[162:165], v[132:133], off offset:256
	global_load_dwordx4 v[146:149], v[134:135], off offset:256
	v_and_b32_e32 v130, 64, v205
	v_or_b32_e32 v200, v130, v181
	v_lshlrev_b32_e32 v225, 2, v200
	ds_bpermute_b32 v200, v225, v226
	v_xor_b32_e32 v131, 16, v205
	v_add_u32_e32 v130, 64, v130
	v_cmp_lt_i32_e64 s[44:45], v131, v130
	s_waitcnt lgkmcnt(0)
; __device__ __forceinline__ float bf_lo(unsigned w) { return __uint_as_float(w << 16); }
; __device__ __forceinline__ float bf_hi(unsigned w) { return __uint_as_float(w & 0xffff0000u); }
;     template <int mode> __device__ __forceinline__ void run(const f32x4 (&acc)[2][2][4][2], const Unit& u, int wr, int wc, int fr, int fq, const LAS float* sc) const {
;     ...
;                 if (mode == 4) s = __shfl(ai ? sB : sA, m * 16 + fr);
;                 float ss = 0.f;
; #pragma unroll
;                 for (int bj = 0; bj < 2; ++bj) {
;                     u32x4 wh, wl;
; #pragma unroll
;                     for (int n = 0; n < 2; ++n) {
;                         const int q = 2 * bj + n;
;                         const unsigned h0 = n ? xh[cb][bj].z : xh[cb][bj].x, h1 = n ? xh[cb][bj].w : xh[cb][bj].y, l0 = n ? xl[cb][bj].z : xl[cb][bj].x, l1 = n ? xl[cb][bj].w : xl[cb][bj].y;
;                         f32x4 xo;
;                         if (mode == 5) xo = xi[cb][q];
;                         else { xo[0] = bf_lo(h0) + bf_lo(l0); xo[1] = bf_hi(h0) + bf_hi(l0); xo[2] = bf_lo(h1) + bf_lo(l1); xo[3] = bf_hi(h1) + bf_hi(l1); }
;                         f32x4 v;
;                         if (mode != 4) v = xo + acc[ai][bj][m][n] * alpha + bvv[q];
;                         else {
;                             const f32x4 a = acc[ai][bj][m][n] * s;
;                             const unsigned p0 = n ? pq[cb][bj].z : pq[cb][bj].x, p1 = n ? pq[cb][bj].w : pq[cb][bj].y;
;                             v[0] = xo[0] + sigmoidf_(a[0]) * bf_lo(p0); v[1] = xo[1] + sigmoidf_(a[1]) * bf_hi(p0);
;                             v[2] = xo[2] + sigmoidf_(a[2]) * bf_lo(p1); v[3] = xo[3] + sigmoidf_(a[3]) * bf_hi(p1);
;                         }
;                         const unsigned w0 = pk2(v[0], v[1]), w1 = pk2(v[2], v[3]);
;                         const unsigned m0 = pk2(v[0] - bf_lo(w0), v[1] - bf_hi(w0)), m1 = pk2(v[2] - bf_lo(w1), v[3] - bf_hi(w1));
;                         if (n == 0) { wh.x = w0; wh.y = w1; wl.x = m0; wl.y = m1; } else { wh.z = w0; wh.w = w1; wl.z = m0; wl.w = m1; }
;                         ss += (v[0] * v[0] + v[1] * v[1]) + (v[2] * v[2] + v[3] * v[3]);
;                     }
;                     *(u32x4*)(xb + off + bj * HALF) = wh;
;                     *(u32x4*)(lout + off + bj * HALF) = wl;
	v_pk_mul_f32 v[126:127], v[126:127], v[200:201] op_sel_hi:[1,0]
	v_cndmask_b32_e64 v131, v205, v131, s[44:45]
	v_lshlrev_b32_e32 v191, 2, v131
	v_xor_b32_e32 v131, 32, v205
	v_mul_f32_e32 v126, 0xbfb8aa3b, v126
	v_cmp_lt_i32_e64 s[44:45], v131, v130
	v_exp_f32_e32 v126, v126
	v_pk_mul_f32 v[128:129], v[128:129], v[200:201] op_sel_hi:[1,0]
	v_cndmask_b32_e64 v130, v205, v131, s[44:45]
	v_lshlrev_b32_e32 v224, 2, v130
	v_lshlrev_b64 v[130:131], 10, v[194:195]
	v_lshl_add_u64 v[130:131], v[130:131], 0, v[188:189]
	v_lshlrev_b64 v[196:197], 1, v[130:131]
	v_add_f32_e32 v126, 1.0, v126
	v_lshl_add_u64 v[130:131], s[34:35], 0, v[196:197]
	v_lshl_add_u64 v[132:133], s[92:93], 0, v[196:197]
	v_lshl_add_u64 v[228:229], s[6:7], 0, v[196:197]
	v_rcp_f32_e32 v126, v126
	global_load_dwordx4 v[150:153], v[130:131], off
	global_load_dwordx4 v[154:157], v[132:133], off
	global_load_dwordx4 v[142:145], v[228:229], off
	global_load_dwordx4 v[134:137], v[130:131], off offset:256
	global_load_dwordx4 v[138:141], v[132:133], off offset:256
	s_nop 0
	global_load_dwordx4 v[130:133], v[228:229], off offset:256
	v_pk_mul_f32 v[122:123], v[122:123], v[200:201] op_sel_hi:[1,0]
	v_pk_mul_f32 v[124:125], v[124:125], v[200:201] op_sel_hi:[1,0]
	v_mul_f32_e32 v122, 0xbfb8aa3b, v122
	v_exp_f32_e32 v122, v122
	v_pk_mul_f32 v[118:119], v[118:119], v[200:201] op_sel_hi:[1,0]
	v_pk_mul_f32 v[120:121], v[120:121], v[200:201] op_sel_hi:[1,0]
	v_mul_f32_e32 v118, 0xbfb8aa3b, v118
	v_add_f32_e32 v122, 1.0, v122
	v_rcp_f32_e32 v122, v122
	v_exp_f32_e32 v118, v118
	v_pk_mul_f32 v[114:115], v[114:115], v[200:201] op_sel_hi:[1,0]
	v_pk_mul_f32 v[116:117], v[116:117], v[200:201] op_sel_hi:[1,0]
	v_mul_f32_e32 v114, 0xbfb8aa3b, v114
	v_add_f32_e32 v118, 1.0, v118
	v_rcp_f32_e32 v118, v118
	v_exp_f32_e32 v114, v114
	s_lshl_b32 s44, s2, 2
	s_ashr_i32 s45, s44, 31
	v_add_f32_e32 v114, 1.0, v114
	v_rcp_f32_e32 v114, v114
	s_waitcnt vmcnt(11)
	v_lshlrev_b32_e32 v227, 16, v170
	s_waitcnt vmcnt(10)
	v_lshlrev_b32_e32 v228, 16, v174
	v_and_b32_e32 v174, 0xffff0000, v174
	v_and_b32_e32 v170, 0xffff0000, v170
	v_add_f32_e32 v227, v228, v227
	v_add_f32_e32 v170, v174, v170
	v_lshlrev_b32_e32 v174, 16, v171
	v_lshlrev_b32_e32 v228, 16, v175
	v_and_b32_e32 v175, 0xffff0000, v175
	v_and_b32_e32 v171, 0xffff0000, v171
	v_add_f32_e32 v171, v175, v171
	s_waitcnt vmcnt(9)
	v_lshlrev_b32_e32 v175, 16, v166
	v_fmac_f32_e32 v227, v126, v175
	v_mul_f32_e32 v126, 0xbfb8aa3b, v127
	v_exp_f32_e32 v126, v126
	v_and_b32_e32 v127, 0xffff0000, v166
	v_add_f32_e32 v174, v228, v174
	v_add_f32_e32 v126, 1.0, v126
	v_rcp_f32_e32 v126, v126
	s_nop 0
	v_fmac_f32_e32 v170, v126, v127
	v_mul_f32_e32 v126, 0xbfb8aa3b, v128
	v_exp_f32_e32 v126, v126
	v_lshlrev_b32_e32 v127, 16, v167
	v_add_f32_e32 v126, 1.0, v126
	v_rcp_f32_e32 v126, v126
	s_nop 0
	v_fmac_f32_e32 v174, v126, v127
	v_mul_f32_e32 v126, 0xbfb8aa3b, v129
	v_exp_f32_e32 v126, v126
	v_and_b32_e32 v127, 0xffff0000, v167
	v_add_f32_e32 v126, 1.0, v126
	v_rcp_f32_e32 v126, v126
	s_nop 0
	v_fmac_f32_e32 v171, v126, v127
	v_cvt_pk_bf16_f32 v126, v227, v170
	v_cvt_pk_bf16_f32 v127, v174, v171
	s_nop 0
	v_lshlrev_b32_e32 v128, 16, v126
	v_and_b32_e32 v129, 0xffff0000, v126
	v_sub_f32_e32 v128, v227, v128
	v_sub_f32_e32 v129, v170, v129
	v_cvt_pk_bf16_f32 v166, v128, v129
	v_lshlrev_b32_e32 v128, 16, v127
	v_and_b32_e32 v129, 0xffff0000, v127
	v_sub_f32_e32 v128, v174, v128
	v_sub_f32_e32 v129, v171, v129
	v_cvt_pk_bf16_f32 v167, v128, v129
	v_mul_f32_e32 v128, v170, v170
	v_mul_f32_e32 v129, v171, v171
	v_fmac_f32_e32 v128, v227, v227
	v_fmac_f32_e32 v129, v174, v174
	v_add_f32_e32 v170, v128, v129
	v_lshlrev_b32_e32 v128, 16, v172
	v_lshlrev_b32_e32 v129, 16, v176
	v_add_f32_e32 v171, v129, v128
	v_and_b32_e32 v128, 0xffff0000, v176
	v_and_b32_e32 v129, 0xffff0000, v172
	v_add_f32_e32 v172, v128, v129
	v_lshlrev_b32_e32 v128, 16, v173
	v_lshlrev_b32_e32 v129, 16, v177
	v_add_f32_e32 v174, v129, v128
	v_and_b32_e32 v128, 0xffff0000, v177
	v_and_b32_e32 v129, 0xffff0000, v173
	v_add_f32_e32 v173, v128, v129
	v_lshlrev_b32_e32 v128, 16, v168
	v_fmac_f32_e32 v171, v122, v128
	v_mul_f32_e32 v122, 0xbfb8aa3b, v123
	v_exp_f32_e32 v122, v122
	v_and_b32_e32 v123, 0xffff0000, v168
	v_add_f32_e32 v122, 1.0, v122
	v_rcp_f32_e32 v122, v122
	s_nop 0
	v_fmac_f32_e32 v172, v122, v123
	v_mul_f32_e32 v122, 0xbfb8aa3b, v124
	v_exp_f32_e32 v122, v122
	v_lshlrev_b32_e32 v123, 16, v169
	v_cvt_pk_bf16_f32 v128, v171, v172
	v_add_f32_e32 v122, 1.0, v122
	v_rcp_f32_e32 v122, v122
	s_nop 0
	v_fmac_f32_e32 v174, v122, v123
	v_mul_f32_e32 v122, 0xbfb8aa3b, v125
	v_exp_f32_e32 v122, v122
	v_and_b32_e32 v123, 0xffff0000, v169
	v_lshl_add_u64 v[124:125], s[28:29], 0, v[198:199]
	v_add_f32_e32 v122, 1.0, v122
	v_rcp_f32_e32 v122, v122
	s_nop 0
	v_fmac_f32_e32 v173, v122, v123
	v_lshlrev_b32_e32 v122, 16, v128
	v_and_b32_e32 v123, 0xffff0000, v128
	v_sub_f32_e32 v122, v171, v122
	v_sub_f32_e32 v123, v172, v123
	v_cvt_pk_bf16_f32 v129, v174, v173
	v_cvt_pk_bf16_f32 v168, v122, v123
	s_nop 0
	v_lshlrev_b32_e32 v122, 16, v129
	v_and_b32_e32 v123, 0xffff0000, v129
	v_sub_f32_e32 v122, v174, v122
	v_sub_f32_e32 v123, v173, v123
	v_cvt_pk_bf16_f32 v169, v122, v123
	v_mul_f32_e32 v122, v172, v172
	v_mul_f32_e32 v123, v173, v173
	v_fmac_f32_e32 v122, v171, v171
	v_fmac_f32_e32 v123, v174, v174
	v_add_f32_e32 v122, v122, v123
	v_add_f32_e32 v170, v170, v122
	v_lshl_add_u64 v[122:123], s[10:11], 0, v[198:199]
	global_store_dwordx4 v[122:123], v[126:129], off
	global_store_dwordx4 v[124:125], v[166:169], off
	s_waitcnt vmcnt(10)
; __device__ __forceinline__ float bf_lo(unsigned w) { return __uint_as_float(w << 16); }
; __device__ __forceinline__ float bf_hi(unsigned w) { return __uint_as_float(w & 0xffff0000u); }
;     template <int mode> __device__ __forceinline__ void run(const f32x4 (&acc)[2][2][4][2], const Unit& u, int wr, int wc, int fr, int fq, const LAS float* sc) const {
;     ...
;                 for (int bj = 0; bj < 2; ++bj) {
;                     u32x4 wh, wl;
; #pragma unroll
;                     for (int n = 0; n < 2; ++n) {
;                         const int q = 2 * bj + n;
;                         const unsigned h0 = n ? xh[cb][bj].z : xh[cb][bj].x, h1 = n ? xh[cb][bj].w : xh[cb][bj].y, l0 = n ? xl[cb][bj].z : xl[cb][bj].x, l1 = n ? xl[cb][bj].w : xl[cb][bj].y;
;                         f32x4 xo;
;                         if (mode == 5) xo = xi[cb][q];
;                         else { xo[0] = bf_lo(h0) + bf_lo(l0); xo[1] = bf_hi(h0) + bf_hi(l0); xo[2] = bf_lo(h1) + bf_lo(l1); xo[3] = bf_hi(h1) + bf_hi(l1); }
;                         f32x4 v;
;                         if (mode != 4) v = xo + acc[ai][bj][m][n] * alpha + bvv[q];
;                         else {
;                             const f32x4 a = acc[ai][bj][m][n] * s;
;                             const unsigned p0 = n ? pq[cb][bj].z : pq[cb][bj].x, p1 = n ? pq[cb][bj].w : pq[cb][bj].y;
;                             v[0] = xo[0] + sigmoidf_(a[0]) * bf_lo(p0); v[1] = xo[1] + sigmoidf_(a[1]) * bf_hi(p0);
;                             v[2] = xo[2] + sigmoidf_(a[2]) * bf_lo(p1); v[3] = xo[3] + sigmoidf_(a[3]) * bf_hi(p1);
;                         }
;                         const unsigned w0 = pk2(v[0], v[1]), w1 = pk2(v[2], v[3]);
;                         const unsigned m0 = pk2(v[0] - bf_lo(w0), v[1] - bf_hi(w0)), m1 = pk2(v[2] - bf_lo(w1), v[3] - bf_hi(w1));
;                         if (n == 0) { wh.x = w0; wh.y = w1; wl.x = m0; wl.y = m1; } else { wh.z = w0; wh.w = w1; wl.z = m0; wl.w = m1; }
;                         ss += (v[0] * v[0] + v[1] * v[1]) + (v[2] * v[2] + v[3] * v[3]);
;                     }
;                     *(u32x4*)(xb + off + bj * HALF) = wh;
;                     *(u32x4*)(lout + off + bj * HALF) = wl;
;                 }
;                 ss += __shfl_xor(ss, 16); ss += __shfl_xor(ss, 32);
;                 if (fq == 0) ssq_out[(size_t)row * 16 + u.pn * 4 + wc] = ss;
	v_lshlrev_b32_e32 v126, 16, v158
	s_waitcnt vmcnt(9)
	v_lshlrev_b32_e32 v127, 16, v162
	v_add_f32_e32 v128, v127, v126
	v_and_b32_e32 v126, 0xffff0000, v162
	v_and_b32_e32 v127, 0xffff0000, v158
	v_add_f32_e32 v129, v126, v127
	v_lshlrev_b32_e32 v126, 16, v159
	v_lshlrev_b32_e32 v127, 16, v163
	v_add_f32_e32 v158, v127, v126
	v_and_b32_e32 v126, 0xffff0000, v163
	v_and_b32_e32 v127, 0xffff0000, v159
	v_add_f32_e32 v159, v126, v127
	s_waitcnt vmcnt(8)
	v_lshlrev_b32_e32 v126, 16, v146
	v_fmac_f32_e32 v128, v118, v126
	v_mul_f32_e32 v118, 0xbfb8aa3b, v119
	v_exp_f32_e32 v118, v118
	v_and_b32_e32 v119, 0xffff0000, v146
	v_add_f32_e32 v118, 1.0, v118
	v_rcp_f32_e32 v118, v118
	s_nop 0
	v_fmac_f32_e32 v129, v118, v119
	v_mul_f32_e32 v118, 0xbfb8aa3b, v120
	v_exp_f32_e32 v118, v118
	v_lshlrev_b32_e32 v119, 16, v147
	v_add_f32_e32 v118, 1.0, v118
	v_rcp_f32_e32 v118, v118
	s_nop 0
	v_fmac_f32_e32 v158, v118, v119
	v_mul_f32_e32 v118, 0xbfb8aa3b, v121
	v_exp_f32_e32 v118, v118
	v_and_b32_e32 v119, 0xffff0000, v147
	v_add_f32_e32 v118, 1.0, v118
	v_rcp_f32_e32 v118, v118
	s_nop 0
	v_fmac_f32_e32 v159, v118, v119
	v_cvt_pk_bf16_f32 v118, v128, v129
	v_cvt_pk_bf16_f32 v119, v158, v159
	s_nop 0
	v_lshlrev_b32_e32 v120, 16, v118
	v_and_b32_e32 v121, 0xffff0000, v118
	v_sub_f32_e32 v120, v128, v120
	v_sub_f32_e32 v121, v129, v121
	v_cvt_pk_bf16_f32 v126, v120, v121
	v_lshlrev_b32_e32 v120, 16, v119
	v_and_b32_e32 v121, 0xffff0000, v119
	v_sub_f32_e32 v120, v158, v120
	v_sub_f32_e32 v121, v159, v121
	v_cvt_pk_bf16_f32 v127, v120, v121
	v_mul_f32_e32 v120, v129, v129
	v_mul_f32_e32 v121, v159, v159
	v_fmac_f32_e32 v120, v128, v128
	v_fmac_f32_e32 v121, v158, v158
	v_add_f32_e32 v120, v120, v121
	v_add_f32_e32 v146, v120, v170
	v_lshlrev_b32_e32 v120, 16, v160
	v_lshlrev_b32_e32 v121, 16, v164
	v_add_f32_e32 v147, v121, v120
	v_and_b32_e32 v120, 0xffff0000, v164
	v_and_b32_e32 v121, 0xffff0000, v160
	v_add_f32_e32 v158, v120, v121
	v_lshlrev_b32_e32 v120, 16, v161
	v_lshlrev_b32_e32 v121, 16, v165
	v_add_f32_e32 v159, v121, v120
	v_and_b32_e32 v120, 0xffff0000, v165
	v_and_b32_e32 v121, 0xffff0000, v161
	v_add_f32_e32 v160, v120, v121
	v_lshlrev_b32_e32 v120, 16, v148
	v_fmac_f32_e32 v147, v114, v120
	v_mul_f32_e32 v114, 0xbfb8aa3b, v115
	v_exp_f32_e32 v114, v114
	v_and_b32_e32 v115, 0xffff0000, v148
	v_add_f32_e32 v114, 1.0, v114
	v_rcp_f32_e32 v114, v114
	s_nop 0
	v_fmac_f32_e32 v158, v114, v115
	v_mul_f32_e32 v114, 0xbfb8aa3b, v116
	v_exp_f32_e32 v114, v114
	v_lshlrev_b32_e32 v115, 16, v149
	v_cvt_pk_bf16_f32 v120, v147, v158
	v_add_f32_e32 v114, 1.0, v114
	v_rcp_f32_e32 v114, v114
	s_nop 0
	v_fmac_f32_e32 v159, v114, v115
	v_mul_f32_e32 v114, 0xbfb8aa3b, v117
	v_exp_f32_e32 v114, v114
	v_and_b32_e32 v115, 0xffff0000, v149
	v_add_f32_e32 v114, 1.0, v114
	v_rcp_f32_e32 v114, v114
	s_nop 0
	v_fmac_f32_e32 v160, v114, v115
	v_lshlrev_b32_e32 v114, 16, v120
	v_and_b32_e32 v115, 0xffff0000, v120
	v_sub_f32_e32 v114, v147, v114
	v_sub_f32_e32 v115, v158, v115
	v_cvt_pk_bf16_f32 v121, v159, v160
	v_cvt_pk_bf16_f32 v128, v114, v115
	s_nop 0
	v_lshlrev_b32_e32 v114, 16, v121
	v_and_b32_e32 v115, 0xffff0000, v121
	v_sub_f32_e32 v114, v159, v114
	v_sub_f32_e32 v115, v160, v115
	v_cvt_pk_bf16_f32 v129, v114, v115
	v_mul_f32_e32 v114, v158, v158
	v_mul_f32_e32 v115, v160, v160
	v_fmac_f32_e32 v114, v147, v147
	v_fmac_f32_e32 v115, v159, v159
	v_add_f32_e32 v114, v114, v115
	v_add_f32_e32 v114, v114, v146
	ds_bpermute_b32 v115, v191, v114
	global_store_dwordx4 v[122:123], v[118:121], off offset:256
	global_store_dwordx4 v[124:125], v[126:129], off offset:256
	s_waitcnt lgkmcnt(0)
	v_add_f32_e32 v114, v114, v115
	ds_bpermute_b32 v115, v224, v114
	s_and_saveexec_b64 s[4:5], s[40:41]
	s_cbranch_execz .LBB0_162
	v_lshlrev_b64 v[116:117], 6, v[192:193]
	v_lshl_add_u64 v[116:117], s[62:63], 0, v[116:117]
	v_lshl_add_u64 v[116:117], s[44:45], 2, v[116:117]
	s_lshl_b32 s24, s20, 2
	v_lshl_add_u64 v[116:117], v[116:117], 0, s[24:25]
	s_waitcnt lgkmcnt(0)
	v_add_f32_e32 v114, v114, v115
	global_store_dword v[116:117], v114, off

; #define PG8_STAGE(bufoff, gbase, voff) do { _Pragma("unroll") for (int _i = 0; _i < 2; ++_i) \
;         __builtin_amdgcn_global_load_lds((const unsigned*)((const char*)(gbase) + (voff)[_i]), (LAS unsigned*)(lds + (bufoff) + ldsw + _i * 8192), 16, 0, 0); } while (0)
; #define PG8_LDA(dst, b, h) do { _Pragma("unroll") for (int m = 0; m < 4; ++m) _Pragma("unroll") for (int k = 0; k < 2; ++k) dst[m][k] = *(const LAS bf16x8*)(lds + PG8_SA(b, h) + aoff + m * 2048 + k * 1024); } while (0)
; #define PG8_LDB(dst, b, h) do { _Pragma("unroll") for (int n = 0; n < 2; ++n) _Pragma("unroll") for (int k = 0; k < 2; ++k) dst[n][k] = *(const LAS bf16x8*)(lds + PG8_SB(b, h) + boff + n * 2048 + k * 1024); } while (0)
; #define PG8_MMA(ai, bj, At, Bt) do { __builtin_amdgcn_s_setprio(1); _Pragma("unroll") for (int m = 0; m < 4; ++m) _Pragma("unroll") for (int n = 0; n < 2; ++n) _Pragma("unroll") for (int k = 0; k < 2; ++k) \
;         acc[ai][bj][m][n] = __builtin_amdgcn_mfma_f32_16x16x32_bf16(Bt[n][k], At[m][k], acc[ai][bj][m][n], 0, 0, 0); __builtin_amdgcn_s_setprio(0); } while (0)
; #define PG8_WAIT_V(n) asm volatile("s_waitcnt vmcnt(" #n ")" ::: "memory")
; #define PG8_WAIT_L(n) asm volatile("s_waitcnt lgkmcnt(" #n ")" ::: "memory")
; template <int MODE, class EpiT, class Sched>
; __device__ __forceinline__ void gemm_phase(LAS unsigned char* lds, const Gemm g, const Sched& S, const EpiT& E) {
;     ...
;         for (int t = 0; t < nt; t += 2) {
;             const bool last = (t == nt - 2);
;             const char* a1 = cA + (size_t)(t + 1) * kstep;
;             const char* a2 = last ? nA : cA + (size_t)(t + 2) * kstep; const char* b2 = last ? nB : cB + (size_t)(t + 2) * kstep;
;             const char* a3 = a2 + kstep; const char* b3 = b2 + kstep;
;             PG8_LDB(B0, 0, 0); PG8_SCHED; PG8_LDA(At, 0, 0); PG8_STAGE(PG8_SA(1, 1), a1 + hstep, voffA);
;             PG8_WAIT_L(8); PG8_BAR; PG8_WAIT_L(0); PG8_MMA(0, 0, At, B0); PG8_BAR; PG8_SCHED;
;             PG8_LDB(B1, 0, 1); PG8_STAGE(PG8_SB(0, 0), b2, voffB);
;             PG8_BAR; PG8_WAIT_L(0); PG8_MMA(0, 1, At, B1); PG8_BAR;
;             PG8_LDA(At, 0, 1); PG8_STAGE(PG8_SA(0, 0), a2, voffA);
;             PG8_BAR; PG8_WAIT_L(0); PG8_MMA(1, 0, At, B0); PG8_BAR; PG8_SCHED;
;             PG8_STAGE(PG8_SB(0, 1), b2 + hstep, voffB);
;             PG8_WAIT_V(6); PG8_BAR; PG8_MMA(1, 1, At, B1); PG8_BAR;
.LBB0_195:
	s_add_i32 vcc_lo, s44, 2
	s_add_u32 s52, s4, 0x80
	s_addc_u32 s45, s5, 0
	s_add_u32 s100, s4, s38
	s_addc_u32 s101, s5, 0
	ds_read_b128 v[58:61], v249
	ds_read_b128 v[62:65], v249 offset:1024
	ds_read_b128 v[70:73], v249 offset:2048
	ds_read_b128 v[74:77], v249 offset:3072
	s_cmp_eq_u32 s75, s44
	s_cselect_b32 s44, s68, s52
	s_cselect_b32 s45, s69, s45
	s_cselect_b32 s53, s47, s90
	s_cselect_b32 s52, s46, s89
	s_add_i32 m0, s21, 0xc000
	ds_read_b128 v[138:141], v196
	ds_read_b128 v[142:145], v196 offset:1024
	ds_read_b128 v[146:149], v196 offset:2048
	ds_read_b128 v[150:153], v196 offset:3072
	ds_read_b128 v[162:165], v196 offset:4096
	ds_read_b128 v[166:169], v196 offset:5120
	ds_read_b128 v[170:173], v196 offset:6144
	global_load_lds_dwordx4 v0, s[100:101]
	s_add_i32 m0, s21, 0xe000
	ds_read_b128 v[184:187], v196 offset:7168
	global_load_lds_dwordx4 v174, s[100:101]
	s_waitcnt lgkmcnt(8)
	s_setprio 1
	s_barrier
	s_waitcnt lgkmcnt(0)
	v_mfma_f32_16x16x32_bf16 v[158:161], v[58:61], v[138:141], v[158:161]
	v_mfma_f32_16x16x32_bf16 v[154:157], v[70:73], v[138:141], v[154:157]
	v_mfma_f32_16x16x32_bf16 v[126:129], v[58:61], v[146:149], v[126:129]
	v_mfma_f32_16x16x32_bf16 v[122:125], v[70:73], v[146:149], v[122:125]
	v_mfma_f32_16x16x32_bf16 v[110:113], v[58:61], v[162:165], v[110:113]
	v_mfma_f32_16x16x32_bf16 v[106:109], v[70:73], v[162:165], v[106:109]
	v_mfma_f32_16x16x32_bf16 v[94:97], v[58:61], v[170:173], v[94:97]
	v_mfma_f32_16x16x32_bf16 v[90:93], v[70:73], v[170:173], v[90:93]
	v_mfma_f32_16x16x32_bf16 v[158:161], v[62:65], v[142:145], v[158:161]
	v_mfma_f32_16x16x32_bf16 v[154:157], v[74:77], v[142:145], v[154:157]
	v_mfma_f32_16x16x32_bf16 v[126:129], v[62:65], v[150:153], v[126:129]
	v_mfma_f32_16x16x32_bf16 v[122:125], v[74:77], v[150:153], v[122:125]
	v_mfma_f32_16x16x32_bf16 v[110:113], v[62:65], v[166:169], v[110:113]
	v_mfma_f32_16x16x32_bf16 v[106:109], v[74:77], v[166:169], v[106:109]
	v_mfma_f32_16x16x32_bf16 v[94:97], v[62:65], v[184:187], v[94:97]
	v_mfma_f32_16x16x32_bf16 v[90:93], v[74:77], v[184:187], v[90:93]
	s_barrier
	s_setprio 0
	ds_read_b128 v[188:191], v249 offset:16384
	ds_read_b128 v[220:223], v249 offset:17408
	ds_read_b128 v[224:227], v249 offset:18432
	ds_read_b128 v[228:231], v249 offset:19456
	s_add_u32 s98, s52, 0x80
	s_addc_u32 s99, s53, 0
	s_add_i32 m0, s20, 0x10000
	s_nop 0
	global_load_lds_dwordx4 v0, s[52:53]
	s_add_i32 m0, s20, 0x12000
	s_nop 0
	global_load_lds_dwordx4 v174, s[52:53]
	s_setprio 1
	s_barrier
	s_waitcnt lgkmcnt(0)
	v_mfma_f32_16x16x32_bf16 v[134:137], v[188:191], v[138:141], v[134:137]
	v_mfma_f32_16x16x32_bf16 v[130:133], v[224:227], v[138:141], v[130:133]
	v_mfma_f32_16x16x32_bf16 v[118:121], v[188:191], v[146:149], v[118:121]
	v_mfma_f32_16x16x32_bf16 v[114:117], v[224:227], v[146:149], v[114:117]
	v_mfma_f32_16x16x32_bf16 v[102:105], v[188:191], v[162:165], v[102:105]
	v_mfma_f32_16x16x32_bf16 v[98:101], v[224:227], v[162:165], v[98:101]
	v_mfma_f32_16x16x32_bf16 v[86:89], v[188:191], v[170:173], v[86:89]
	v_mfma_f32_16x16x32_bf16 v[82:85], v[224:227], v[170:173], v[82:85]
	v_mfma_f32_16x16x32_bf16 v[134:137], v[220:223], v[142:145], v[134:137]
	v_mfma_f32_16x16x32_bf16 v[130:133], v[228:231], v[142:145], v[130:133]
	v_mfma_f32_16x16x32_bf16 v[118:121], v[220:223], v[150:153], v[118:121]
	v_mfma_f32_16x16x32_bf16 v[114:117], v[228:231], v[150:153], v[114:117]
	v_mfma_f32_16x16x32_bf16 v[102:105], v[220:223], v[166:169], v[102:105]
	v_mfma_f32_16x16x32_bf16 v[98:101], v[228:231], v[166:169], v[98:101]
	v_mfma_f32_16x16x32_bf16 v[86:89], v[220:223], v[184:187], v[86:89]
	v_mfma_f32_16x16x32_bf16 v[82:85], v[228:231], v[184:187], v[82:85]
	s_barrier
	s_setprio 0
	s_mov_b32 m0, s21
	s_add_u32 s100, s44, 0x80
	s_addc_u32 s101, s45, 0
	ds_read_b128 v[138:141], v196 offset:16384
	ds_read_b128 v[142:145], v196 offset:17408
	ds_read_b128 v[146:149], v196 offset:18432
	ds_read_b128 v[150:153], v196 offset:19456
	ds_read_b128 v[162:165], v196 offset:20480
	ds_read_b128 v[166:169], v196 offset:21504
	ds_read_b128 v[170:173], v196 offset:22528
	global_load_lds_dwordx4 v0, s[44:45]
	s_mov_b32 m0, s50
	ds_read_b128 v[184:187], v196 offset:23552
	global_load_lds_dwordx4 v174, s[44:45]
	s_setprio 1
	s_barrier
	s_waitcnt lgkmcnt(0)
	v_mfma_f32_16x16x32_bf16 v[78:81], v[58:61], v[138:141], v[78:81]
	v_mfma_f32_16x16x32_bf16 v[66:69], v[70:73], v[138:141], v[66:69]
	v_mfma_f32_16x16x32_bf16 v[46:49], v[58:61], v[146:149], v[46:49]
	v_mfma_f32_16x16x32_bf16 v[42:45], v[70:73], v[146:149], v[42:45]
	v_mfma_f32_16x16x32_bf16 v[30:33], v[58:61], v[162:165], v[30:33]
	v_mfma_f32_16x16x32_bf16 v[26:29], v[70:73], v[162:165], v[26:29]
	v_mfma_f32_16x16x32_bf16 v[14:17], v[58:61], v[170:173], v[14:17]
	v_mfma_f32_16x16x32_bf16 v[10:13], v[70:73], v[170:173], v[10:13]
	v_mfma_f32_16x16x32_bf16 v[78:81], v[62:65], v[142:145], v[78:81]
	v_mfma_f32_16x16x32_bf16 v[66:69], v[74:77], v[142:145], v[66:69]
	v_mfma_f32_16x16x32_bf16 v[46:49], v[62:65], v[150:153], v[46:49]
	v_mfma_f32_16x16x32_bf16 v[42:45], v[74:77], v[150:153], v[42:45]
	v_mfma_f32_16x16x32_bf16 v[30:33], v[62:65], v[166:169], v[30:33]
	v_mfma_f32_16x16x32_bf16 v[26:29], v[74:77], v[166:169], v[26:29]
	v_mfma_f32_16x16x32_bf16 v[14:17], v[62:65], v[184:187], v[14:17]
	v_mfma_f32_16x16x32_bf16 v[10:13], v[74:77], v[184:187], v[10:13]
	s_barrier
	s_setprio 0
	s_add_u32 s52, s52, s38
	s_addc_u32 s53, s53, 0
	s_add_i32 m0, s20, 0x14000
	s_nop 0
	global_load_lds_dwordx4 v0, s[52:53]
	s_add_i32 m0, s20, 0x16000
	s_nop 0
	global_load_lds_dwordx4 v174, s[52:53]
	s_waitcnt vmcnt(6)
	s_setprio 1
	s_barrier
; #define PG8_STAGE(bufoff, gbase, voff) do { _Pragma("unroll") for (int _i = 0; _i < 2; ++_i) \
;         __builtin_amdgcn_global_load_lds((const unsigned*)((const char*)(gbase) + (voff)[_i]), (LAS unsigned*)(lds + (bufoff) + ldsw + _i * 8192), 16, 0, 0); } while (0)
; #define PG8_LDA(dst, b, h) do { _Pragma("unroll") for (int m = 0; m < 4; ++m) _Pragma("unroll") for (int k = 0; k < 2; ++k) dst[m][k] = *(const LAS bf16x8*)(lds + PG8_SA(b, h) + aoff + m * 2048 + k * 1024); } while (0)
; #define PG8_LDB(dst, b, h) do { _Pragma("unroll") for (int n = 0; n < 2; ++n) _Pragma("unroll") for (int k = 0; k < 2; ++k) dst[n][k] = *(const LAS bf16x8*)(lds + PG8_SB(b, h) + boff + n * 2048 + k * 1024); } while (0)
; #define PG8_MMA(ai, bj, At, Bt) do { __builtin_amdgcn_s_setprio(1); _Pragma("unroll") for (int m = 0; m < 4; ++m) _Pragma("unroll") for (int n = 0; n < 2; ++n) _Pragma("unroll") for (int k = 0; k < 2; ++k) \
;         acc[ai][bj][m][n] = __builtin_amdgcn_mfma_f32_16x16x32_bf16(Bt[n][k], At[m][k], acc[ai][bj][m][n], 0, 0, 0); __builtin_amdgcn_s_setprio(0); } while (0)
; #define PG8_WAIT_V(n) asm volatile("s_waitcnt vmcnt(" #n ")" ::: "memory")
; #define PG8_WAIT_L(n) asm volatile("s_waitcnt lgkmcnt(" #n ")" ::: "memory")
; #define PG8_BAR __builtin_amdgcn_s_barrier()
; #define PG8_SCHED __builtin_amdgcn_sched_barrier(0)
; template <int MODE, class EpiT, class Sched>
; __device__ __forceinline__ void gemm_phase(LAS unsigned char* lds, const Gemm g, const Sched& S, const EpiT& E) {
;     ...
;             PG8_WAIT_V(6); PG8_BAR; PG8_MMA(1, 1, At, B1); PG8_BAR;
;             PG8_LDB(B0, 1, 0); PG8_SCHED; PG8_LDA(At, 1, 0); PG8_STAGE(PG8_SA(0, 1), a2 + hstep, voffA);
;             PG8_WAIT_L(8); PG8_BAR; PG8_WAIT_L(0); PG8_MMA(0, 0, At, B0); PG8_BAR; PG8_SCHED;
;             PG8_LDB(B1, 1, 1); PG8_STAGE(PG8_SB(1, 0), b3, voffB);
;             PG8_BAR; PG8_WAIT_L(0); PG8_MMA(0, 1, At, B1); PG8_BAR;
;             PG8_LDA(At, 1, 1); PG8_STAGE(PG8_SA(1, 0), a3, voffA);
;             PG8_BAR; PG8_WAIT_L(0); PG8_MMA(1, 0, At, B0); PG8_BAR; PG8_SCHED;
	v_mfma_f32_16x16x32_bf16 v[54:57], v[188:191], v[138:141], v[54:57]
	v_mfma_f32_16x16x32_bf16 v[50:53], v[224:227], v[138:141], v[50:53]
	v_mfma_f32_16x16x32_bf16 v[38:41], v[188:191], v[146:149], v[38:41]
	v_mfma_f32_16x16x32_bf16 v[34:37], v[224:227], v[146:149], v[34:37]
	v_mfma_f32_16x16x32_bf16 v[22:25], v[188:191], v[162:165], v[22:25]
	v_mfma_f32_16x16x32_bf16 v[18:21], v[224:227], v[162:165], v[18:21]
	v_mfma_f32_16x16x32_bf16 v[6:9], v[188:191], v[170:173], v[6:9]
	v_mfma_f32_16x16x32_bf16 v[2:5], v[224:227], v[170:173], v[2:5]
	v_mfma_f32_16x16x32_bf16 v[54:57], v[220:223], v[142:145], v[54:57]
	v_mfma_f32_16x16x32_bf16 v[50:53], v[228:231], v[142:145], v[50:53]
	v_mfma_f32_16x16x32_bf16 v[38:41], v[220:223], v[150:153], v[38:41]
	v_mfma_f32_16x16x32_bf16 v[34:37], v[228:231], v[150:153], v[34:37]
	v_mfma_f32_16x16x32_bf16 v[22:25], v[220:223], v[166:169], v[22:25]
	v_mfma_f32_16x16x32_bf16 v[18:21], v[228:231], v[166:169], v[18:21]
	v_mfma_f32_16x16x32_bf16 v[6:9], v[220:223], v[184:187], v[6:9]
	v_mfma_f32_16x16x32_bf16 v[2:5], v[228:231], v[184:187], v[2:5]
	s_barrier
	s_setprio 0
	ds_read_b128 v[58:61], v249 offset:32768
	ds_read_b128 v[62:65], v249 offset:33792
	ds_read_b128 v[70:73], v249 offset:34816
	ds_read_b128 v[74:77], v249 offset:35840
	s_add_u32 s44, s44, s38
	s_addc_u32 s45, s45, 0
	s_mov_b32 m0, s51
	ds_read_b128 v[138:141], v196 offset:32768
	ds_read_b128 v[142:145], v196 offset:33792
	ds_read_b128 v[146:149], v196 offset:34816
	ds_read_b128 v[150:153], v196 offset:35840
	ds_read_b128 v[162:165], v196 offset:36864
	ds_read_b128 v[166:169], v196 offset:37888
	ds_read_b128 v[170:173], v196 offset:38912
	global_load_lds_dwordx4 v0, s[44:45]
	s_mov_b32 m0, s56
	ds_read_b128 v[184:187], v196 offset:39936
	global_load_lds_dwordx4 v174, s[44:45]
	s_waitcnt lgkmcnt(8)
	s_setprio 1
	s_barrier
	s_waitcnt lgkmcnt(0)
	v_mfma_f32_16x16x32_bf16 v[158:161], v[58:61], v[138:141], v[158:161]
	v_mfma_f32_16x16x32_bf16 v[154:157], v[70:73], v[138:141], v[154:157]
	v_mfma_f32_16x16x32_bf16 v[126:129], v[58:61], v[146:149], v[126:129]
	v_mfma_f32_16x16x32_bf16 v[122:125], v[70:73], v[146:149], v[122:125]
	v_mfma_f32_16x16x32_bf16 v[110:113], v[58:61], v[162:165], v[110:113]
	v_mfma_f32_16x16x32_bf16 v[106:109], v[70:73], v[162:165], v[106:109]
	v_mfma_f32_16x16x32_bf16 v[94:97], v[58:61], v[170:173], v[94:97]
	v_mfma_f32_16x16x32_bf16 v[90:93], v[70:73], v[170:173], v[90:93]
	v_mfma_f32_16x16x32_bf16 v[158:161], v[62:65], v[142:145], v[158:161]
	v_mfma_f32_16x16x32_bf16 v[154:157], v[74:77], v[142:145], v[154:157]
	v_mfma_f32_16x16x32_bf16 v[126:129], v[62:65], v[150:153], v[126:129]
	v_mfma_f32_16x16x32_bf16 v[122:125], v[74:77], v[150:153], v[122:125]
	v_mfma_f32_16x16x32_bf16 v[110:113], v[62:65], v[166:169], v[110:113]
	v_mfma_f32_16x16x32_bf16 v[106:109], v[74:77], v[166:169], v[106:109]
	v_mfma_f32_16x16x32_bf16 v[94:97], v[62:65], v[184:187], v[94:97]
	v_mfma_f32_16x16x32_bf16 v[90:93], v[74:77], v[184:187], v[90:93]
	s_barrier
	s_setprio 0
	s_add_i32 m0, s20, 0x18000
	ds_read_b128 v[188:191], v249 offset:49152
	ds_read_b128 v[220:223], v249 offset:50176
	ds_read_b128 v[224:227], v249 offset:51200
	global_load_lds_dwordx4 v0, s[98:99]
	s_add_i32 m0, s20, 0x1a000
	ds_read_b128 v[228:231], v249 offset:52224
	global_load_lds_dwordx4 v174, s[98:99]
	s_setprio 1
	s_barrier
	s_waitcnt lgkmcnt(0)
	v_mfma_f32_16x16x32_bf16 v[134:137], v[188:191], v[138:141], v[134:137]
	v_mfma_f32_16x16x32_bf16 v[130:133], v[224:227], v[138:141], v[130:133]
	v_mfma_f32_16x16x32_bf16 v[118:121], v[188:191], v[146:149], v[118:121]
	v_mfma_f32_16x16x32_bf16 v[114:117], v[224:227], v[146:149], v[114:117]
	v_mfma_f32_16x16x32_bf16 v[102:105], v[188:191], v[162:165], v[102:105]
	v_mfma_f32_16x16x32_bf16 v[98:101], v[224:227], v[162:165], v[98:101]
	v_mfma_f32_16x16x32_bf16 v[86:89], v[188:191], v[170:173], v[86:89]
	v_mfma_f32_16x16x32_bf16 v[82:85], v[224:227], v[170:173], v[82:85]
	v_mfma_f32_16x16x32_bf16 v[134:137], v[220:223], v[142:145], v[134:137]
	v_mfma_f32_16x16x32_bf16 v[130:133], v[228:231], v[142:145], v[130:133]
	v_mfma_f32_16x16x32_bf16 v[118:121], v[220:223], v[150:153], v[118:121]
	v_mfma_f32_16x16x32_bf16 v[114:117], v[228:231], v[150:153], v[114:117]
	v_mfma_f32_16x16x32_bf16 v[102:105], v[220:223], v[166:169], v[102:105]
	v_mfma_f32_16x16x32_bf16 v[98:101], v[228:231], v[166:169], v[98:101]
	v_mfma_f32_16x16x32_bf16 v[86:89], v[220:223], v[184:187], v[86:89]
	v_mfma_f32_16x16x32_bf16 v[82:85], v[228:231], v[184:187], v[82:85]
	s_barrier
; #define PG8_STAGE(bufoff, gbase, voff) do { _Pragma("unroll") for (int _i = 0; _i < 2; ++_i) \
;         __builtin_amdgcn_global_load_lds((const unsigned*)((const char*)(gbase) + (voff)[_i]), (LAS unsigned*)(lds + (bufoff) + ldsw + _i * 8192), 16, 0, 0); } while (0)
; #define PG8_LDA(dst, b, h) do { _Pragma("unroll") for (int m = 0; m < 4; ++m) _Pragma("unroll") for (int k = 0; k < 2; ++k) dst[m][k] = *(const LAS bf16x8*)(lds + PG8_SA(b, h) + aoff + m * 2048 + k * 1024); } while (0)
; #define PG8_MMA(ai, bj, At, Bt) do { __builtin_amdgcn_s_setprio(1); _Pragma("unroll") for (int m = 0; m < 4; ++m) _Pragma("unroll") for (int n = 0; n < 2; ++n) _Pragma("unroll") for (int k = 0; k < 2; ++k) \
;         acc[ai][bj][m][n] = __builtin_amdgcn_mfma_f32_16x16x32_bf16(Bt[n][k], At[m][k], acc[ai][bj][m][n], 0, 0, 0); __builtin_amdgcn_s_setprio(0); } while (0)
; #define PG8_WAIT_V(n) asm volatile("s_waitcnt vmcnt(" #n ")" ::: "memory")
; #define PG8_WAIT_L(n) asm volatile("s_waitcnt lgkmcnt(" #n ")" ::: "memory")
; #define PG8_BAR __builtin_amdgcn_s_barrier()
; #define PG8_SCHED __builtin_amdgcn_sched_barrier(0)
;     template <int mode> __device__ __forceinline__ void run(const f32x4 (&acc)[2][2][4][2], const Unit& u, int wr, int wc, int fr, int fq, const LAS float* sc) const {
;     ...
;             const int col0 = u.pn * BM + wc * 32 + 8 * fq;
;             float sA = 1.f, sB = 1.f;
;             if (mode == 4) scales2(u, wr, fr, fq, sA, sB);
;             f32x4 bvv[4];
; #pragma unroll
;             for (int q = 0; q < 4; ++q) bvv[q] = (mode != 4 && bias) ? *(const f32x4*)(bias + col0 + (q >> 1) * HALF + (q & 1) * 4) : (f32x4){0.f, 0.f, 0.f, 0.f};
; template <int MODE, class EpiT, class Sched>
; __device__ __forceinline__ void gemm_phase(LAS unsigned char* lds, const Gemm g, const Sched& S, const EpiT& E) {
;     ...
;             PG8_BAR; PG8_WAIT_L(0); PG8_MMA(0, 1, At, B1); PG8_BAR;
;             PG8_LDA(At, 1, 1); PG8_STAGE(PG8_SA(1, 0), a3, voffA);
;             PG8_BAR; PG8_WAIT_L(0); PG8_MMA(1, 0, At, B0); PG8_BAR; PG8_SCHED;
;             PG8_STAGE(PG8_SB(1, 1), b3 + hstep, voffB);
;             PG8_WAIT_V(6); PG8_BAR; PG8_MMA(1, 1, At, B1); PG8_BAR;
;         }
;         E.template run<MODE>(acc, cur, wr, wc, fr, fq, SC + ui * 256);
	s_setprio 0
	s_mov_b32 m0, s61
	ds_read_b128 v[138:141], v196 offset:49152
	ds_read_b128 v[142:145], v196 offset:50176
	ds_read_b128 v[146:149], v196 offset:51200
	ds_read_b128 v[150:153], v196 offset:52224
	ds_read_b128 v[162:165], v196 offset:53248
	ds_read_b128 v[166:169], v196 offset:54272
	ds_read_b128 v[170:173], v196 offset:55296
	global_load_lds_dwordx4 v0, s[100:101]
	s_mov_b32 m0, s74
	ds_read_b128 v[184:187], v196 offset:56320
	global_load_lds_dwordx4 v174, s[100:101]
	s_setprio 1
	s_barrier
	s_waitcnt lgkmcnt(0)
	v_mfma_f32_16x16x32_bf16 v[78:81], v[58:61], v[138:141], v[78:81]
	v_mfma_f32_16x16x32_bf16 v[66:69], v[70:73], v[138:141], v[66:69]
	v_mfma_f32_16x16x32_bf16 v[46:49], v[58:61], v[146:149], v[46:49]
	v_mfma_f32_16x16x32_bf16 v[42:45], v[70:73], v[146:149], v[42:45]
	v_mfma_f32_16x16x32_bf16 v[30:33], v[58:61], v[162:165], v[30:33]
	v_mfma_f32_16x16x32_bf16 v[26:29], v[70:73], v[162:165], v[26:29]
	v_mfma_f32_16x16x32_bf16 v[14:17], v[58:61], v[170:173], v[14:17]
	v_mfma_f32_16x16x32_bf16 v[10:13], v[70:73], v[170:173], v[10:13]
	v_mfma_f32_16x16x32_bf16 v[78:81], v[62:65], v[142:145], v[78:81]
	v_mfma_f32_16x16x32_bf16 v[66:69], v[74:77], v[142:145], v[66:69]
	v_mfma_f32_16x16x32_bf16 v[46:49], v[62:65], v[150:153], v[46:49]
	v_mfma_f32_16x16x32_bf16 v[42:45], v[74:77], v[150:153], v[42:45]
	v_mfma_f32_16x16x32_bf16 v[30:33], v[62:65], v[166:169], v[30:33]
	v_mfma_f32_16x16x32_bf16 v[26:29], v[74:77], v[166:169], v[26:29]
	v_mfma_f32_16x16x32_bf16 v[14:17], v[62:65], v[184:187], v[14:17]
	v_mfma_f32_16x16x32_bf16 v[10:13], v[74:77], v[184:187], v[10:13]
	s_barrier
	s_setprio 0
	s_add_u32 s98, s98, s38
	s_addc_u32 s99, s99, 0
	s_add_i32 m0, s20, 0x1c000
	s_nop 0
	global_load_lds_dwordx4 v0, s[98:99]
	s_add_i32 m0, s20, 0x1e000
	s_nop 0
	global_load_lds_dwordx4 v174, s[98:99]
	s_waitcnt vmcnt(6)
	s_setprio 1
	s_barrier
	v_mfma_f32_16x16x32_bf16 v[54:57], v[188:191], v[138:141], v[54:57]
	v_mfma_f32_16x16x32_bf16 v[50:53], v[224:227], v[138:141], v[50:53]
	v_mfma_f32_16x16x32_bf16 v[38:41], v[188:191], v[146:149], v[38:41]
	v_mfma_f32_16x16x32_bf16 v[34:37], v[224:227], v[146:149], v[34:37]
	v_mfma_f32_16x16x32_bf16 v[22:25], v[188:191], v[162:165], v[22:25]
	v_mfma_f32_16x16x32_bf16 v[18:21], v[224:227], v[162:165], v[18:21]
	v_mfma_f32_16x16x32_bf16 v[6:9], v[188:191], v[170:173], v[6:9]
	v_mfma_f32_16x16x32_bf16 v[2:5], v[224:227], v[170:173], v[2:5]
	v_mfma_f32_16x16x32_bf16 v[54:57], v[220:223], v[142:145], v[54:57]
	v_mfma_f32_16x16x32_bf16 v[50:53], v[228:231], v[142:145], v[50:53]
	v_mfma_f32_16x16x32_bf16 v[38:41], v[220:223], v[150:153], v[38:41]
	v_mfma_f32_16x16x32_bf16 v[34:37], v[228:231], v[150:153], v[34:37]
	v_mfma_f32_16x16x32_bf16 v[22:25], v[220:223], v[166:169], v[22:25]
	v_mfma_f32_16x16x32_bf16 v[18:21], v[228:231], v[166:169], v[18:21]
	v_mfma_f32_16x16x32_bf16 v[6:9], v[220:223], v[184:187], v[6:9]
	v_mfma_f32_16x16x32_bf16 v[2:5], v[228:231], v[184:187], v[2:5]
	s_barrier
	s_setprio 0
	s_add_u32 s4, s4, 0x100
	s_addc_u32 s5, s5, 0
	s_add_u32 s89, s89, 0x100
	s_addc_u32 s90, s90, 0
	s_cmp_ge_u32 vcc_lo, s60
	s_mov_b32 s44, vcc_lo
	s_cbranch_scc0 .LBB0_195
	v_lshl_or_b32 v186, s24, 8, v195
	v_ashrrev_i32_e32 v187, 31, v186
	v_mov_b32_e32 v70, 0
	v_cndmask_b32_e64 v58, 0, 1, s[78:79]
	v_lshl_add_u64 v[138:139], v[186:187], 2, s[12:13]
	v_cmp_ne_u32_e64 s[44:45], 1, v58
	s_andn2_b64 vcc, exec, s[78:79]
	v_mov_b32_e32 v74, 0
	v_mov_b32_e32 v75, v70
	v_mov_b32_e32 v184, 0
	v_mov_b32_e32 v185, v70
	s_cbranch_vccnz .LBB0_198
	global_load_dwordx4 v[74:77], v[138:139], off
	s_waitcnt vmcnt(0)
	v_mov_b32_e32 v184, v76
	v_mov_b32_e32 v185, v77

; #define PG8_STAGE(bufoff, gbase, voff) do { _Pragma("unroll") for (int _i = 0; _i < 2; ++_i) \
;         __builtin_amdgcn_global_load_lds((const unsigned*)((const char*)(gbase) + (voff)[_i]), (LAS unsigned*)(lds + (bufoff) + ldsw + _i * 8192), 16, 0, 0); } while (0)
; #define PG8_LDA(dst, b, h) do { _Pragma("unroll") for (int m = 0; m < 4; ++m) _Pragma("unroll") for (int k = 0; k < 2; ++k) dst[m][k] = *(const LAS bf16x8*)(lds + PG8_SA(b, h) + aoff + m * 2048 + k * 1024); } while (0)
; #define PG8_LDB(dst, b, h) do { _Pragma("unroll") for (int n = 0; n < 2; ++n) _Pragma("unroll") for (int k = 0; k < 2; ++k) dst[n][k] = *(const LAS bf16x8*)(lds + PG8_SB(b, h) + boff + n * 2048 + k * 1024); } while (0)
; #define PG8_MMA(ai, bj, At, Bt) do { __builtin_amdgcn_s_setprio(1); _Pragma("unroll") for (int m = 0; m < 4; ++m) _Pragma("unroll") for (int n = 0; n < 2; ++n) _Pragma("unroll") for (int k = 0; k < 2; ++k) \
;         acc[ai][bj][m][n] = __builtin_amdgcn_mfma_f32_16x16x32_bf16(Bt[n][k], At[m][k], acc[ai][bj][m][n], 0, 0, 0); __builtin_amdgcn_s_setprio(0); } while (0)
; #define PG8_WAIT_V(n) asm volatile("s_waitcnt vmcnt(" #n ")" ::: "memory")
; #define PG8_WAIT_L(n) asm volatile("s_waitcnt lgkmcnt(" #n ")" ::: "memory")
; template <int MODE, class EpiT, class Sched>
; __device__ __forceinline__ void gemm_phase(LAS unsigned char* lds, const Gemm g, const Sched& S, const EpiT& E) {
;     ...
;         for (int t = 0; t < nt; t += 2) {
;             const bool last = (t == nt - 2);
;             const char* a1 = cA + (size_t)(t + 1) * kstep;
;             const char* a2 = last ? nA : cA + (size_t)(t + 2) * kstep; const char* b2 = last ? nB : cB + (size_t)(t + 2) * kstep;
;             const char* a3 = a2 + kstep; const char* b3 = b2 + kstep;
;             PG8_LDB(B0, 0, 0); PG8_SCHED; PG8_LDA(At, 0, 0); PG8_STAGE(PG8_SA(1, 1), a1 + hstep, voffA);
;             PG8_WAIT_L(8); PG8_BAR; PG8_WAIT_L(0); PG8_MMA(0, 0, At, B0); PG8_BAR; PG8_SCHED;
;             PG8_LDB(B1, 0, 1); PG8_STAGE(PG8_SB(0, 0), b2, voffB);
;             PG8_BAR; PG8_WAIT_L(0); PG8_MMA(0, 1, At, B1); PG8_BAR;
;             PG8_LDA(At, 0, 1); PG8_STAGE(PG8_SA(0, 0), a2, voffA);
;             PG8_BAR; PG8_WAIT_L(0); PG8_MMA(1, 0, At, B0); PG8_BAR; PG8_SCHED;
;             PG8_STAGE(PG8_SB(0, 1), b2 + hstep, voffB);
;             PG8_WAIT_V(6); PG8_BAR; PG8_MMA(1, 1, At, B1); PG8_BAR;
.LBB0_236:
	s_add_i32 s44, s34, 2
	s_add_u32 s38, s28, 0x80
	s_addc_u32 s35, s29, 0
	s_add_i32 s45, 0, 0x10000
	v_add_u32_e32 v136, s45, v139
	ds_read_b128 v[142:145], v136
	ds_read_b128 v[146:149], v136 offset:1024
	ds_read_b128 v[150:153], v136 offset:2048
	ds_read_b128 v[154:157], v136 offset:3072
	s_cmp_eq_u32 s52, s34
	s_cselect_b32 s34, s4, s38
	s_cselect_b32 s35, s5, s35
	s_cselect_b32 s39, s11, s43
	s_cselect_b32 s38, s10, s42
	v_lshl_add_u64 v[136:137], s[28:29], 0, v[132:133]
	s_add_i32 m0, s22, 0xc000
	ds_read_b128 v[158:161], v141
	ds_read_b128 v[162:165], v141 offset:1024
	ds_read_b128 v[166:169], v141 offset:2048
	ds_read_b128 v[170:173], v141 offset:3072
	ds_read_b128 v[174:177], v141 offset:4096
	ds_read_b128 v[182:185], v141 offset:5120
	ds_read_b128 v[186:189], v141 offset:6144
	ds_read_b128 v[190:193], v141 offset:7168
	global_load_lds_dwordx4 v[136:137], off
	v_lshl_add_u64 v[136:137], s[28:29], 0, v[134:135]
	s_add_i32 m0, s22, 0xe000
	s_nop 0
	global_load_lds_dwordx4 v[136:137], off
	s_waitcnt lgkmcnt(8)
	s_setprio 1
	s_barrier
	s_waitcnt lgkmcnt(0)
	v_mfma_f32_16x16x32_bf16 v[126:129], v[142:145], v[158:161], v[126:129]
	v_mfma_f32_16x16x32_bf16 v[122:125], v[150:153], v[158:161], v[122:125]
	v_mfma_f32_16x16x32_bf16 v[118:121], v[142:145], v[166:169], v[118:121]
	v_mfma_f32_16x16x32_bf16 v[110:113], v[150:153], v[166:169], v[110:113]
	v_mfma_f32_16x16x32_bf16 v[102:105], v[142:145], v[174:177], v[102:105]
	v_mfma_f32_16x16x32_bf16 v[94:97], v[150:153], v[174:177], v[94:97]
	v_mfma_f32_16x16x32_bf16 v[86:89], v[142:145], v[186:189], v[86:89]
	v_mfma_f32_16x16x32_bf16 v[78:81], v[150:153], v[186:189], v[78:81]
	v_mfma_f32_16x16x32_bf16 v[126:129], v[146:149], v[162:165], v[126:129]
	v_mfma_f32_16x16x32_bf16 v[122:125], v[154:157], v[162:165], v[122:125]
	v_mfma_f32_16x16x32_bf16 v[118:121], v[146:149], v[170:173], v[118:121]
	v_mfma_f32_16x16x32_bf16 v[110:113], v[154:157], v[170:173], v[110:113]
	v_mfma_f32_16x16x32_bf16 v[102:105], v[146:149], v[182:185], v[102:105]
	v_mfma_f32_16x16x32_bf16 v[94:97], v[154:157], v[182:185], v[94:97]
	v_mfma_f32_16x16x32_bf16 v[86:89], v[146:149], v[190:193], v[86:89]
	v_mfma_f32_16x16x32_bf16 v[78:81], v[154:157], v[190:193], v[78:81]
	s_barrier
	s_setprio 0
	s_add_i32 s58, 0, 0x14000
	v_add_u32_e32 v136, s58, v139
	s_add_i32 s45, s45, s9
	ds_read_b128 v[194:197], v136
	ds_read_b128 v[220:223], v136 offset:1024
	ds_read_b128 v[224:227], v136 offset:2048
	ds_read_b128 v[228:231], v136 offset:3072
	v_lshl_add_u64 v[136:137], s[38:39], 0, v[0:1]
	s_mov_b32 m0, s45
	v_lshl_add_u64 v[198:199], s[38:39], 0, v[130:131]
	global_load_lds_dwordx4 v[136:137], off
	s_add_i32 m0, s45, 0x2000
	s_nop 0
	global_load_lds_dwordx4 v[198:199], off
	s_setprio 1
	s_barrier
	s_waitcnt lgkmcnt(0)
	v_mfma_f32_16x16x32_bf16 v[114:117], v[194:197], v[158:161], v[114:117]
	v_mfma_f32_16x16x32_bf16 v[106:109], v[224:227], v[158:161], v[106:109]
	v_mfma_f32_16x16x32_bf16 v[98:101], v[194:197], v[166:169], v[98:101]
	v_mfma_f32_16x16x32_bf16 v[90:93], v[224:227], v[166:169], v[90:93]
	v_mfma_f32_16x16x32_bf16 v[82:85], v[194:197], v[174:177], v[82:85]
	v_mfma_f32_16x16x32_bf16 v[74:77], v[224:227], v[174:177], v[74:77]
	v_mfma_f32_16x16x32_bf16 v[70:73], v[194:197], v[186:189], v[70:73]
	v_mfma_f32_16x16x32_bf16 v[66:69], v[224:227], v[186:189], v[66:69]
	v_mfma_f32_16x16x32_bf16 v[114:117], v[220:223], v[162:165], v[114:117]
	v_mfma_f32_16x16x32_bf16 v[106:109], v[228:231], v[162:165], v[106:109]
	v_mfma_f32_16x16x32_bf16 v[98:101], v[220:223], v[170:173], v[98:101]
	v_mfma_f32_16x16x32_bf16 v[90:93], v[228:231], v[170:173], v[90:93]
	v_mfma_f32_16x16x32_bf16 v[82:85], v[220:223], v[182:185], v[82:85]
	v_mfma_f32_16x16x32_bf16 v[74:77], v[228:231], v[182:185], v[74:77]
	v_mfma_f32_16x16x32_bf16 v[70:73], v[220:223], v[190:193], v[70:73]
	v_mfma_f32_16x16x32_bf16 v[66:69], v[228:231], v[190:193], v[66:69]
	s_barrier
	s_setprio 0
	s_mov_b32 m0, s22
	v_lshl_add_u64 v[232:233], s[34:35], 0, v[0:1]
	ds_read_b128 v[158:161], v141 offset:16384
	ds_read_b128 v[162:165], v141 offset:17408
	ds_read_b128 v[166:169], v141 offset:18432
	ds_read_b128 v[170:173], v141 offset:19456
	ds_read_b128 v[174:177], v141 offset:20480
	ds_read_b128 v[182:185], v141 offset:21504
	ds_read_b128 v[186:189], v141 offset:22528
	ds_read_b128 v[190:193], v141 offset:23552
	global_load_lds_dwordx4 v[232:233], off
	v_lshl_add_u64 v[234:235], s[34:35], 0, v[130:131]
	s_mov_b32 m0, s23
	s_nop 0
	global_load_lds_dwordx4 v[234:235], off
	s_setprio 1
	s_barrier
	s_waitcnt lgkmcnt(0)
	v_mfma_f32_16x16x32_bf16 v[62:65], v[142:145], v[158:161], v[62:65]
	v_mfma_f32_16x16x32_bf16 v[58:61], v[150:153], v[158:161], v[58:61]
	v_mfma_f32_16x16x32_bf16 v[54:57], v[142:145], v[166:169], v[54:57]
	v_mfma_f32_16x16x32_bf16 v[46:49], v[150:153], v[166:169], v[46:49]
	v_mfma_f32_16x16x32_bf16 v[38:41], v[142:145], v[174:177], v[38:41]
	v_mfma_f32_16x16x32_bf16 v[30:33], v[150:153], v[174:177], v[30:33]
	v_mfma_f32_16x16x32_bf16 v[22:25], v[142:145], v[186:189], v[22:25]
	v_mfma_f32_16x16x32_bf16 v[14:17], v[150:153], v[186:189], v[14:17]
	v_mfma_f32_16x16x32_bf16 v[62:65], v[146:149], v[162:165], v[62:65]
	v_mfma_f32_16x16x32_bf16 v[58:61], v[154:157], v[162:165], v[58:61]
	v_mfma_f32_16x16x32_bf16 v[54:57], v[146:149], v[170:173], v[54:57]
	v_mfma_f32_16x16x32_bf16 v[46:49], v[154:157], v[170:173], v[46:49]
	v_mfma_f32_16x16x32_bf16 v[38:41], v[146:149], v[182:185], v[38:41]
	v_mfma_f32_16x16x32_bf16 v[30:33], v[154:157], v[182:185], v[30:33]
	v_mfma_f32_16x16x32_bf16 v[22:25], v[146:149], v[190:193], v[22:25]
	v_mfma_f32_16x16x32_bf16 v[14:17], v[154:157], v[190:193], v[14:17]
	s_barrier
; #define PG8_STAGE(bufoff, gbase, voff) do { _Pragma("unroll") for (int _i = 0; _i < 2; ++_i) \
;         __builtin_amdgcn_global_load_lds((const unsigned*)((const char*)(gbase) + (voff)[_i]), (LAS unsigned*)(lds + (bufoff) + ldsw + _i * 8192), 16, 0, 0); } while (0)
; #define PG8_LDA(dst, b, h) do { _Pragma("unroll") for (int m = 0; m < 4; ++m) _Pragma("unroll") for (int k = 0; k < 2; ++k) dst[m][k] = *(const LAS bf16x8*)(lds + PG8_SA(b, h) + aoff + m * 2048 + k * 1024); } while (0)
; #define PG8_LDB(dst, b, h) do { _Pragma("unroll") for (int n = 0; n < 2; ++n) _Pragma("unroll") for (int k = 0; k < 2; ++k) dst[n][k] = *(const LAS bf16x8*)(lds + PG8_SB(b, h) + boff + n * 2048 + k * 1024); } while (0)
; #define PG8_MMA(ai, bj, At, Bt) do { __builtin_amdgcn_s_setprio(1); _Pragma("unroll") for (int m = 0; m < 4; ++m) _Pragma("unroll") for (int n = 0; n < 2; ++n) _Pragma("unroll") for (int k = 0; k < 2; ++k) \
;         acc[ai][bj][m][n] = __builtin_amdgcn_mfma_f32_16x16x32_bf16(Bt[n][k], At[m][k], acc[ai][bj][m][n], 0, 0, 0); __builtin_amdgcn_s_setprio(0); } while (0)
; #define PG8_WAIT_V(n) asm volatile("s_waitcnt vmcnt(" #n ")" ::: "memory")
; #define PG8_WAIT_L(n) asm volatile("s_waitcnt lgkmcnt(" #n ")" ::: "memory")
; #define PG8_BAR __builtin_amdgcn_s_barrier()
; #define PG8_SCHED __builtin_amdgcn_sched_barrier(0)
; template <int MODE, class EpiT, class Sched>
; __device__ __forceinline__ void gemm_phase(LAS unsigned char* lds, const Gemm g, const Sched& S, const EpiT& E) {
;     ...
;             PG8_WAIT_V(6); PG8_BAR; PG8_MMA(1, 1, At, B1); PG8_BAR;
;             PG8_LDB(B0, 1, 0); PG8_SCHED; PG8_LDA(At, 1, 0); PG8_STAGE(PG8_SA(0, 1), a2 + hstep, voffA);
;             PG8_WAIT_L(8); PG8_BAR; PG8_WAIT_L(0); PG8_MMA(0, 0, At, B0); PG8_BAR; PG8_SCHED;
;             PG8_LDB(B1, 1, 1); PG8_STAGE(PG8_SB(1, 0), b3, voffB);
;             PG8_BAR; PG8_WAIT_L(0); PG8_MMA(0, 1, At, B1); PG8_BAR;
;             PG8_LDA(At, 1, 1); PG8_STAGE(PG8_SA(1, 0), a3, voffA);
;             PG8_BAR; PG8_WAIT_L(0); PG8_MMA(1, 0, At, B0); PG8_BAR; PG8_SCHED;
	s_setprio 0
	s_add_u32 s38, s38, s24
	s_addc_u32 s39, s39, 0
	s_add_i32 s45, s58, s9
	v_lshl_add_u64 v[236:237], s[38:39], 0, v[0:1]
	s_mov_b32 m0, s45
	v_lshl_add_u64 v[238:239], s[38:39], 0, v[130:131]
	global_load_lds_dwordx4 v[236:237], off
	s_add_i32 m0, s45, 0x2000
	s_nop 0
	global_load_lds_dwordx4 v[238:239], off
	s_waitcnt vmcnt(6)
	s_setprio 1
	s_barrier
	v_mfma_f32_16x16x32_bf16 v[50:53], v[194:197], v[158:161], v[50:53]
	v_mfma_f32_16x16x32_bf16 v[42:45], v[224:227], v[158:161], v[42:45]
	v_mfma_f32_16x16x32_bf16 v[34:37], v[194:197], v[166:169], v[34:37]
	v_mfma_f32_16x16x32_bf16 v[26:29], v[224:227], v[166:169], v[26:29]
	v_mfma_f32_16x16x32_bf16 v[18:21], v[194:197], v[174:177], v[18:21]
	v_mfma_f32_16x16x32_bf16 v[10:13], v[224:227], v[174:177], v[10:13]
	v_mfma_f32_16x16x32_bf16 v[6:9], v[194:197], v[186:189], v[6:9]
	v_mfma_f32_16x16x32_bf16 v[2:5], v[224:227], v[186:189], v[2:5]
	v_mfma_f32_16x16x32_bf16 v[50:53], v[220:223], v[162:165], v[50:53]
	v_mfma_f32_16x16x32_bf16 v[42:45], v[228:231], v[162:165], v[42:45]
	v_mfma_f32_16x16x32_bf16 v[34:37], v[220:223], v[170:173], v[34:37]
	v_mfma_f32_16x16x32_bf16 v[26:29], v[228:231], v[170:173], v[26:29]
	v_mfma_f32_16x16x32_bf16 v[18:21], v[220:223], v[182:185], v[18:21]
	v_mfma_f32_16x16x32_bf16 v[10:13], v[228:231], v[182:185], v[10:13]
	v_mfma_f32_16x16x32_bf16 v[6:9], v[220:223], v[190:193], v[6:9]
	v_mfma_f32_16x16x32_bf16 v[2:5], v[228:231], v[190:193], v[2:5]
	s_barrier
	s_setprio 0
	s_add_i32 s38, 0, 0x18000
	v_add_u32_e32 v154, s38, v139
	ds_read_b128 v[142:145], v154
	ds_read_b128 v[146:149], v154 offset:1024
	ds_read_b128 v[150:153], v154 offset:2048
	ds_read_b128 v[154:157], v154 offset:3072
	s_add_u32 s34, s34, s24
	s_addc_u32 s35, s35, 0
	s_mov_b32 m0, s30
	v_lshl_add_u64 v[194:195], s[34:35], 0, v[0:1]
	ds_read_b128 v[158:161], v141 offset:32768
	ds_read_b128 v[162:165], v141 offset:33792
	ds_read_b128 v[166:169], v141 offset:34816
	ds_read_b128 v[170:173], v141 offset:35840
	ds_read_b128 v[174:177], v141 offset:36864
	ds_read_b128 v[182:185], v141 offset:37888
	ds_read_b128 v[186:189], v141 offset:38912
	ds_read_b128 v[190:193], v141 offset:39936
	global_load_lds_dwordx4 v[194:195], off
	v_lshl_add_u64 v[194:195], s[34:35], 0, v[130:131]
	s_mov_b32 m0, s46
	s_nop 0
	global_load_lds_dwordx4 v[194:195], off
	s_waitcnt lgkmcnt(8)
	s_setprio 1
	s_barrier
	s_waitcnt lgkmcnt(0)
	v_mfma_f32_16x16x32_bf16 v[126:129], v[142:145], v[158:161], v[126:129]
	v_mfma_f32_16x16x32_bf16 v[122:125], v[150:153], v[158:161], v[122:125]
	v_mfma_f32_16x16x32_bf16 v[118:121], v[142:145], v[166:169], v[118:121]
	v_mfma_f32_16x16x32_bf16 v[110:113], v[150:153], v[166:169], v[110:113]
	v_mfma_f32_16x16x32_bf16 v[102:105], v[142:145], v[174:177], v[102:105]
	v_mfma_f32_16x16x32_bf16 v[94:97], v[150:153], v[174:177], v[94:97]
	v_mfma_f32_16x16x32_bf16 v[86:89], v[142:145], v[186:189], v[86:89]
	v_mfma_f32_16x16x32_bf16 v[78:81], v[150:153], v[186:189], v[78:81]
	v_mfma_f32_16x16x32_bf16 v[126:129], v[146:149], v[162:165], v[126:129]
	v_mfma_f32_16x16x32_bf16 v[122:125], v[154:157], v[162:165], v[122:125]
	v_mfma_f32_16x16x32_bf16 v[118:121], v[146:149], v[170:173], v[118:121]
	v_mfma_f32_16x16x32_bf16 v[110:113], v[154:157], v[170:173], v[110:113]
	v_mfma_f32_16x16x32_bf16 v[102:105], v[146:149], v[182:185], v[102:105]
	v_mfma_f32_16x16x32_bf16 v[94:97], v[154:157], v[182:185], v[94:97]
	v_mfma_f32_16x16x32_bf16 v[86:89], v[146:149], v[190:193], v[86:89]
	v_mfma_f32_16x16x32_bf16 v[78:81], v[154:157], v[190:193], v[78:81]
	s_barrier
	s_setprio 0
	s_add_i32 s34, 0, 0x1c000
	s_add_i32 s35, s38, s9
	v_add_u32_e32 v181, s34, v139
	v_lshl_add_u64 v[136:137], v[136:137], 0, s[76:77]
	s_mov_b32 m0, s35
	ds_read_b128 v[194:197], v181
	ds_read_b128 v[220:223], v181 offset:1024
	ds_read_b128 v[224:227], v181 offset:2048
	ds_read_b128 v[228:231], v181 offset:3072
	global_load_lds_dwordx4 v[136:137], off
	v_lshl_add_u64 v[136:137], v[198:199], 0, s[76:77]
	s_add_i32 m0, s35, 0x2000
	s_nop 0
	global_load_lds_dwordx4 v[136:137], off
	s_setprio 1
	s_barrier
	s_waitcnt lgkmcnt(0)
	v_mfma_f32_16x16x32_bf16 v[114:117], v[194:197], v[158:161], v[114:117]
	v_mfma_f32_16x16x32_bf16 v[106:109], v[224:227], v[158:161], v[106:109]
	v_mfma_f32_16x16x32_bf16 v[98:101], v[194:197], v[166:169], v[98:101]
	v_mfma_f32_16x16x32_bf16 v[90:93], v[224:227], v[166:169], v[90:93]
	v_mfma_f32_16x16x32_bf16 v[82:85], v[194:197], v[174:177], v[82:85]
	v_mfma_f32_16x16x32_bf16 v[74:77], v[224:227], v[174:177], v[74:77]
	v_mfma_f32_16x16x32_bf16 v[70:73], v[194:197], v[186:189], v[70:73]
	v_mfma_f32_16x16x32_bf16 v[66:69], v[224:227], v[186:189], v[66:69]
	v_mfma_f32_16x16x32_bf16 v[114:117], v[220:223], v[162:165], v[114:117]
	v_mfma_f32_16x16x32_bf16 v[106:109], v[228:231], v[162:165], v[106:109]
	v_mfma_f32_16x16x32_bf16 v[98:101], v[220:223], v[170:173], v[98:101]
	v_mfma_f32_16x16x32_bf16 v[90:93], v[228:231], v[170:173], v[90:93]
	v_mfma_f32_16x16x32_bf16 v[82:85], v[220:223], v[182:185], v[82:85]
	v_mfma_f32_16x16x32_bf16 v[74:77], v[228:231], v[182:185], v[74:77]
	v_mfma_f32_16x16x32_bf16 v[70:73], v[220:223], v[190:193], v[70:73]
	v_mfma_f32_16x16x32_bf16 v[66:69], v[228:231], v[190:193], v[66:69]
	s_barrier
	s_setprio 0
	s_mov_b32 m0, s50
	v_lshl_add_u64 v[136:137], v[232:233], 0, s[76:77]
	ds_read_b128 v[158:161], v141 offset:49152
	ds_read_b128 v[162:165], v141 offset:50176
	ds_read_b128 v[166:169], v141 offset:51200
	ds_read_b128 v[170:173], v141 offset:52224
	ds_read_b128 v[174:177], v141 offset:53248
	ds_read_b128 v[182:185], v141 offset:54272
	ds_read_b128 v[186:189], v141 offset:55296
	ds_read_b128 v[190:193], v141 offset:56320
	global_load_lds_dwordx4 v[136:137], off
	v_lshl_add_u64 v[136:137], v[234:235], 0, s[76:77]
	s_mov_b32 m0, s51
	s_nop 0
	global_load_lds_dwordx4 v[136:137], off
	s_setprio 1
	s_barrier
; #define PG8_STAGE(bufoff, gbase, voff) do { _Pragma("unroll") for (int _i = 0; _i < 2; ++_i) \
;         __builtin_amdgcn_global_load_lds((const unsigned*)((const char*)(gbase) + (voff)[_i]), (LAS unsigned*)(lds + (bufoff) + ldsw + _i * 8192), 16, 0, 0); } while (0)
; #define PG8_LDA(dst, b, h) do { _Pragma("unroll") for (int m = 0; m < 4; ++m) _Pragma("unroll") for (int k = 0; k < 2; ++k) dst[m][k] = *(const LAS bf16x8*)(lds + PG8_SA(b, h) + aoff + m * 2048 + k * 1024); } while (0)
; #define PG8_MMA(ai, bj, At, Bt) do { __builtin_amdgcn_s_setprio(1); _Pragma("unroll") for (int m = 0; m < 4; ++m) _Pragma("unroll") for (int n = 0; n < 2; ++n) _Pragma("unroll") for (int k = 0; k < 2; ++k) \
;         acc[ai][bj][m][n] = __builtin_amdgcn_mfma_f32_16x16x32_bf16(Bt[n][k], At[m][k], acc[ai][bj][m][n], 0, 0, 0); __builtin_amdgcn_s_setprio(0); } while (0)
; #define PG8_WAIT_V(n) asm volatile("s_waitcnt vmcnt(" #n ")" ::: "memory")
; #define PG8_WAIT_L(n) asm volatile("s_waitcnt lgkmcnt(" #n ")" ::: "memory")
; #define PG8_BAR __builtin_amdgcn_s_barrier()
; #define PG8_SCHED __builtin_amdgcn_sched_barrier(0)
; template <int MODE, class EpiT, class Sched>
; __device__ __forceinline__ void gemm_phase(LAS unsigned char* lds, const Gemm g, const Sched& S, const EpiT& E) {
;     ...
;             PG8_BAR; PG8_WAIT_L(0); PG8_MMA(0, 1, At, B1); PG8_BAR;
;             PG8_LDA(At, 1, 1); PG8_STAGE(PG8_SA(1, 0), a3, voffA);
;             PG8_BAR; PG8_WAIT_L(0); PG8_MMA(1, 0, At, B0); PG8_BAR; PG8_SCHED;
;             PG8_STAGE(PG8_SB(1, 1), b3 + hstep, voffB);
;             PG8_WAIT_V(6); PG8_BAR; PG8_MMA(1, 1, At, B1); PG8_BAR;
;         }
	s_waitcnt lgkmcnt(0)
	v_mfma_f32_16x16x32_bf16 v[62:65], v[142:145], v[158:161], v[62:65]
	v_mfma_f32_16x16x32_bf16 v[58:61], v[150:153], v[158:161], v[58:61]
	v_mfma_f32_16x16x32_bf16 v[54:57], v[142:145], v[166:169], v[54:57]
	v_mfma_f32_16x16x32_bf16 v[46:49], v[150:153], v[166:169], v[46:49]
	v_mfma_f32_16x16x32_bf16 v[38:41], v[142:145], v[174:177], v[38:41]
	v_mfma_f32_16x16x32_bf16 v[30:33], v[150:153], v[174:177], v[30:33]
	v_mfma_f32_16x16x32_bf16 v[22:25], v[142:145], v[186:189], v[22:25]
	v_mfma_f32_16x16x32_bf16 v[14:17], v[150:153], v[186:189], v[14:17]
	v_mfma_f32_16x16x32_bf16 v[62:65], v[146:149], v[162:165], v[62:65]
	v_mfma_f32_16x16x32_bf16 v[58:61], v[154:157], v[162:165], v[58:61]
	v_mfma_f32_16x16x32_bf16 v[54:57], v[146:149], v[170:173], v[54:57]
	v_mfma_f32_16x16x32_bf16 v[46:49], v[154:157], v[170:173], v[46:49]
	v_mfma_f32_16x16x32_bf16 v[38:41], v[146:149], v[182:185], v[38:41]
	v_mfma_f32_16x16x32_bf16 v[30:33], v[154:157], v[182:185], v[30:33]
	v_mfma_f32_16x16x32_bf16 v[22:25], v[146:149], v[190:193], v[22:25]
	v_mfma_f32_16x16x32_bf16 v[14:17], v[154:157], v[190:193], v[14:17]
	s_barrier
	s_setprio 0
	s_add_i32 s34, s34, s9
	v_lshl_add_u64 v[136:137], v[236:237], 0, s[76:77]
	s_mov_b32 m0, s34
	s_nop 0
	global_load_lds_dwordx4 v[136:137], off
	v_lshl_add_u64 v[136:137], v[238:239], 0, s[76:77]
	s_add_i32 m0, s34, 0x2000
	s_nop 0
	global_load_lds_dwordx4 v[136:137], off
	s_waitcnt vmcnt(6)
	s_setprio 1
	s_barrier
	v_mfma_f32_16x16x32_bf16 v[50:53], v[194:197], v[158:161], v[50:53]
	v_mfma_f32_16x16x32_bf16 v[42:45], v[224:227], v[158:161], v[42:45]
	v_mfma_f32_16x16x32_bf16 v[34:37], v[194:197], v[166:169], v[34:37]
	v_mfma_f32_16x16x32_bf16 v[26:29], v[224:227], v[166:169], v[26:29]
	v_mfma_f32_16x16x32_bf16 v[18:21], v[194:197], v[174:177], v[18:21]
	v_mfma_f32_16x16x32_bf16 v[10:13], v[224:227], v[174:177], v[10:13]
	v_mfma_f32_16x16x32_bf16 v[6:9], v[194:197], v[186:189], v[6:9]
	v_mfma_f32_16x16x32_bf16 v[2:5], v[224:227], v[186:189], v[2:5]
	v_mfma_f32_16x16x32_bf16 v[50:53], v[220:223], v[162:165], v[50:53]
	v_mfma_f32_16x16x32_bf16 v[42:45], v[228:231], v[162:165], v[42:45]
	v_mfma_f32_16x16x32_bf16 v[34:37], v[220:223], v[170:173], v[34:37]
	v_mfma_f32_16x16x32_bf16 v[26:29], v[228:231], v[170:173], v[26:29]
	v_mfma_f32_16x16x32_bf16 v[18:21], v[220:223], v[182:185], v[18:21]
	v_mfma_f32_16x16x32_bf16 v[10:13], v[228:231], v[182:185], v[10:13]
	v_mfma_f32_16x16x32_bf16 v[6:9], v[220:223], v[190:193], v[6:9]
	v_mfma_f32_16x16x32_bf16 v[2:5], v[228:231], v[190:193], v[2:5]
	s_barrier
	s_setprio 0
	s_add_u32 s28, s28, 0x100
	s_addc_u32 s29, s29, 0
	s_add_u32 s42, s42, 0x100
	s_addc_u32 s43, s43, 0
	s_cmp_ge_u32 s44, s47
	s_mov_b32 s34, s44
	s_cbranch_scc0 .LBB0_236
; __device__ __forceinline__ unsigned pk2(float lo, float hi) { unsigned r; asm volatile("v_cvt_pk_bf16_f32 %0, %1, %2" : "=v"(r) : "v"(lo), "v"(hi)); return r; }
; #define PG8_WAIT_V(n) asm volatile("s_waitcnt vmcnt(" #n ")" ::: "memory")
; #define PG8_BAR __builtin_amdgcn_s_barrier()
;     template <int mode> __device__ __forceinline__ void run(const f32x4 (&acc)[2][2][4][2], const Unit& u, int wr, int wc, int fr, int fq, const LAS float* sc) const {
;     ...
;         } else if (mode == 2) {
;             const int col0 = u.pn * BM + wc * 32 + 8 * fq;
; #pragma unroll
;             for (int ai = 0; ai < 2; ++ai)
; #pragma unroll
;                 for (int m = 0; m < 4; ++m) {
;                     bf16_t* rowp = ob + (size_t)(row0 + ai * HALF + m * 16) * D + col0;
; #pragma unroll
;                     for (int bj = 0; bj < 2; ++bj) {
;                         const f32x4 v0 = acc[ai][bj][m][0], v1 = acc[ai][bj][m][1];
;                         u32x4 w; w.x = pk2(v0[0], v0[1]); w.y = pk2(v0[2], v0[3]); w.z = pk2(v1[0], v1[1]); w.w = pk2(v1[2], v1[3]);
;                         *(u32x4*)(rowp + bj * HALF) = w;
;                     }
;                 }
; template <int MODE, class EpiT, class Sched>
; __device__ __forceinline__ void gemm_phase(LAS unsigned char* lds, const Gemm g, const Sched& S, const EpiT& E) {
;     ...
;         if (!has_next) break;
; #pragma unroll
;         for (int a = 0; a < 2; ++a)
; #pragma unroll
;             for (int b = 0; b < 2; ++b)
; #pragma unroll
;                 for (int m = 0; m < 4; ++m)
; #pragma unroll
;                     for (int n = 0; n < 2; ++n) acc[a][b][m][n] = (f32x4){0.f, 0.f, 0.f, 0.f};
;         cur = nxt; cA = nA; cB = nB; ++ui;
;     }
;     PG8_WAIT_V(0);
;     if (wr == 0) PG8_BAR;
;     PG8_BAR;
	v_lshl_add_u32 v142, s56, 8, v138
	v_lshl_or_b32 v136, s61, 8, v140
	v_ashrrev_i32_e32 v143, 31, v142
	v_ashrrev_i32_e32 v137, 31, v136
	v_lshlrev_b64 v[144:145], 11, v[142:143]
	v_lshl_add_u64 v[144:145], s[6:7], 0, v[144:145]
	v_lshlrev_b64 v[146:147], 1, v[136:137]
	v_lshl_add_u64 v[136:137], v[144:145], 0, v[146:147]
	v_cvt_pk_bf16_f32 v126, v126, v127
	v_cvt_pk_bf16_f32 v127, v128, v129
	v_cvt_pk_bf16_f32 v128, v122, v123
	v_cvt_pk_bf16_f32 v129, v124, v125
	global_store_dwordx4 v[136:137], v[126:129], off
	v_cvt_pk_bf16_f32 v114, v114, v115
	v_cvt_pk_bf16_f32 v115, v116, v117
	v_cvt_pk_bf16_f32 v116, v106, v107
	v_or_b32_e32 v106, 16, v142
	v_ashrrev_i32_e32 v107, 31, v106
	v_lshlrev_b64 v[106:107], 11, v[106:107]
	v_lshl_add_u64 v[106:107], s[6:7], 0, v[106:107]
	v_cvt_pk_bf16_f32 v117, v108, v109
	global_store_dwordx4 v[136:137], v[114:117], off offset:256
	s_mov_b64 s[28:29], 0x40000
	s_mov_b32 s61, s57
	v_lshl_add_u64 v[114:115], v[106:107], 0, v[146:147]
	v_cvt_pk_bf16_f32 v106, v118, v119
	v_cvt_pk_bf16_f32 v107, v120, v121
	v_cvt_pk_bf16_f32 v108, v110, v111
	v_cvt_pk_bf16_f32 v109, v112, v113
	global_store_dwordx4 v[114:115], v[106:109], off
	v_cvt_pk_bf16_f32 v98, v98, v99
	v_cvt_pk_bf16_f32 v99, v100, v101
	v_cvt_pk_bf16_f32 v100, v90, v91
	v_or_b32_e32 v90, 32, v142
	v_ashrrev_i32_e32 v91, 31, v90
	v_lshlrev_b64 v[90:91], 11, v[90:91]
	v_lshl_add_u64 v[90:91], s[6:7], 0, v[90:91]
	v_cvt_pk_bf16_f32 v101, v92, v93
	global_store_dwordx4 v[114:115], v[98:101], off offset:256
	s_mov_b32 s56, s60
	s_mov_b64 s[34:35], s[10:11]
	v_lshl_add_u64 v[98:99], v[90:91], 0, v[146:147]
	v_cvt_pk_bf16_f32 v90, v102, v103
	v_cvt_pk_bf16_f32 v91, v104, v105
	v_cvt_pk_bf16_f32 v92, v94, v95
	v_cvt_pk_bf16_f32 v93, v96, v97
	global_store_dwordx4 v[98:99], v[90:93], off
	v_cvt_pk_bf16_f32 v82, v82, v83
	v_cvt_pk_bf16_f32 v83, v84, v85
	v_cvt_pk_bf16_f32 v84, v74, v75
	v_or_b32_e32 v74, 48, v142
	v_ashrrev_i32_e32 v75, 31, v74
	v_lshlrev_b64 v[74:75], 11, v[74:75]
	v_lshl_add_u64 v[74:75], s[6:7], 0, v[74:75]
	v_cvt_pk_bf16_f32 v85, v76, v77
	global_store_dwordx4 v[98:99], v[82:85], off offset:256
	s_nop 1
	v_lshl_add_u64 v[82:83], v[74:75], 0, v[146:147]
	v_cvt_pk_bf16_f32 v74, v86, v87
	v_cvt_pk_bf16_f32 v75, v88, v89
	v_cvt_pk_bf16_f32 v76, v78, v79
	v_cvt_pk_bf16_f32 v77, v80, v81
	global_store_dwordx4 v[82:83], v[74:77], off
	v_cvt_pk_bf16_f32 v70, v70, v71
	v_cvt_pk_bf16_f32 v71, v72, v73
	v_cvt_pk_bf16_f32 v72, v66, v67
	v_cvt_pk_bf16_f32 v73, v68, v69
	global_store_dwordx4 v[82:83], v[70:73], off offset:256
	v_cvt_pk_bf16_f32 v62, v62, v63
	v_cvt_pk_bf16_f32 v63, v64, v65
	v_cvt_pk_bf16_f32 v64, v58, v59
	v_add_co_u32_e32 v58, vcc, s91, v136
	v_lshl_add_u64 v[66:67], v[136:137], 0, s[28:29]
	s_nop 0
	v_addc_co_u32_e32 v59, vcc, 0, v137, vcc
	v_cvt_pk_bf16_f32 v65, v60, v61
	global_store_dwordx4 v[58:59], v[62:65], off
	v_cvt_pk_bf16_f32 v50, v50, v51
	v_cvt_pk_bf16_f32 v51, v52, v53
	s_mov_b64 s[28:29], 0x48000
	v_cvt_pk_bf16_f32 v52, v42, v43
	v_cvt_pk_bf16_f32 v53, v44, v45
	global_store_dwordx4 v[66:67], v[50:53], off offset:256
	v_cvt_pk_bf16_f32 v42, v54, v55
	v_cvt_pk_bf16_f32 v43, v56, v57
	v_cvt_pk_bf16_f32 v44, v46, v47
	v_cvt_pk_bf16_f32 v45, v48, v49
	s_nop 1
	v_lshl_add_u64 v[50:51], v[136:137], 0, s[28:29]
	s_mov_b32 s28, 0x48000
	v_add_co_u32_e32 v46, vcc, s28, v136
	s_mov_b64 s[28:29], 0x50000
	s_nop 0
	v_addc_co_u32_e32 v47, vcc, 0, v137, vcc
	global_store_dwordx4 v[46:47], v[42:45], off
	v_cvt_pk_bf16_f32 v34, v34, v35
	v_cvt_pk_bf16_f32 v35, v36, v37
	v_cvt_pk_bf16_f32 v36, v26, v27
	v_cvt_pk_bf16_f32 v37, v28, v29
	global_store_dwordx4 v[50:51], v[34:37], off offset:256
	v_cvt_pk_bf16_f32 v26, v38, v39
	v_cvt_pk_bf16_f32 v27, v40, v41
	v_cvt_pk_bf16_f32 v28, v30, v31
	v_cvt_pk_bf16_f32 v29, v32, v33
	s_nop 1
	v_lshl_add_u64 v[34:35], v[136:137], 0, s[28:29]
	s_mov_b32 s28, 0x50000
	v_add_co_u32_e32 v30, vcc, s28, v136
	s_mov_b64 s[28:29], 0x58000
	s_nop 0
	v_addc_co_u32_e32 v31, vcc, 0, v137, vcc
	global_store_dwordx4 v[30:31], v[26:29], off
	v_cvt_pk_bf16_f32 v18, v18, v19
	v_cvt_pk_bf16_f32 v19, v20, v21
	v_cvt_pk_bf16_f32 v20, v10, v11
	v_cvt_pk_bf16_f32 v21, v12, v13
	global_store_dwordx4 v[34:35], v[18:21], off offset:256
	v_cvt_pk_bf16_f32 v10, v22, v23
	v_cvt_pk_bf16_f32 v11, v24, v25
	v_cvt_pk_bf16_f32 v12, v14, v15
	v_cvt_pk_bf16_f32 v13, v16, v17
	s_nop 1
	v_lshl_add_u64 v[18:19], v[136:137], 0, s[28:29]
	s_mov_b32 s28, 0x58000
	v_add_co_u32_e32 v14, vcc, s28, v136
	s_mov_b64 s[28:29], s[4:5]
	s_nop 0
	v_addc_co_u32_e32 v15, vcc, 0, v137, vcc
	s_and_b64 vcc, exec, s[40:41]
	global_store_dwordx4 v[14:15], v[10:13], off
	v_cvt_pk_bf16_f32 v6, v6, v7
	v_cvt_pk_bf16_f32 v7, v8, v9
	v_cvt_pk_bf16_f32 v8, v2, v3
	v_cvt_pk_bf16_f32 v9, v4, v5
	global_store_dwordx4 v[18:19], v[6:9], off offset:256
	s_cbranch_vccz .LBB0_229
	s_waitcnt vmcnt(0)
	v_readlane_b32 s46, v247, 49
	v_readlane_b32 s50, v246, 29
	v_readlane_b32 s56, v246, 31
	v_readlane_b32 s58, v246, 33
	v_readlane_b32 s60, v246, 35
	s_cmpk_gt_u32 s2, 0xff
	s_mov_b32 s52, 0x800000
	s_movk_i32 s53, 0x1000
	s_movk_i32 s23, 0x2000
	s_movk_i32 s30, 0x2840
	s_movk_i32 s42, 0x3000
	s_mov_b64 s[44:45], 0x1800
	v_readlane_b32 s47, v247, 50
	v_readlane_b32 s43, v247, 51
	v_readlane_b32 s51, v246, 30
	v_readlane_b32 s57, v246, 32
	v_readlane_b32 s59, v246, 34
	v_readlane_b32 s61, v246, 36
	s_cbranch_scc1 .LBB0_240
	s_barrier

; #define PG8_STAGE(bufoff, gbase, voff) do { _Pragma("unroll") for (int _i = 0; _i < 2; ++_i) \
;         __builtin_amdgcn_global_load_lds((const unsigned*)((const char*)(gbase) + (voff)[_i]), (LAS unsigned*)(lds + (bufoff) + ldsw + _i * 8192), 16, 0, 0); } while (0)
; #define PG8_LDA(dst, b, h) do { _Pragma("unroll") for (int m = 0; m < 4; ++m) _Pragma("unroll") for (int k = 0; k < 2; ++k) dst[m][k] = *(const LAS bf16x8*)(lds + PG8_SA(b, h) + aoff + m * 2048 + k * 1024); } while (0)
; #define PG8_LDB(dst, b, h) do { _Pragma("unroll") for (int n = 0; n < 2; ++n) _Pragma("unroll") for (int k = 0; k < 2; ++k) dst[n][k] = *(const LAS bf16x8*)(lds + PG8_SB(b, h) + boff + n * 2048 + k * 1024); } while (0)
; #define PG8_MMA(ai, bj, At, Bt) do { __builtin_amdgcn_s_setprio(1); _Pragma("unroll") for (int m = 0; m < 4; ++m) _Pragma("unroll") for (int n = 0; n < 2; ++n) _Pragma("unroll") for (int k = 0; k < 2; ++k) \
;         acc[ai][bj][m][n] = __builtin_amdgcn_mfma_f32_16x16x32_bf16(Bt[n][k], At[m][k], acc[ai][bj][m][n], 0, 0, 0); __builtin_amdgcn_s_setprio(0); } while (0)
; #define PG8_WAIT_V(n) asm volatile("s_waitcnt vmcnt(" #n ")" ::: "memory")
; #define PG8_WAIT_L(n) asm volatile("s_waitcnt lgkmcnt(" #n ")" ::: "memory")
; template <int MODE, class EpiT, class Sched>
; __device__ __forceinline__ void gemm_phase(LAS unsigned char* lds, const Gemm g, const Sched& S, const EpiT& E) {
;     ...
;         for (int t = 0; t < nt; t += 2) {
;             const bool last = (t == nt - 2);
;             const char* a1 = cA + (size_t)(t + 1) * kstep;
;             const char* a2 = last ? nA : cA + (size_t)(t + 2) * kstep; const char* b2 = last ? nB : cB + (size_t)(t + 2) * kstep;
;             const char* a3 = a2 + kstep; const char* b3 = b2 + kstep;
;             PG8_LDB(B0, 0, 0); PG8_SCHED; PG8_LDA(At, 0, 0); PG8_STAGE(PG8_SA(1, 1), a1 + hstep, voffA);
;             PG8_WAIT_L(8); PG8_BAR; PG8_WAIT_L(0); PG8_MMA(0, 0, At, B0); PG8_BAR; PG8_SCHED;
;             PG8_LDB(B1, 0, 1); PG8_STAGE(PG8_SB(0, 0), b2, voffB);
;             PG8_BAR; PG8_WAIT_L(0); PG8_MMA(0, 1, At, B1); PG8_BAR;
;             PG8_LDA(At, 0, 1); PG8_STAGE(PG8_SA(0, 0), a2, voffA);
;             PG8_BAR; PG8_WAIT_L(0); PG8_MMA(1, 0, At, B0); PG8_BAR; PG8_SCHED;
;             PG8_STAGE(PG8_SB(0, 1), b2 + hstep, voffB);
;             PG8_WAIT_V(6); PG8_BAR; PG8_MMA(1, 1, At, B1); PG8_BAR;
.LBB0_280:
	s_add_i32 s68, s46, 2
	s_add_u32 s52, s10, s44
	s_addc_u32 s47, s11, s45
	s_add_u32 s58, s4, s44
	s_addc_u32 s53, s5, s45
	s_add_u32 s100, s10, s44
	s_addc_u32 s101, s11, s45
	s_add_u32 s100, s100, s22
	s_addc_u32 s101, s101, 0
	s_sub_u32 s100, s100, 0x80
	s_subb_u32 s101, s101, 0
	s_add_i32 s59, 0, 0x10000
	ds_read_b128 v[134:137], v250
	ds_read_b128 v[138:141], v250 offset:1024
	ds_read_b128 v[142:145], v250 offset:2048
	ds_read_b128 v[152:155], v250 offset:3072
	s_cmp_eq_u32 s60, s46
	s_cselect_b32 s46, s34, s52
	s_cselect_b32 s47, s35, s47
	s_cselect_b32 s53, s39, s53
	s_cselect_b32 s52, s38, s58
	s_add_i32 m0, s30, 0xc000
	ds_read_b128 v[162:165], v160
	ds_read_b128 v[166:169], v160 offset:1024
	ds_read_b128 v[170:173], v160 offset:2048
	ds_read_b128 v[174:177], v160 offset:3072
	ds_read_b128 v[182:185], v160 offset:4096
	ds_read_b128 v[186:189], v160 offset:5120
	ds_read_b128 v[190:193], v160 offset:6144
	global_load_lds_dwordx4 v0, s[100:101]
	s_add_i32 m0, s30, 0xe000
	ds_read_b128 v[194:197], v160 offset:7168
	global_load_lds_dwordx4 v146, s[100:101]
	s_waitcnt lgkmcnt(8)
	s_setprio 1
	s_barrier
	s_waitcnt lgkmcnt(0)
	v_mfma_f32_16x16x32_bf16 v[126:129], v[134:137], v[162:165], v[126:129]
	v_mfma_f32_16x16x32_bf16 v[122:125], v[142:145], v[162:165], v[122:125]
	v_mfma_f32_16x16x32_bf16 v[118:121], v[134:137], v[170:173], v[118:121]
	v_mfma_f32_16x16x32_bf16 v[114:117], v[142:145], v[170:173], v[114:117]
	v_mfma_f32_16x16x32_bf16 v[110:113], v[134:137], v[182:185], v[110:113]
	v_mfma_f32_16x16x32_bf16 v[106:109], v[142:145], v[182:185], v[106:109]
	v_mfma_f32_16x16x32_bf16 v[102:105], v[134:137], v[190:193], v[102:105]
	v_mfma_f32_16x16x32_bf16 v[98:101], v[142:145], v[190:193], v[98:101]
	v_mfma_f32_16x16x32_bf16 v[126:129], v[138:141], v[166:169], v[126:129]
	v_mfma_f32_16x16x32_bf16 v[122:125], v[152:155], v[166:169], v[122:125]
	v_mfma_f32_16x16x32_bf16 v[118:121], v[138:141], v[174:177], v[118:121]
	v_mfma_f32_16x16x32_bf16 v[114:117], v[152:155], v[174:177], v[114:117]
	v_mfma_f32_16x16x32_bf16 v[110:113], v[138:141], v[186:189], v[110:113]
	v_mfma_f32_16x16x32_bf16 v[106:109], v[152:155], v[186:189], v[106:109]
	v_mfma_f32_16x16x32_bf16 v[102:105], v[138:141], v[194:197], v[102:105]
	v_mfma_f32_16x16x32_bf16 v[98:101], v[152:155], v[194:197], v[98:101]
	s_barrier
	s_setprio 0
	s_add_i32 s58, 0, 0x14000
	s_add_i32 s59, s59, s24
	s_add_u32 s98, s52, 0x80
	s_addc_u32 s99, s53, 0
	s_mov_b32 m0, s59
	ds_read_b128 v[220:223], v250 offset:16384
	ds_read_b128 v[224:227], v250 offset:17408
	ds_read_b128 v[228:231], v250 offset:18432
	global_load_lds_dwordx4 v0, s[52:53]
	s_add_i32 m0, s59, 0x2000
	ds_read_b128 v[232:235], v250 offset:19456
	global_load_lds_dwordx4 v146, s[52:53]
	s_setprio 1
	s_barrier
	s_waitcnt lgkmcnt(0)
	v_mfma_f32_16x16x32_bf16 v[94:97], v[220:223], v[162:165], v[94:97]
	v_mfma_f32_16x16x32_bf16 v[90:93], v[228:231], v[162:165], v[90:93]
	v_mfma_f32_16x16x32_bf16 v[86:89], v[220:223], v[170:173], v[86:89]
	v_mfma_f32_16x16x32_bf16 v[82:85], v[228:231], v[170:173], v[82:85]
	v_mfma_f32_16x16x32_bf16 v[78:81], v[220:223], v[182:185], v[78:81]
	v_mfma_f32_16x16x32_bf16 v[74:77], v[228:231], v[182:185], v[74:77]
	v_mfma_f32_16x16x32_bf16 v[70:73], v[220:223], v[190:193], v[70:73]
	v_mfma_f32_16x16x32_bf16 v[66:69], v[228:231], v[190:193], v[66:69]
	v_mfma_f32_16x16x32_bf16 v[94:97], v[224:227], v[166:169], v[94:97]
	v_mfma_f32_16x16x32_bf16 v[90:93], v[232:235], v[166:169], v[90:93]
	v_mfma_f32_16x16x32_bf16 v[86:89], v[224:227], v[174:177], v[86:89]
	v_mfma_f32_16x16x32_bf16 v[82:85], v[232:235], v[174:177], v[82:85]
	v_mfma_f32_16x16x32_bf16 v[78:81], v[224:227], v[186:189], v[78:81]
	v_mfma_f32_16x16x32_bf16 v[74:77], v[232:235], v[186:189], v[74:77]
	v_mfma_f32_16x16x32_bf16 v[70:73], v[224:227], v[194:197], v[70:73]
	v_mfma_f32_16x16x32_bf16 v[66:69], v[232:235], v[194:197], v[66:69]
	s_barrier
	s_setprio 0
	s_mov_b32 m0, s30
	s_add_u32 s100, s46, 0x80
	s_addc_u32 s101, s47, 0
	ds_read_b128 v[162:165], v160 offset:16384
	ds_read_b128 v[166:169], v160 offset:17408
	ds_read_b128 v[170:173], v160 offset:18432
	ds_read_b128 v[174:177], v160 offset:19456
	ds_read_b128 v[182:185], v160 offset:20480
	ds_read_b128 v[186:189], v160 offset:21504
	ds_read_b128 v[190:193], v160 offset:22528
	global_load_lds_dwordx4 v0, s[46:47]
	s_mov_b32 m0, s50
	ds_read_b128 v[194:197], v160 offset:23552
	global_load_lds_dwordx4 v146, s[46:47]
	s_setprio 1
	s_barrier
	s_waitcnt lgkmcnt(0)
	v_mfma_f32_16x16x32_bf16 v[62:65], v[134:137], v[162:165], v[62:65]
	v_mfma_f32_16x16x32_bf16 v[58:61], v[142:145], v[162:165], v[58:61]
	v_mfma_f32_16x16x32_bf16 v[54:57], v[134:137], v[170:173], v[54:57]
	v_mfma_f32_16x16x32_bf16 v[50:53], v[142:145], v[170:173], v[50:53]
	v_mfma_f32_16x16x32_bf16 v[46:49], v[134:137], v[182:185], v[46:49]
	v_mfma_f32_16x16x32_bf16 v[42:45], v[142:145], v[182:185], v[42:45]
	v_mfma_f32_16x16x32_bf16 v[38:41], v[134:137], v[190:193], v[38:41]
	v_mfma_f32_16x16x32_bf16 v[34:37], v[142:145], v[190:193], v[34:37]
	v_mfma_f32_16x16x32_bf16 v[62:65], v[138:141], v[166:169], v[62:65]
	v_mfma_f32_16x16x32_bf16 v[58:61], v[152:155], v[166:169], v[58:61]
	v_mfma_f32_16x16x32_bf16 v[54:57], v[138:141], v[174:177], v[54:57]
	v_mfma_f32_16x16x32_bf16 v[50:53], v[152:155], v[174:177], v[50:53]
	v_mfma_f32_16x16x32_bf16 v[46:49], v[138:141], v[186:189], v[46:49]
	v_mfma_f32_16x16x32_bf16 v[42:45], v[152:155], v[186:189], v[42:45]
	v_mfma_f32_16x16x32_bf16 v[38:41], v[138:141], v[194:197], v[38:41]
	v_mfma_f32_16x16x32_bf16 v[34:37], v[152:155], v[194:197], v[34:37]
	s_barrier
; #define PG8_STAGE(bufoff, gbase, voff) do { _Pragma("unroll") for (int _i = 0; _i < 2; ++_i) \
;         __builtin_amdgcn_global_load_lds((const unsigned*)((const char*)(gbase) + (voff)[_i]), (LAS unsigned*)(lds + (bufoff) + ldsw + _i * 8192), 16, 0, 0); } while (0)
; #define PG8_LDA(dst, b, h) do { _Pragma("unroll") for (int m = 0; m < 4; ++m) _Pragma("unroll") for (int k = 0; k < 2; ++k) dst[m][k] = *(const LAS bf16x8*)(lds + PG8_SA(b, h) + aoff + m * 2048 + k * 1024); } while (0)
; #define PG8_LDB(dst, b, h) do { _Pragma("unroll") for (int n = 0; n < 2; ++n) _Pragma("unroll") for (int k = 0; k < 2; ++k) dst[n][k] = *(const LAS bf16x8*)(lds + PG8_SB(b, h) + boff + n * 2048 + k * 1024); } while (0)
; #define PG8_MMA(ai, bj, At, Bt) do { __builtin_amdgcn_s_setprio(1); _Pragma("unroll") for (int m = 0; m < 4; ++m) _Pragma("unroll") for (int n = 0; n < 2; ++n) _Pragma("unroll") for (int k = 0; k < 2; ++k) \
;         acc[ai][bj][m][n] = __builtin_amdgcn_mfma_f32_16x16x32_bf16(Bt[n][k], At[m][k], acc[ai][bj][m][n], 0, 0, 0); __builtin_amdgcn_s_setprio(0); } while (0)
; #define PG8_WAIT_V(n) asm volatile("s_waitcnt vmcnt(" #n ")" ::: "memory")
; #define PG8_WAIT_L(n) asm volatile("s_waitcnt lgkmcnt(" #n ")" ::: "memory")
; #define PG8_BAR __builtin_amdgcn_s_barrier()
; #define PG8_SCHED __builtin_amdgcn_sched_barrier(0)
; template <int MODE, class EpiT, class Sched>
; __device__ __forceinline__ void gemm_phase(LAS unsigned char* lds, const Gemm g, const Sched& S, const EpiT& E) {
;     ...
;             PG8_WAIT_V(6); PG8_BAR; PG8_MMA(1, 1, At, B1); PG8_BAR;
;             PG8_LDB(B0, 1, 0); PG8_SCHED; PG8_LDA(At, 1, 0); PG8_STAGE(PG8_SA(0, 1), a2 + hstep, voffA);
;             PG8_WAIT_L(8); PG8_BAR; PG8_WAIT_L(0); PG8_MMA(0, 0, At, B0); PG8_BAR; PG8_SCHED;
;             PG8_LDB(B1, 1, 1); PG8_STAGE(PG8_SB(1, 0), b3, voffB);
;             PG8_BAR; PG8_WAIT_L(0); PG8_MMA(0, 1, At, B1); PG8_BAR;
;             PG8_LDA(At, 1, 1); PG8_STAGE(PG8_SA(1, 0), a3, voffA);
;             PG8_BAR; PG8_WAIT_L(0); PG8_MMA(1, 0, At, B0); PG8_BAR; PG8_SCHED;
	s_setprio 0
	s_add_u32 s52, s52, s22
	s_addc_u32 s53, s53, 0
	s_add_i32 s58, s58, s24
	s_mov_b32 m0, s58
	s_nop 0
	global_load_lds_dwordx4 v0, s[52:53]
	s_add_i32 m0, s58, 0x2000
	s_nop 0
	global_load_lds_dwordx4 v146, s[52:53]
	s_waitcnt vmcnt(6)
	s_setprio 1
	s_barrier
	v_mfma_f32_16x16x32_bf16 v[30:33], v[220:223], v[162:165], v[30:33]
	v_mfma_f32_16x16x32_bf16 v[26:29], v[228:231], v[162:165], v[26:29]
	v_mfma_f32_16x16x32_bf16 v[22:25], v[220:223], v[170:173], v[22:25]
	v_mfma_f32_16x16x32_bf16 v[18:21], v[228:231], v[170:173], v[18:21]
	v_mfma_f32_16x16x32_bf16 v[14:17], v[220:223], v[182:185], v[14:17]
	v_mfma_f32_16x16x32_bf16 v[10:13], v[228:231], v[182:185], v[10:13]
	v_mfma_f32_16x16x32_bf16 v[6:9], v[220:223], v[190:193], v[6:9]
	v_mfma_f32_16x16x32_bf16 v[2:5], v[228:231], v[190:193], v[2:5]
	v_mfma_f32_16x16x32_bf16 v[30:33], v[224:227], v[166:169], v[30:33]
	v_mfma_f32_16x16x32_bf16 v[26:29], v[232:235], v[166:169], v[26:29]
	v_mfma_f32_16x16x32_bf16 v[22:25], v[224:227], v[174:177], v[22:25]
	v_mfma_f32_16x16x32_bf16 v[18:21], v[232:235], v[174:177], v[18:21]
	v_mfma_f32_16x16x32_bf16 v[14:17], v[224:227], v[186:189], v[14:17]
	v_mfma_f32_16x16x32_bf16 v[10:13], v[232:235], v[186:189], v[10:13]
	v_mfma_f32_16x16x32_bf16 v[6:9], v[224:227], v[194:197], v[6:9]
	v_mfma_f32_16x16x32_bf16 v[2:5], v[232:235], v[194:197], v[2:5]
	s_barrier
	s_setprio 0
	s_add_i32 s52, 0, 0x18000
	ds_read_b128 v[134:137], v250 offset:32768
	ds_read_b128 v[138:141], v250 offset:33792
	ds_read_b128 v[142:145], v250 offset:34816
	ds_read_b128 v[152:155], v250 offset:35840
	s_add_u32 s46, s46, s22
	s_addc_u32 s47, s47, 0
	s_mov_b32 m0, s51
	ds_read_b128 v[162:165], v160 offset:32768
	ds_read_b128 v[166:169], v160 offset:33792
	ds_read_b128 v[170:173], v160 offset:34816
	ds_read_b128 v[174:177], v160 offset:35840
	ds_read_b128 v[182:185], v160 offset:36864
	ds_read_b128 v[186:189], v160 offset:37888
	ds_read_b128 v[190:193], v160 offset:38912
	global_load_lds_dwordx4 v0, s[46:47]
	s_mov_b32 m0, s54
	ds_read_b128 v[194:197], v160 offset:39936
	global_load_lds_dwordx4 v146, s[46:47]
	s_waitcnt lgkmcnt(8)
	s_setprio 1
	s_barrier
	s_waitcnt lgkmcnt(0)
	v_mfma_f32_16x16x32_bf16 v[126:129], v[134:137], v[162:165], v[126:129]
	v_mfma_f32_16x16x32_bf16 v[122:125], v[142:145], v[162:165], v[122:125]
	v_mfma_f32_16x16x32_bf16 v[118:121], v[134:137], v[170:173], v[118:121]
	v_mfma_f32_16x16x32_bf16 v[114:117], v[142:145], v[170:173], v[114:117]
	v_mfma_f32_16x16x32_bf16 v[110:113], v[134:137], v[182:185], v[110:113]
	v_mfma_f32_16x16x32_bf16 v[106:109], v[142:145], v[182:185], v[106:109]
	v_mfma_f32_16x16x32_bf16 v[102:105], v[134:137], v[190:193], v[102:105]
	v_mfma_f32_16x16x32_bf16 v[98:101], v[142:145], v[190:193], v[98:101]
	v_mfma_f32_16x16x32_bf16 v[126:129], v[138:141], v[166:169], v[126:129]
	v_mfma_f32_16x16x32_bf16 v[122:125], v[152:155], v[166:169], v[122:125]
	v_mfma_f32_16x16x32_bf16 v[118:121], v[138:141], v[174:177], v[118:121]
	v_mfma_f32_16x16x32_bf16 v[114:117], v[152:155], v[174:177], v[114:117]
	v_mfma_f32_16x16x32_bf16 v[110:113], v[138:141], v[186:189], v[110:113]
	v_mfma_f32_16x16x32_bf16 v[106:109], v[152:155], v[186:189], v[106:109]
	v_mfma_f32_16x16x32_bf16 v[102:105], v[138:141], v[194:197], v[102:105]
	v_mfma_f32_16x16x32_bf16 v[98:101], v[152:155], v[194:197], v[98:101]
	s_barrier
	s_setprio 0
	s_add_i32 s46, 0, 0x1c000
	s_add_i32 s47, s52, s24
	s_mov_b32 m0, s47
	ds_read_b128 v[220:223], v250 offset:49152
	ds_read_b128 v[224:227], v250 offset:50176
	ds_read_b128 v[228:231], v250 offset:51200
	global_load_lds_dwordx4 v0, s[98:99]
	s_add_i32 m0, s47, 0x2000
	ds_read_b128 v[232:235], v250 offset:52224
	global_load_lds_dwordx4 v146, s[98:99]
	s_setprio 1
	s_barrier
; #define PG8_STAGE(bufoff, gbase, voff) do { _Pragma("unroll") for (int _i = 0; _i < 2; ++_i) \
;         __builtin_amdgcn_global_load_lds((const unsigned*)((const char*)(gbase) + (voff)[_i]), (LAS unsigned*)(lds + (bufoff) + ldsw + _i * 8192), 16, 0, 0); } while (0)
; #define PG8_LDA(dst, b, h) do { _Pragma("unroll") for (int m = 0; m < 4; ++m) _Pragma("unroll") for (int k = 0; k < 2; ++k) dst[m][k] = *(const LAS bf16x8*)(lds + PG8_SA(b, h) + aoff + m * 2048 + k * 1024); } while (0)
; #define PG8_MMA(ai, bj, At, Bt) do { __builtin_amdgcn_s_setprio(1); _Pragma("unroll") for (int m = 0; m < 4; ++m) _Pragma("unroll") for (int n = 0; n < 2; ++n) _Pragma("unroll") for (int k = 0; k < 2; ++k) \
;         acc[ai][bj][m][n] = __builtin_amdgcn_mfma_f32_16x16x32_bf16(Bt[n][k], At[m][k], acc[ai][bj][m][n], 0, 0, 0); __builtin_amdgcn_s_setprio(0); } while (0)
; #define PG8_WAIT_V(n) asm volatile("s_waitcnt vmcnt(" #n ")" ::: "memory")
; #define PG8_WAIT_L(n) asm volatile("s_waitcnt lgkmcnt(" #n ")" ::: "memory")
; #define PG8_BAR __builtin_amdgcn_s_barrier()
; #define PG8_SCHED __builtin_amdgcn_sched_barrier(0)
;     template <int mode> __device__ __forceinline__ void run(const f32x4 (&acc)[2][2][4][2], const Unit& u, int wr, int wc, int fr, int fq, const LAS float* sc) const {
;     ...
;             const int col0 = u.pn * BM + wc * 32 + 8 * fq;
;             float sA = 1.f, sB = 1.f;
;             if (mode == 4) scales2(u, wr, fr, fq, sA, sB);
;             f32x4 bvv[4];
; #pragma unroll
;             for (int q = 0; q < 4; ++q) bvv[q] = (mode != 4 && bias) ? *(const f32x4*)(bias + col0 + (q >> 1) * HALF + (q & 1) * 4) : (f32x4){0.f, 0.f, 0.f, 0.f};
; template <int MODE, class EpiT, class Sched>
; __device__ __forceinline__ void gemm_phase(LAS unsigned char* lds, const Gemm g, const Sched& S, const EpiT& E) {
;     ...
;             PG8_BAR; PG8_WAIT_L(0); PG8_MMA(0, 1, At, B1); PG8_BAR;
;             PG8_LDA(At, 1, 1); PG8_STAGE(PG8_SA(1, 0), a3, voffA);
;             PG8_BAR; PG8_WAIT_L(0); PG8_MMA(1, 0, At, B0); PG8_BAR; PG8_SCHED;
;             PG8_STAGE(PG8_SB(1, 1), b3 + hstep, voffB);
;             PG8_WAIT_V(6); PG8_BAR; PG8_MMA(1, 1, At, B1); PG8_BAR;
;         }
;         E.template run<MODE>(acc, cur, wr, wc, fr, fq, SC + ui * 256);
	s_waitcnt lgkmcnt(0)
	v_mfma_f32_16x16x32_bf16 v[94:97], v[220:223], v[162:165], v[94:97]
	v_mfma_f32_16x16x32_bf16 v[90:93], v[228:231], v[162:165], v[90:93]
	v_mfma_f32_16x16x32_bf16 v[86:89], v[220:223], v[170:173], v[86:89]
	v_mfma_f32_16x16x32_bf16 v[82:85], v[228:231], v[170:173], v[82:85]
	v_mfma_f32_16x16x32_bf16 v[78:81], v[220:223], v[182:185], v[78:81]
	v_mfma_f32_16x16x32_bf16 v[74:77], v[228:231], v[182:185], v[74:77]
	v_mfma_f32_16x16x32_bf16 v[70:73], v[220:223], v[190:193], v[70:73]
	v_mfma_f32_16x16x32_bf16 v[66:69], v[228:231], v[190:193], v[66:69]
	v_mfma_f32_16x16x32_bf16 v[94:97], v[224:227], v[166:169], v[94:97]
	v_mfma_f32_16x16x32_bf16 v[90:93], v[232:235], v[166:169], v[90:93]
	v_mfma_f32_16x16x32_bf16 v[86:89], v[224:227], v[174:177], v[86:89]
	v_mfma_f32_16x16x32_bf16 v[82:85], v[232:235], v[174:177], v[82:85]
	v_mfma_f32_16x16x32_bf16 v[78:81], v[224:227], v[186:189], v[78:81]
	v_mfma_f32_16x16x32_bf16 v[74:77], v[232:235], v[186:189], v[74:77]
	v_mfma_f32_16x16x32_bf16 v[70:73], v[224:227], v[194:197], v[70:73]
	v_mfma_f32_16x16x32_bf16 v[66:69], v[232:235], v[194:197], v[66:69]
	s_barrier
	s_setprio 0
	s_mov_b32 m0, s56
	ds_read_b128 v[162:165], v160 offset:49152
	ds_read_b128 v[166:169], v160 offset:50176
	ds_read_b128 v[170:173], v160 offset:51200
	ds_read_b128 v[174:177], v160 offset:52224
	ds_read_b128 v[182:185], v160 offset:53248
	ds_read_b128 v[186:189], v160 offset:54272
	ds_read_b128 v[190:193], v160 offset:55296
	global_load_lds_dwordx4 v0, s[100:101]
	s_mov_b32 m0, s57
	ds_read_b128 v[194:197], v160 offset:56320
	global_load_lds_dwordx4 v146, s[100:101]
	s_setprio 1
	s_barrier
	s_waitcnt lgkmcnt(0)
	v_mfma_f32_16x16x32_bf16 v[62:65], v[134:137], v[162:165], v[62:65]
	v_mfma_f32_16x16x32_bf16 v[58:61], v[142:145], v[162:165], v[58:61]
	v_mfma_f32_16x16x32_bf16 v[54:57], v[134:137], v[170:173], v[54:57]
	v_mfma_f32_16x16x32_bf16 v[50:53], v[142:145], v[170:173], v[50:53]
	v_mfma_f32_16x16x32_bf16 v[46:49], v[134:137], v[182:185], v[46:49]
	v_mfma_f32_16x16x32_bf16 v[42:45], v[142:145], v[182:185], v[42:45]
	v_mfma_f32_16x16x32_bf16 v[38:41], v[134:137], v[190:193], v[38:41]
	v_mfma_f32_16x16x32_bf16 v[34:37], v[142:145], v[190:193], v[34:37]
	v_mfma_f32_16x16x32_bf16 v[62:65], v[138:141], v[166:169], v[62:65]
	v_mfma_f32_16x16x32_bf16 v[58:61], v[152:155], v[166:169], v[58:61]
	v_mfma_f32_16x16x32_bf16 v[54:57], v[138:141], v[174:177], v[54:57]
	v_mfma_f32_16x16x32_bf16 v[50:53], v[152:155], v[174:177], v[50:53]
	v_mfma_f32_16x16x32_bf16 v[46:49], v[138:141], v[186:189], v[46:49]
	v_mfma_f32_16x16x32_bf16 v[42:45], v[152:155], v[186:189], v[42:45]
	v_mfma_f32_16x16x32_bf16 v[38:41], v[138:141], v[194:197], v[38:41]
	v_mfma_f32_16x16x32_bf16 v[34:37], v[152:155], v[194:197], v[34:37]
	s_barrier
	s_setprio 0
	s_add_i32 s46, s46, s24
	s_add_u32 s98, s98, s22
	s_addc_u32 s99, s99, 0
	s_mov_b32 m0, s46
	s_nop 0
	global_load_lds_dwordx4 v0, s[98:99]
	s_add_i32 m0, s46, 0x2000
	s_nop 0
	global_load_lds_dwordx4 v146, s[98:99]
	s_waitcnt vmcnt(6)
	s_setprio 1
	s_barrier
	v_mfma_f32_16x16x32_bf16 v[30:33], v[220:223], v[162:165], v[30:33]
	v_mfma_f32_16x16x32_bf16 v[26:29], v[228:231], v[162:165], v[26:29]
	v_mfma_f32_16x16x32_bf16 v[22:25], v[220:223], v[170:173], v[22:25]
	v_mfma_f32_16x16x32_bf16 v[18:21], v[228:231], v[170:173], v[18:21]
	v_mfma_f32_16x16x32_bf16 v[14:17], v[220:223], v[182:185], v[14:17]
	v_mfma_f32_16x16x32_bf16 v[10:13], v[228:231], v[182:185], v[10:13]
	v_mfma_f32_16x16x32_bf16 v[6:9], v[220:223], v[190:193], v[6:9]
	v_mfma_f32_16x16x32_bf16 v[2:5], v[228:231], v[190:193], v[2:5]
	v_mfma_f32_16x16x32_bf16 v[30:33], v[224:227], v[166:169], v[30:33]
	v_mfma_f32_16x16x32_bf16 v[26:29], v[232:235], v[166:169], v[26:29]
	v_mfma_f32_16x16x32_bf16 v[22:25], v[224:227], v[174:177], v[22:25]
	v_mfma_f32_16x16x32_bf16 v[18:21], v[232:235], v[174:177], v[18:21]
	v_mfma_f32_16x16x32_bf16 v[14:17], v[224:227], v[186:189], v[14:17]
	v_mfma_f32_16x16x32_bf16 v[10:13], v[232:235], v[186:189], v[10:13]
	v_mfma_f32_16x16x32_bf16 v[6:9], v[224:227], v[194:197], v[6:9]
	v_mfma_f32_16x16x32_bf16 v[2:5], v[232:235], v[194:197], v[2:5]
	s_barrier
	s_setprio 0
	s_add_u32 s44, s44, 0x100
	s_addc_u32 s45, s45, 0
	s_cmp_ge_u32 s68, s55
	s_mov_b32 s46, s68
	s_cbranch_scc0 .LBB0_280
	v_lshl_or_b32 v152, s3, 8, v159
	v_ashrrev_i32_e32 v153, 31, v152
	v_cndmask_b32_e64 v131, 0, 1, s[28:29]
	v_lshl_add_u64 v[154:155], v[152:153], 2, s[12:13]
	v_mov_b32_e32 v130, 0
	v_cmp_ne_u32_e64 s[44:45], 1, v131
	s_andn2_b64 vcc, exec, s[28:29]
	v_mov_b32_e32 v134, 0
	v_mov_b32_e32 v135, 0
	v_mov_b32_e32 v136, 0
	v_mov_b32_e32 v137, 0
	s_cbranch_vccnz .LBB0_283
	global_load_dwordx4 v[134:137], v[154:155], off

; #define PG8_STAGE(bufoff, gbase, voff) do { _Pragma("unroll") for (int _i = 0; _i < 2; ++_i) \
;         __builtin_amdgcn_global_load_lds((const unsigned*)((const char*)(gbase) + (voff)[_i]), (LAS unsigned*)(lds + (bufoff) + ldsw + _i * 8192), 16, 0, 0); } while (0)
; #define PG8_LDA(dst, b, h) do { _Pragma("unroll") for (int m = 0; m < 4; ++m) _Pragma("unroll") for (int k = 0; k < 2; ++k) dst[m][k] = *(const LAS bf16x8*)(lds + PG8_SA(b, h) + aoff + m * 2048 + k * 1024); } while (0)
; #define PG8_LDB(dst, b, h) do { _Pragma("unroll") for (int n = 0; n < 2; ++n) _Pragma("unroll") for (int k = 0; k < 2; ++k) dst[n][k] = *(const LAS bf16x8*)(lds + PG8_SB(b, h) + boff + n * 2048 + k * 1024); } while (0)
; #define PG8_MMA(ai, bj, At, Bt) do { __builtin_amdgcn_s_setprio(1); _Pragma("unroll") for (int m = 0; m < 4; ++m) _Pragma("unroll") for (int n = 0; n < 2; ++n) _Pragma("unroll") for (int k = 0; k < 2; ++k) \
;         acc[ai][bj][m][n] = __builtin_amdgcn_mfma_f32_16x16x32_bf16(Bt[n][k], At[m][k], acc[ai][bj][m][n], 0, 0, 0); __builtin_amdgcn_s_setprio(0); } while (0)
; #define PG8_WAIT_V(n) asm volatile("s_waitcnt vmcnt(" #n ")" ::: "memory")
; #define PG8_WAIT_L(n) asm volatile("s_waitcnt lgkmcnt(" #n ")" ::: "memory")
; template <int MODE, class EpiT, class Sched>
; __device__ __forceinline__ void gemm_phase(LAS unsigned char* lds, const Gemm g, const Sched& S, const EpiT& E) {
;     ...
;         for (int t = 0; t < nt; t += 2) {
;             const bool last = (t == nt - 2);
;             const char* a1 = cA + (size_t)(t + 1) * kstep;
;             const char* a2 = last ? nA : cA + (size_t)(t + 2) * kstep; const char* b2 = last ? nB : cB + (size_t)(t + 2) * kstep;
;             const char* a3 = a2 + kstep; const char* b3 = b2 + kstep;
;             PG8_LDB(B0, 0, 0); PG8_SCHED; PG8_LDA(At, 0, 0); PG8_STAGE(PG8_SA(1, 1), a1 + hstep, voffA);
;             PG8_WAIT_L(8); PG8_BAR; PG8_WAIT_L(0); PG8_MMA(0, 0, At, B0); PG8_BAR; PG8_SCHED;
;             PG8_LDB(B1, 0, 1); PG8_STAGE(PG8_SB(0, 0), b2, voffB);
;             PG8_BAR; PG8_WAIT_L(0); PG8_MMA(0, 1, At, B1); PG8_BAR;
;             PG8_LDA(At, 0, 1); PG8_STAGE(PG8_SA(0, 0), a2, voffA);
;             PG8_BAR; PG8_WAIT_L(0); PG8_MMA(1, 0, At, B0); PG8_BAR; PG8_SCHED;
;             PG8_STAGE(PG8_SB(0, 1), b2 + hstep, voffB);
;             PG8_WAIT_V(6); PG8_BAR; PG8_MMA(1, 1, At, B1); PG8_BAR;
.LBB0_332:
	s_add_i32 s23, s22, 2
	s_add_u32 s30, s12, s4
	s_addc_u32 s38, s13, s5
	s_add_u32 s44, s10, s4
	s_addc_u32 s45, s11, s5
	ds_read_b128 v[146:149], v145
	ds_read_b128 v[150:153], v145 offset:1024
	ds_read_b128 v[154:157], v145 offset:2048
	ds_read_b128 v[158:161], v145 offset:3072
	s_cmp_eq_u32 s55, s22
	s_cselect_b32 s39, s29, s38
	s_cselect_b32 s38, s28, s30
	s_cselect_b32 s45, s35, s45
	s_cselect_b32 s44, s34, s44
	s_add_i32 m0, s47, 0xc000
	ds_read_b128 v[162:165], v144
	ds_read_b128 v[166:169], v144 offset:1024
	ds_read_b128 v[170:173], v144 offset:2048
	ds_read_b128 v[174:177], v144 offset:3072
	ds_read_b128 v[182:185], v144 offset:4096
	ds_read_b128 v[186:189], v144 offset:5120
	ds_read_b128 v[190:193], v144 offset:6144
	global_load_lds_dwordx4 v0, s[100:101]
	s_add_i32 m0, s47, 0xe000
	ds_read_b128 v[194:197], v144 offset:7168
	global_load_lds_dwordx4 v130, s[100:101]
	s_waitcnt lgkmcnt(8)
	s_setprio 1
	s_barrier
	s_waitcnt lgkmcnt(0)
	v_mfma_f32_16x16x32_bf16 v[126:129], v[146:149], v[162:165], v[126:129]
	v_mfma_f32_16x16x32_bf16 v[122:125], v[154:157], v[162:165], v[122:125]
	v_mfma_f32_16x16x32_bf16 v[118:121], v[146:149], v[170:173], v[118:121]
	v_mfma_f32_16x16x32_bf16 v[114:117], v[154:157], v[170:173], v[114:117]
	v_mfma_f32_16x16x32_bf16 v[110:113], v[146:149], v[182:185], v[110:113]
	v_mfma_f32_16x16x32_bf16 v[106:109], v[154:157], v[182:185], v[106:109]
	v_mfma_f32_16x16x32_bf16 v[102:105], v[146:149], v[190:193], v[102:105]
	v_mfma_f32_16x16x32_bf16 v[98:101], v[154:157], v[190:193], v[98:101]
	v_mfma_f32_16x16x32_bf16 v[126:129], v[150:153], v[166:169], v[126:129]
	v_mfma_f32_16x16x32_bf16 v[122:125], v[158:161], v[166:169], v[122:125]
	v_mfma_f32_16x16x32_bf16 v[118:121], v[150:153], v[174:177], v[118:121]
	v_mfma_f32_16x16x32_bf16 v[114:117], v[158:161], v[174:177], v[114:117]
	v_mfma_f32_16x16x32_bf16 v[110:113], v[150:153], v[186:189], v[110:113]
	v_mfma_f32_16x16x32_bf16 v[106:109], v[158:161], v[186:189], v[106:109]
	v_mfma_f32_16x16x32_bf16 v[102:105], v[150:153], v[194:197], v[102:105]
	v_mfma_f32_16x16x32_bf16 v[98:101], v[158:161], v[194:197], v[98:101]
	s_barrier
	s_setprio 0
	s_add_u32 s98, s44, 0x80
	s_addc_u32 s99, s45, 0
	s_add_i32 m0, s46, 0x10000
	ds_read_b128 v[220:223], v145 offset:16384
	ds_read_b128 v[224:227], v145 offset:17408
	ds_read_b128 v[228:231], v145 offset:18432
	global_load_lds_dwordx4 v0, s[44:45]
	s_add_i32 m0, s46, 0x12000
	ds_read_b128 v[232:235], v145 offset:19456
	global_load_lds_dwordx4 v130, s[44:45]
	s_setprio 1
	s_barrier
	s_waitcnt lgkmcnt(0)
	v_mfma_f32_16x16x32_bf16 v[94:97], v[220:223], v[162:165], v[94:97]
	v_mfma_f32_16x16x32_bf16 v[90:93], v[228:231], v[162:165], v[90:93]
	v_mfma_f32_16x16x32_bf16 v[86:89], v[220:223], v[170:173], v[86:89]
	v_mfma_f32_16x16x32_bf16 v[82:85], v[228:231], v[170:173], v[82:85]
	v_mfma_f32_16x16x32_bf16 v[78:81], v[220:223], v[182:185], v[78:81]
	v_mfma_f32_16x16x32_bf16 v[74:77], v[228:231], v[182:185], v[74:77]
	v_mfma_f32_16x16x32_bf16 v[70:73], v[220:223], v[190:193], v[70:73]
	v_mfma_f32_16x16x32_bf16 v[66:69], v[228:231], v[190:193], v[66:69]
	v_mfma_f32_16x16x32_bf16 v[94:97], v[224:227], v[166:169], v[94:97]
	v_mfma_f32_16x16x32_bf16 v[90:93], v[232:235], v[166:169], v[90:93]
	v_mfma_f32_16x16x32_bf16 v[86:89], v[224:227], v[174:177], v[86:89]
	v_mfma_f32_16x16x32_bf16 v[82:85], v[232:235], v[174:177], v[82:85]
	v_mfma_f32_16x16x32_bf16 v[78:81], v[224:227], v[186:189], v[78:81]
	v_mfma_f32_16x16x32_bf16 v[74:77], v[232:235], v[186:189], v[74:77]
	v_mfma_f32_16x16x32_bf16 v[70:73], v[224:227], v[194:197], v[70:73]
	v_mfma_f32_16x16x32_bf16 v[66:69], v[232:235], v[194:197], v[66:69]
	s_barrier
	s_setprio 0
	s_mov_b32 m0, s47
	ds_read_b128 v[162:165], v144 offset:16384
	ds_read_b128 v[166:169], v144 offset:17408
	ds_read_b128 v[170:173], v144 offset:18432
	ds_read_b128 v[174:177], v144 offset:19456
	ds_read_b128 v[182:185], v144 offset:20480
	ds_read_b128 v[186:189], v144 offset:21504
	ds_read_b128 v[190:193], v144 offset:22528
	global_load_lds_dwordx4 v0, s[38:39]
	s_mov_b32 m0, s50
	ds_read_b128 v[194:197], v144 offset:23552
	global_load_lds_dwordx4 v130, s[38:39]
	s_setprio 1
	s_barrier
	s_waitcnt lgkmcnt(0)
	v_mfma_f32_16x16x32_bf16 v[62:65], v[146:149], v[162:165], v[62:65]
	v_mfma_f32_16x16x32_bf16 v[58:61], v[154:157], v[162:165], v[58:61]
	v_mfma_f32_16x16x32_bf16 v[54:57], v[146:149], v[170:173], v[54:57]
	v_mfma_f32_16x16x32_bf16 v[50:53], v[154:157], v[170:173], v[50:53]
	v_mfma_f32_16x16x32_bf16 v[46:49], v[146:149], v[182:185], v[46:49]
	v_mfma_f32_16x16x32_bf16 v[42:45], v[154:157], v[182:185], v[42:45]
	v_mfma_f32_16x16x32_bf16 v[38:41], v[146:149], v[190:193], v[38:41]
	v_mfma_f32_16x16x32_bf16 v[34:37], v[154:157], v[190:193], v[34:37]
	v_mfma_f32_16x16x32_bf16 v[62:65], v[150:153], v[166:169], v[62:65]
	v_mfma_f32_16x16x32_bf16 v[58:61], v[158:161], v[166:169], v[58:61]
	v_mfma_f32_16x16x32_bf16 v[54:57], v[150:153], v[174:177], v[54:57]
	v_mfma_f32_16x16x32_bf16 v[50:53], v[158:161], v[174:177], v[50:53]
	v_mfma_f32_16x16x32_bf16 v[46:49], v[150:153], v[186:189], v[46:49]
	v_mfma_f32_16x16x32_bf16 v[42:45], v[158:161], v[186:189], v[42:45]
	v_mfma_f32_16x16x32_bf16 v[38:41], v[150:153], v[194:197], v[38:41]
	v_mfma_f32_16x16x32_bf16 v[34:37], v[158:161], v[194:197], v[34:37]
	s_barrier
	s_setprio 0
	s_add_u32 s44, s44, s21
	s_addc_u32 s45, s45, 0
	s_add_i32 m0, s46, 0x14000
	s_nop 0
	global_load_lds_dwordx4 v0, s[44:45]
	s_add_i32 m0, s46, 0x16000
	s_nop 0
	global_load_lds_dwordx4 v130, s[44:45]
	s_waitcnt vmcnt(6)
	s_setprio 1
	s_barrier
; #define PG8_STAGE(bufoff, gbase, voff) do { _Pragma("unroll") for (int _i = 0; _i < 2; ++_i) \
;         __builtin_amdgcn_global_load_lds((const unsigned*)((const char*)(gbase) + (voff)[_i]), (LAS unsigned*)(lds + (bufoff) + ldsw + _i * 8192), 16, 0, 0); } while (0)
; #define PG8_LDA(dst, b, h) do { _Pragma("unroll") for (int m = 0; m < 4; ++m) _Pragma("unroll") for (int k = 0; k < 2; ++k) dst[m][k] = *(const LAS bf16x8*)(lds + PG8_SA(b, h) + aoff + m * 2048 + k * 1024); } while (0)
; #define PG8_LDB(dst, b, h) do { _Pragma("unroll") for (int n = 0; n < 2; ++n) _Pragma("unroll") for (int k = 0; k < 2; ++k) dst[n][k] = *(const LAS bf16x8*)(lds + PG8_SB(b, h) + boff + n * 2048 + k * 1024); } while (0)
; #define PG8_MMA(ai, bj, At, Bt) do { __builtin_amdgcn_s_setprio(1); _Pragma("unroll") for (int m = 0; m < 4; ++m) _Pragma("unroll") for (int n = 0; n < 2; ++n) _Pragma("unroll") for (int k = 0; k < 2; ++k) \
;         acc[ai][bj][m][n] = __builtin_amdgcn_mfma_f32_16x16x32_bf16(Bt[n][k], At[m][k], acc[ai][bj][m][n], 0, 0, 0); __builtin_amdgcn_s_setprio(0); } while (0)
; #define PG8_WAIT_V(n) asm volatile("s_waitcnt vmcnt(" #n ")" ::: "memory")
; #define PG8_WAIT_L(n) asm volatile("s_waitcnt lgkmcnt(" #n ")" ::: "memory")
; #define PG8_BAR __builtin_amdgcn_s_barrier()
; #define PG8_SCHED __builtin_amdgcn_sched_barrier(0)
; template <int MODE, class EpiT, class Sched>
; __device__ __forceinline__ void gemm_phase(LAS unsigned char* lds, const Gemm g, const Sched& S, const EpiT& E) {
;     ...
;             PG8_WAIT_V(6); PG8_BAR; PG8_MMA(1, 1, At, B1); PG8_BAR;
;             PG8_LDB(B0, 1, 0); PG8_SCHED; PG8_LDA(At, 1, 0); PG8_STAGE(PG8_SA(0, 1), a2 + hstep, voffA);
;             PG8_WAIT_L(8); PG8_BAR; PG8_WAIT_L(0); PG8_MMA(0, 0, At, B0); PG8_BAR; PG8_SCHED;
;             PG8_LDB(B1, 1, 1); PG8_STAGE(PG8_SB(1, 0), b3, voffB);
;             PG8_BAR; PG8_WAIT_L(0); PG8_MMA(0, 1, At, B1); PG8_BAR;
;             PG8_LDA(At, 1, 1); PG8_STAGE(PG8_SA(1, 0), a3, voffA);
;             PG8_BAR; PG8_WAIT_L(0); PG8_MMA(1, 0, At, B0); PG8_BAR; PG8_SCHED;
	v_mfma_f32_16x16x32_bf16 v[30:33], v[220:223], v[162:165], v[30:33]
	v_mfma_f32_16x16x32_bf16 v[26:29], v[228:231], v[162:165], v[26:29]
	v_mfma_f32_16x16x32_bf16 v[22:25], v[220:223], v[170:173], v[22:25]
	v_mfma_f32_16x16x32_bf16 v[18:21], v[228:231], v[170:173], v[18:21]
	v_mfma_f32_16x16x32_bf16 v[14:17], v[220:223], v[182:185], v[14:17]
	v_mfma_f32_16x16x32_bf16 v[10:13], v[228:231], v[182:185], v[10:13]
	v_mfma_f32_16x16x32_bf16 v[6:9], v[220:223], v[190:193], v[6:9]
	v_mfma_f32_16x16x32_bf16 v[2:5], v[228:231], v[190:193], v[2:5]
	v_mfma_f32_16x16x32_bf16 v[30:33], v[224:227], v[166:169], v[30:33]
	v_mfma_f32_16x16x32_bf16 v[26:29], v[232:235], v[166:169], v[26:29]
	v_mfma_f32_16x16x32_bf16 v[22:25], v[224:227], v[174:177], v[22:25]
	v_mfma_f32_16x16x32_bf16 v[18:21], v[232:235], v[174:177], v[18:21]
	v_mfma_f32_16x16x32_bf16 v[14:17], v[224:227], v[186:189], v[14:17]
	v_mfma_f32_16x16x32_bf16 v[10:13], v[232:235], v[186:189], v[10:13]
	v_mfma_f32_16x16x32_bf16 v[6:9], v[224:227], v[194:197], v[6:9]
	v_mfma_f32_16x16x32_bf16 v[2:5], v[232:235], v[194:197], v[2:5]
	s_barrier
	s_setprio 0
	ds_read_b128 v[146:149], v145 offset:32768
	ds_read_b128 v[150:153], v145 offset:33792
	ds_read_b128 v[154:157], v145 offset:34816
	ds_read_b128 v[158:161], v145 offset:35840
	s_add_u32 s38, s38, s21
	s_addc_u32 s39, s39, 0
	s_mov_b32 m0, s51
	ds_read_b128 v[162:165], v144 offset:32768
	ds_read_b128 v[166:169], v144 offset:33792
	ds_read_b128 v[170:173], v144 offset:34816
	ds_read_b128 v[174:177], v144 offset:35840
	ds_read_b128 v[182:185], v144 offset:36864
	ds_read_b128 v[186:189], v144 offset:37888
	ds_read_b128 v[190:193], v144 offset:38912
	global_load_lds_dwordx4 v0, s[38:39]
	s_mov_b32 m0, s52
	ds_read_b128 v[194:197], v144 offset:39936
	global_load_lds_dwordx4 v130, s[38:39]
	s_waitcnt lgkmcnt(8)
	s_setprio 1
	s_barrier
	s_waitcnt lgkmcnt(0)
	v_mfma_f32_16x16x32_bf16 v[126:129], v[146:149], v[162:165], v[126:129]
	v_mfma_f32_16x16x32_bf16 v[122:125], v[154:157], v[162:165], v[122:125]
	v_mfma_f32_16x16x32_bf16 v[118:121], v[146:149], v[170:173], v[118:121]
	v_mfma_f32_16x16x32_bf16 v[114:117], v[154:157], v[170:173], v[114:117]
	v_mfma_f32_16x16x32_bf16 v[110:113], v[146:149], v[182:185], v[110:113]
	v_mfma_f32_16x16x32_bf16 v[106:109], v[154:157], v[182:185], v[106:109]
	v_mfma_f32_16x16x32_bf16 v[102:105], v[146:149], v[190:193], v[102:105]
	v_mfma_f32_16x16x32_bf16 v[98:101], v[154:157], v[190:193], v[98:101]
	v_mfma_f32_16x16x32_bf16 v[126:129], v[150:153], v[166:169], v[126:129]
	v_mfma_f32_16x16x32_bf16 v[122:125], v[158:161], v[166:169], v[122:125]
	v_mfma_f32_16x16x32_bf16 v[118:121], v[150:153], v[174:177], v[118:121]
	v_mfma_f32_16x16x32_bf16 v[114:117], v[158:161], v[174:177], v[114:117]
	v_mfma_f32_16x16x32_bf16 v[110:113], v[150:153], v[186:189], v[110:113]
	v_mfma_f32_16x16x32_bf16 v[106:109], v[158:161], v[186:189], v[106:109]
	v_mfma_f32_16x16x32_bf16 v[102:105], v[150:153], v[194:197], v[102:105]
	v_mfma_f32_16x16x32_bf16 v[98:101], v[158:161], v[194:197], v[98:101]
	s_barrier
	s_setprio 0
	s_add_i32 m0, s46, 0x18000
	ds_read_b128 v[220:223], v145 offset:49152
	ds_read_b128 v[224:227], v145 offset:50176
	ds_read_b128 v[228:231], v145 offset:51200
	global_load_lds_dwordx4 v0, s[98:99]
	s_add_i32 m0, s46, 0x1a000
	ds_read_b128 v[232:235], v145 offset:52224
	global_load_lds_dwordx4 v130, s[98:99]
	s_setprio 1
	s_barrier
	s_waitcnt lgkmcnt(0)
	v_mfma_f32_16x16x32_bf16 v[94:97], v[220:223], v[162:165], v[94:97]
	v_mfma_f32_16x16x32_bf16 v[90:93], v[228:231], v[162:165], v[90:93]
	v_mfma_f32_16x16x32_bf16 v[86:89], v[220:223], v[170:173], v[86:89]
	v_mfma_f32_16x16x32_bf16 v[82:85], v[228:231], v[170:173], v[82:85]
	v_mfma_f32_16x16x32_bf16 v[78:81], v[220:223], v[182:185], v[78:81]
	v_mfma_f32_16x16x32_bf16 v[74:77], v[228:231], v[182:185], v[74:77]
	v_mfma_f32_16x16x32_bf16 v[70:73], v[220:223], v[190:193], v[70:73]
	v_mfma_f32_16x16x32_bf16 v[66:69], v[228:231], v[190:193], v[66:69]
	v_mfma_f32_16x16x32_bf16 v[94:97], v[224:227], v[166:169], v[94:97]
	v_mfma_f32_16x16x32_bf16 v[90:93], v[232:235], v[166:169], v[90:93]
	v_mfma_f32_16x16x32_bf16 v[86:89], v[224:227], v[174:177], v[86:89]
	v_mfma_f32_16x16x32_bf16 v[82:85], v[232:235], v[174:177], v[82:85]
	v_mfma_f32_16x16x32_bf16 v[78:81], v[224:227], v[186:189], v[78:81]
	v_mfma_f32_16x16x32_bf16 v[74:77], v[232:235], v[186:189], v[74:77]
	v_mfma_f32_16x16x32_bf16 v[70:73], v[224:227], v[194:197], v[70:73]
	v_mfma_f32_16x16x32_bf16 v[66:69], v[232:235], v[194:197], v[66:69]
	s_barrier
	s_setprio 0
	s_mov_b32 m0, s53
	s_sub_u32 s98, s38, s21
	s_subb_u32 s99, s39, 0
	s_add_u32 s98, s98, 0x80
	s_addc_u32 s99, s99, 0
	ds_read_b128 v[162:165], v144 offset:49152
	ds_read_b128 v[166:169], v144 offset:50176
	ds_read_b128 v[170:173], v144 offset:51200
	ds_read_b128 v[174:177], v144 offset:52224
	ds_read_b128 v[182:185], v144 offset:53248
	ds_read_b128 v[186:189], v144 offset:54272
	ds_read_b128 v[190:193], v144 offset:55296
	global_load_lds_dwordx4 v0, s[98:99]
	s_mov_b32 m0, s54
	ds_read_b128 v[194:197], v144 offset:56320
	global_load_lds_dwordx4 v130, s[98:99]
	s_setprio 1
	s_barrier
; __device__ __forceinline__ unsigned pk2(float lo, float hi) { unsigned r; asm volatile("v_cvt_pk_bf16_f32 %0, %1, %2" : "=v"(r) : "v"(lo), "v"(hi)); return r; }
; __device__ __forceinline__ float siluf_(float x) { return x * __builtin_amdgcn_rcpf(1.0f + __expf(-x)); }
; #define PG8_STAGE(bufoff, gbase, voff) do { _Pragma("unroll") for (int _i = 0; _i < 2; ++_i) \
;         __builtin_amdgcn_global_load_lds((const unsigned*)((const char*)(gbase) + (voff)[_i]), (LAS unsigned*)(lds + (bufoff) + ldsw + _i * 8192), 16, 0, 0); } while (0)
; #define PG8_LDA(dst, b, h) do { _Pragma("unroll") for (int m = 0; m < 4; ++m) _Pragma("unroll") for (int k = 0; k < 2; ++k) dst[m][k] = *(const LAS bf16x8*)(lds + PG8_SA(b, h) + aoff + m * 2048 + k * 1024); } while (0)
;     template <int mode> __device__ __forceinline__ void run(const f32x4 (&acc)[2][2][4][2], const Unit& u, int wr, int wc, int fr, int fq, const LAS float* sc) const {
;     ...
;         if (mode == 0) {
;             const int col0 = u.pn * HALF + wc * 32 + 8 * fq;
; #pragma unroll
;             for (int ai = 0; ai < 2; ++ai)
; #pragma unroll
;                 for (int m = 0; m < 4; ++m) {
;                     const int row = row0 + ai * HALF + m * 16;
;                     const float s = sc[ai * HALF + wr * 64 + m * 16 + fr];
;                     const f32x4 g0 = acc[ai][0][m][0] * s, u0 = acc[ai][1][m][0] * s, g1 = acc[ai][0][m][1] * s, u1 = acc[ai][1][m][1] * s;
;                     u32x4 w;
;                     w.x = pk2(siluf_(g0[0]) * u0[0], siluf_(g0[1]) * u0[1]); w.y = pk2(siluf_(g0[2]) * u0[2], siluf_(g0[3]) * u0[3]);
;                     w.z = pk2(siluf_(g1[0]) * u1[0], siluf_(g1[1]) * u1[1]); w.w = pk2(siluf_(g1[2]) * u1[2], siluf_(g1[3]) * u1[3]);
;                     *(u32x4*)(ob + (size_t)row * FF + col0) = w;
; template <int MODE, class EpiT, class Sched>
; __device__ __forceinline__ void gemm_phase(LAS unsigned char* lds, const Gemm g, const Sched& S, const EpiT& E) {
;     ...
;             PG8_BAR; PG8_WAIT_L(0); PG8_MMA(0, 1, At, B1); PG8_BAR;
;             PG8_LDA(At, 1, 1); PG8_STAGE(PG8_SA(1, 0), a3, voffA);
;             PG8_BAR; PG8_WAIT_L(0); PG8_MMA(1, 0, At, B0); PG8_BAR; PG8_SCHED;
;             PG8_STAGE(PG8_SB(1, 1), b3 + hstep, voffB);
;             PG8_WAIT_V(6); PG8_BAR; PG8_MMA(1, 1, At, B1); PG8_BAR;
;         }
;         E.template run<MODE>(acc, cur, wr, wc, fr, fq, SC + ui * 256);
	s_waitcnt lgkmcnt(0)
	v_mfma_f32_16x16x32_bf16 v[62:65], v[146:149], v[162:165], v[62:65]
	v_mfma_f32_16x16x32_bf16 v[58:61], v[154:157], v[162:165], v[58:61]
	v_mfma_f32_16x16x32_bf16 v[54:57], v[146:149], v[170:173], v[54:57]
	v_mfma_f32_16x16x32_bf16 v[50:53], v[154:157], v[170:173], v[50:53]
	v_mfma_f32_16x16x32_bf16 v[46:49], v[146:149], v[182:185], v[46:49]
	v_mfma_f32_16x16x32_bf16 v[42:45], v[154:157], v[182:185], v[42:45]
	v_mfma_f32_16x16x32_bf16 v[38:41], v[146:149], v[190:193], v[38:41]
	v_mfma_f32_16x16x32_bf16 v[34:37], v[154:157], v[190:193], v[34:37]
	v_mfma_f32_16x16x32_bf16 v[62:65], v[150:153], v[166:169], v[62:65]
	v_mfma_f32_16x16x32_bf16 v[58:61], v[158:161], v[166:169], v[58:61]
	v_mfma_f32_16x16x32_bf16 v[54:57], v[150:153], v[174:177], v[54:57]
	v_mfma_f32_16x16x32_bf16 v[50:53], v[158:161], v[174:177], v[50:53]
	v_mfma_f32_16x16x32_bf16 v[46:49], v[150:153], v[186:189], v[46:49]
	v_mfma_f32_16x16x32_bf16 v[42:45], v[158:161], v[186:189], v[42:45]
	v_mfma_f32_16x16x32_bf16 v[38:41], v[150:153], v[194:197], v[38:41]
	v_mfma_f32_16x16x32_bf16 v[34:37], v[158:161], v[194:197], v[34:37]
	s_barrier
	s_setprio 0
	s_add_u32 s98, s44, 0x80
	s_addc_u32 s99, s45, 0
	s_add_i32 m0, s46, 0x1c000
	s_nop 0
	global_load_lds_dwordx4 v0, s[98:99]
	s_add_i32 m0, s46, 0x1e000
	s_nop 0
	global_load_lds_dwordx4 v130, s[98:99]
	s_waitcnt vmcnt(6)
	s_setprio 1
	s_barrier
	v_mfma_f32_16x16x32_bf16 v[30:33], v[220:223], v[162:165], v[30:33]
	v_mfma_f32_16x16x32_bf16 v[26:29], v[228:231], v[162:165], v[26:29]
	v_mfma_f32_16x16x32_bf16 v[22:25], v[220:223], v[170:173], v[22:25]
	v_mfma_f32_16x16x32_bf16 v[18:21], v[228:231], v[170:173], v[18:21]
	v_mfma_f32_16x16x32_bf16 v[14:17], v[220:223], v[182:185], v[14:17]
	v_mfma_f32_16x16x32_bf16 v[10:13], v[228:231], v[182:185], v[10:13]
	v_mfma_f32_16x16x32_bf16 v[6:9], v[220:223], v[190:193], v[6:9]
	v_mfma_f32_16x16x32_bf16 v[2:5], v[228:231], v[190:193], v[2:5]
	v_mfma_f32_16x16x32_bf16 v[30:33], v[224:227], v[166:169], v[30:33]
	v_mfma_f32_16x16x32_bf16 v[26:29], v[232:235], v[166:169], v[26:29]
	v_mfma_f32_16x16x32_bf16 v[22:25], v[224:227], v[174:177], v[22:25]
	v_mfma_f32_16x16x32_bf16 v[18:21], v[232:235], v[174:177], v[18:21]
	v_mfma_f32_16x16x32_bf16 v[14:17], v[224:227], v[186:189], v[14:17]
	v_mfma_f32_16x16x32_bf16 v[10:13], v[232:235], v[186:189], v[10:13]
	v_mfma_f32_16x16x32_bf16 v[6:9], v[224:227], v[194:197], v[6:9]
	v_mfma_f32_16x16x32_bf16 v[2:5], v[232:235], v[194:197], v[2:5]
	s_barrier
	s_setprio 0
	s_add_u32 s4, s4, 0x100
	s_addc_u32 s5, s5, 0
	s_add_u32 s100, s100, 0x100
	s_addc_u32 s101, s101, 0
	s_cmp_ge_u32 s23, s16
	s_mov_b32 s22, s23
	s_cbranch_scc0 .LBB0_332
	v_lshl_add_u32 v145, s57, 10, v142
	ds_read_b32 v136, v145
	v_lshl_or_b32 v138, s8, 7, v143
	v_lshl_add_u32 v146, s9, 8, v140
	v_ashrrev_i32_e32 v139, 31, v138
	v_lshlrev_b64 v[138:139], 1, v[138:139]
	s_waitcnt lgkmcnt(0)
	v_pk_mul_f32 v[148:149], v[126:127], v[136:137] op_sel_hi:[1,0]
	v_pk_mul_f32 v[154:155], v[94:95], v[136:137] op_sel_hi:[1,0]
	v_mul_f32_e32 v147, 0xbfb8aa3b, v148
	v_exp_f32_e32 v147, v147
	v_pk_mul_f32 v[150:151], v[128:129], v[136:137] op_sel_hi:[1,0]
	v_pk_mul_f32 v[152:153], v[96:97], v[136:137] op_sel_hi:[1,0]
	v_pk_mul_f32 v[158:159], v[122:123], v[136:137] op_sel_hi:[1,0]
	v_add_f32_e32 v147, 1.0, v147
	v_rcp_f32_e32 v147, v147
	v_pk_mul_f32 v[156:157], v[124:125], v[136:137] op_sel_hi:[1,0]
	v_pk_mul_f32 v[160:161], v[92:93], v[136:137] op_sel_hi:[1,0]
	v_pk_mul_f32 v[136:137], v[90:91], v[136:137] op_sel_hi:[1,0]
	v_mul_f32_e32 v147, v148, v147
	v_mul_f32_e32 v148, 0xbfb8aa3b, v149
	v_exp_f32_e32 v148, v148
	v_mul_f32_e32 v147, v154, v147
	s_and_b64 vcc, exec, s[42:43]
	v_add_f32_e32 v148, 1.0, v148
	v_rcp_f32_e32 v148, v148
	s_nop 0
	v_mul_f32_e32 v148, v149, v148
	v_mul_f32_e32 v148, v155, v148
	v_cvt_pk_bf16_f32 v148, v147, v148
	v_mul_f32_e32 v147, 0xbfb8aa3b, v150
	v_mul_f32_e32 v149, 0xbfb8aa3b, v151
	v_exp_f32_e32 v147, v147
	v_exp_f32_e32 v149, v149
	v_add_f32_e32 v147, 1.0, v147
	v_add_f32_e32 v149, 1.0, v149
	v_rcp_f32_e32 v147, v147
	v_rcp_f32_e32 v149, v149
	v_mul_f32_e32 v147, v150, v147
	v_mul_f32_e32 v149, v151, v149
	v_mul_f32_e32 v147, v152, v147
	v_mul_f32_e32 v149, v153, v149
	v_cvt_pk_bf16_f32 v149, v147, v149
	v_mul_f32_e32 v147, 0xbfb8aa3b, v158
	v_exp_f32_e32 v147, v147
	s_nop 0
	v_add_f32_e32 v147, 1.0, v147
	v_rcp_f32_e32 v147, v147
	s_nop 0
	v_mul_f32_e32 v147, v158, v147
	v_mul_f32_e32 v136, v136, v147
	v_mul_f32_e32 v147, 0xbfb8aa3b, v159
	v_exp_f32_e32 v147, v147
	s_nop 0
	v_add_f32_e32 v147, 1.0, v147
	v_rcp_f32_e32 v147, v147
	s_nop 0
	v_mul_f32_e32 v147, v159, v147
	v_mul_f32_e32 v137, v137, v147
	v_cvt_pk_bf16_f32 v150, v136, v137
	v_mul_f32_e32 v136, 0xbfb8aa3b, v156
	v_mul_f32_e32 v137, 0xbfb8aa3b, v157
	v_exp_f32_e32 v136, v136
	v_exp_f32_e32 v137, v137
	v_or_b32_e32 v147, 16, v146
	v_add_f32_e32 v136, 1.0, v136
	v_add_f32_e32 v137, 1.0, v137
	v_rcp_f32_e32 v136, v136
	v_rcp_f32_e32 v137, v137
	v_mul_f32_e32 v136, v156, v136
	v_mul_f32_e32 v137, v157, v137
	v_mul_f32_e32 v136, v160, v136
	v_mul_f32_e32 v137, v161, v137
	v_cvt_pk_bf16_f32 v151, v136, v137
	v_mov_b64_e32 v[136:137], s[6:7]
	v_mad_i64_i32 v[152:153], s[4:5], v146, s33, v[136:137]
	v_lshl_add_u64 v[152:153], v[152:153], 0, v[138:139]
	global_store_dwordx4 v[152:153], v[148:151], off
	ds_read_b32 v148, v145 offset:64
	s_waitcnt lgkmcnt(0)
; __device__ __forceinline__ unsigned pk2(float lo, float hi) { unsigned r; asm volatile("v_cvt_pk_bf16_f32 %0, %1, %2" : "=v"(r) : "v"(lo), "v"(hi)); return r; }
; __device__ __forceinline__ float siluf_(float x) { return x * __builtin_amdgcn_rcpf(1.0f + __expf(-x)); }
;     template <int mode> __device__ __forceinline__ void run(const f32x4 (&acc)[2][2][4][2], const Unit& u, int wr, int wc, int fr, int fq, const LAS float* sc) const {
;     ...
; #pragma unroll
;             for (int ai = 0; ai < 2; ++ai)
; #pragma unroll
;                 for (int m = 0; m < 4; ++m) {
;                     const int row = row0 + ai * HALF + m * 16;
;                     const float s = sc[ai * HALF + wr * 64 + m * 16 + fr];
;                     const f32x4 g0 = acc[ai][0][m][0] * s, u0 = acc[ai][1][m][0] * s, g1 = acc[ai][0][m][1] * s, u1 = acc[ai][1][m][1] * s;
;                     u32x4 w;
;                     w.x = pk2(siluf_(g0[0]) * u0[0], siluf_(g0[1]) * u0[1]); w.y = pk2(siluf_(g0[2]) * u0[2], siluf_(g0[3]) * u0[3]);
;                     w.z = pk2(siluf_(g1[0]) * u1[0], siluf_(g1[1]) * u1[1]); w.w = pk2(siluf_(g1[2]) * u1[2], siluf_(g1[3]) * u1[3]);
;                     *(u32x4*)(ob + (size_t)row * FF + col0) = w;
;                 }
	v_pk_mul_f32 v[152:153], v[118:119], v[148:149] op_sel_hi:[1,0]
	v_pk_mul_f32 v[150:151], v[120:121], v[148:149] op_sel_hi:[1,0]
	v_pk_mul_f32 v[154:155], v[88:89], v[148:149] op_sel_hi:[1,0]
	v_pk_mul_f32 v[156:157], v[86:87], v[148:149] op_sel_hi:[1,0]
	v_pk_mul_f32 v[158:159], v[116:117], v[148:149] op_sel_hi:[1,0]
	v_pk_mul_f32 v[160:161], v[114:115], v[148:149] op_sel_hi:[1,0]
	v_pk_mul_f32 v[162:163], v[84:85], v[148:149] op_sel_hi:[1,0]
	v_pk_mul_f32 v[164:165], v[82:83], v[148:149] op_sel_hi:[1,0]
	v_mul_f32_e32 v148, 0xbfb8aa3b, v152
	v_mul_f32_e32 v149, 0xbfb8aa3b, v153
	v_exp_f32_e32 v148, v148
	v_exp_f32_e32 v149, v149
	v_add_f32_e32 v148, 1.0, v148
	v_add_f32_e32 v149, 1.0, v149
	v_rcp_f32_e32 v148, v148
	v_rcp_f32_e32 v149, v149
	v_mul_f32_e32 v148, v152, v148
	v_mul_f32_e32 v149, v153, v149
	v_mul_f32_e32 v148, v156, v148
	v_mul_f32_e32 v149, v157, v149
	v_cvt_pk_bf16_f32 v148, v148, v149
	v_mul_f32_e32 v149, 0xbfb8aa3b, v150
	v_exp_f32_e32 v149, v149
	v_mul_f32_e32 v152, 0xbfb8aa3b, v159
	v_exp_f32_e32 v152, v152
	v_add_f32_e32 v149, 1.0, v149
	v_rcp_f32_e32 v149, v149
	v_add_f32_e32 v152, 1.0, v152
	v_rcp_f32_e32 v152, v152
	v_mul_f32_e32 v149, v150, v149
	v_mul_f32_e32 v150, 0xbfb8aa3b, v151
	v_exp_f32_e32 v150, v150
	v_mul_f32_e32 v149, v154, v149
	v_mul_f32_e32 v152, v159, v152
	v_mul_f32_e32 v152, v163, v152
	v_add_f32_e32 v150, 1.0, v150
	v_rcp_f32_e32 v150, v150
	s_nop 0
	v_mul_f32_e32 v150, v151, v150
	v_mul_f32_e32 v150, v155, v150
	v_cvt_pk_bf16_f32 v149, v149, v150
	v_mul_f32_e32 v150, 0xbfb8aa3b, v160
	v_mul_f32_e32 v151, 0xbfb8aa3b, v161
	v_exp_f32_e32 v150, v150
	v_exp_f32_e32 v151, v151
	v_add_f32_e32 v150, 1.0, v150
	v_add_f32_e32 v151, 1.0, v151
	v_rcp_f32_e32 v150, v150
	v_rcp_f32_e32 v151, v151
	v_mul_f32_e32 v150, v160, v150
	v_mul_f32_e32 v151, v161, v151
	v_mul_f32_e32 v150, v164, v150
	v_mul_f32_e32 v151, v165, v151
	v_cvt_pk_bf16_f32 v150, v150, v151
	v_mul_f32_e32 v151, 0xbfb8aa3b, v158
	v_exp_f32_e32 v151, v151
	s_nop 0
	v_add_f32_e32 v151, 1.0, v151
	v_rcp_f32_e32 v151, v151
	s_nop 0
	v_mul_f32_e32 v151, v158, v151
	v_mul_f32_e32 v151, v162, v151
	v_cvt_pk_bf16_f32 v151, v151, v152
	v_mad_i64_i32 v[152:153], s[4:5], v147, s33, v[136:137]
	v_lshl_add_u64 v[152:153], v[152:153], 0, v[138:139]
	global_store_dwordx4 v[152:153], v[148:151], off
	ds_read_b32 v148, v145 offset:128
	v_or_b32_e32 v147, 32, v146
	s_waitcnt lgkmcnt(0)
	v_pk_mul_f32 v[152:153], v[110:111], v[148:149] op_sel_hi:[1,0]
	v_pk_mul_f32 v[150:151], v[112:113], v[148:149] op_sel_hi:[1,0]
	v_pk_mul_f32 v[154:155], v[80:81], v[148:149] op_sel_hi:[1,0]
	v_pk_mul_f32 v[156:157], v[78:79], v[148:149] op_sel_hi:[1,0]
	v_pk_mul_f32 v[158:159], v[108:109], v[148:149] op_sel_hi:[1,0]
	v_pk_mul_f32 v[160:161], v[106:107], v[148:149] op_sel_hi:[1,0]
	v_pk_mul_f32 v[162:163], v[76:77], v[148:149] op_sel_hi:[1,0]
	v_pk_mul_f32 v[164:165], v[74:75], v[148:149] op_sel_hi:[1,0]
	v_mul_f32_e32 v148, 0xbfb8aa3b, v152
	v_mul_f32_e32 v149, 0xbfb8aa3b, v153
	v_exp_f32_e32 v148, v148
	v_exp_f32_e32 v149, v149
	v_add_f32_e32 v148, 1.0, v148
	v_add_f32_e32 v149, 1.0, v149
	v_rcp_f32_e32 v148, v148
	v_rcp_f32_e32 v149, v149
	v_mul_f32_e32 v148, v152, v148
	v_mul_f32_e32 v149, v153, v149
	v_mul_f32_e32 v148, v156, v148
	v_mul_f32_e32 v149, v157, v149
	v_cvt_pk_bf16_f32 v148, v148, v149
	v_mul_f32_e32 v149, 0xbfb8aa3b, v150
	v_exp_f32_e32 v149, v149
	v_mul_f32_e32 v152, 0xbfb8aa3b, v159
	v_exp_f32_e32 v152, v152
	v_add_f32_e32 v149, 1.0, v149
	v_rcp_f32_e32 v149, v149
	v_add_f32_e32 v152, 1.0, v152
	v_rcp_f32_e32 v152, v152
	v_mul_f32_e32 v149, v150, v149
	v_mul_f32_e32 v150, 0xbfb8aa3b, v151
	v_exp_f32_e32 v150, v150
	v_mul_f32_e32 v149, v154, v149
	v_mul_f32_e32 v152, v159, v152
	v_mul_f32_e32 v152, v163, v152
	v_add_f32_e32 v150, 1.0, v150
	v_rcp_f32_e32 v150, v150
	s_nop 0
	v_mul_f32_e32 v150, v151, v150
	v_mul_f32_e32 v150, v155, v150
	v_cvt_pk_bf16_f32 v149, v149, v150
	v_mul_f32_e32 v150, 0xbfb8aa3b, v160
	v_mul_f32_e32 v151, 0xbfb8aa3b, v161
	v_exp_f32_e32 v150, v150
	v_exp_f32_e32 v151, v151
	v_add_f32_e32 v150, 1.0, v150
	v_add_f32_e32 v151, 1.0, v151
	v_rcp_f32_e32 v150, v150
	v_rcp_f32_e32 v151, v151
	v_mul_f32_e32 v150, v160, v150
	v_mul_f32_e32 v151, v161, v151
	v_mul_f32_e32 v150, v164, v150
	v_mul_f32_e32 v151, v165, v151
	v_cvt_pk_bf16_f32 v150, v150, v151
	v_mul_f32_e32 v151, 0xbfb8aa3b, v158
	v_exp_f32_e32 v151, v151
	s_nop 0
	v_add_f32_e32 v151, 1.0, v151
	v_rcp_f32_e32 v151, v151
	s_nop 0
	v_mul_f32_e32 v151, v158, v151
	v_mul_f32_e32 v151, v162, v151
	v_cvt_pk_bf16_f32 v151, v151, v152
	v_mad_i64_i32 v[152:153], s[4:5], v147, s33, v[136:137]
	v_lshl_add_u64 v[152:153], v[152:153], 0, v[138:139]
	global_store_dwordx4 v[152:153], v[148:151], off
	ds_read_b32 v148, v145 offset:192
	v_or_b32_e32 v147, 48, v146
	s_waitcnt lgkmcnt(0)
; __device__ __forceinline__ unsigned pk2(float lo, float hi) { unsigned r; asm volatile("v_cvt_pk_bf16_f32 %0, %1, %2" : "=v"(r) : "v"(lo), "v"(hi)); return r; }
; __device__ __forceinline__ float siluf_(float x) { return x * __builtin_amdgcn_rcpf(1.0f + __expf(-x)); }
;     template <int mode> __device__ __forceinline__ void run(const f32x4 (&acc)[2][2][4][2], const Unit& u, int wr, int wc, int fr, int fq, const LAS float* sc) const {
;     ...
; #pragma unroll
;             for (int ai = 0; ai < 2; ++ai)
; #pragma unroll
;                 for (int m = 0; m < 4; ++m) {
;                     const int row = row0 + ai * HALF + m * 16;
;                     const float s = sc[ai * HALF + wr * 64 + m * 16 + fr];
;                     const f32x4 g0 = acc[ai][0][m][0] * s, u0 = acc[ai][1][m][0] * s, g1 = acc[ai][0][m][1] * s, u1 = acc[ai][1][m][1] * s;
;                     u32x4 w;
;                     w.x = pk2(siluf_(g0[0]) * u0[0], siluf_(g0[1]) * u0[1]); w.y = pk2(siluf_(g0[2]) * u0[2], siluf_(g0[3]) * u0[3]);
;                     w.z = pk2(siluf_(g1[0]) * u1[0], siluf_(g1[1]) * u1[1]); w.w = pk2(siluf_(g1[2]) * u1[2], siluf_(g1[3]) * u1[3]);
;                     *(u32x4*)(ob + (size_t)row * FF + col0) = w;
;                 }
	v_pk_mul_f32 v[152:153], v[102:103], v[148:149] op_sel_hi:[1,0]
	v_pk_mul_f32 v[150:151], v[104:105], v[148:149] op_sel_hi:[1,0]
	v_pk_mul_f32 v[154:155], v[72:73], v[148:149] op_sel_hi:[1,0]
	v_pk_mul_f32 v[156:157], v[70:71], v[148:149] op_sel_hi:[1,0]
	v_pk_mul_f32 v[158:159], v[100:101], v[148:149] op_sel_hi:[1,0]
	v_pk_mul_f32 v[160:161], v[98:99], v[148:149] op_sel_hi:[1,0]
	v_pk_mul_f32 v[162:163], v[68:69], v[148:149] op_sel_hi:[1,0]
	v_pk_mul_f32 v[164:165], v[66:67], v[148:149] op_sel_hi:[1,0]
	v_mul_f32_e32 v148, 0xbfb8aa3b, v152
	v_mul_f32_e32 v149, 0xbfb8aa3b, v153
	v_exp_f32_e32 v148, v148
	v_exp_f32_e32 v149, v149
	v_add_f32_e32 v148, 1.0, v148
	v_add_f32_e32 v149, 1.0, v149
	v_rcp_f32_e32 v148, v148
	v_rcp_f32_e32 v149, v149
	v_mul_f32_e32 v148, v152, v148
	v_mul_f32_e32 v149, v153, v149
	v_mul_f32_e32 v148, v156, v148
	v_mul_f32_e32 v149, v157, v149
	v_cvt_pk_bf16_f32 v148, v148, v149
	v_mul_f32_e32 v149, 0xbfb8aa3b, v150
	v_exp_f32_e32 v149, v149
	v_mul_f32_e32 v152, 0xbfb8aa3b, v159
	v_exp_f32_e32 v152, v152
	v_add_f32_e32 v149, 1.0, v149
	v_rcp_f32_e32 v149, v149
	v_add_f32_e32 v152, 1.0, v152
	v_rcp_f32_e32 v152, v152
	v_mul_f32_e32 v149, v150, v149
	v_mul_f32_e32 v150, 0xbfb8aa3b, v151
	v_exp_f32_e32 v150, v150
	v_mul_f32_e32 v149, v154, v149
	v_mul_f32_e32 v152, v159, v152
	v_mul_f32_e32 v152, v163, v152
	v_add_f32_e32 v150, 1.0, v150
	v_rcp_f32_e32 v150, v150
	s_nop 0
	v_mul_f32_e32 v150, v151, v150
	v_mul_f32_e32 v150, v155, v150
	v_cvt_pk_bf16_f32 v149, v149, v150
	v_mul_f32_e32 v150, 0xbfb8aa3b, v160
	v_mul_f32_e32 v151, 0xbfb8aa3b, v161
	v_exp_f32_e32 v150, v150
	v_exp_f32_e32 v151, v151
	v_add_f32_e32 v150, 1.0, v150
	v_add_f32_e32 v151, 1.0, v151
	v_rcp_f32_e32 v150, v150
	v_rcp_f32_e32 v151, v151
	v_mul_f32_e32 v150, v160, v150
	v_mul_f32_e32 v151, v161, v151
	v_mul_f32_e32 v150, v164, v150
	v_mul_f32_e32 v151, v165, v151
	v_cvt_pk_bf16_f32 v150, v150, v151
	v_mul_f32_e32 v151, 0xbfb8aa3b, v158
	v_exp_f32_e32 v151, v151
	s_nop 0
	v_add_f32_e32 v151, 1.0, v151
	v_rcp_f32_e32 v151, v151
	s_nop 0
	v_mul_f32_e32 v151, v158, v151
	v_mul_f32_e32 v151, v162, v151
	v_cvt_pk_bf16_f32 v151, v151, v152
	v_mad_i64_i32 v[152:153], s[4:5], v147, s33, v[136:137]
	v_lshl_add_u64 v[152:153], v[152:153], 0, v[138:139]
	global_store_dwordx4 v[152:153], v[148:151], off
	ds_read_b32 v148, v145 offset:512
	v_add_u32_e32 v147, 0x80, v146
	s_waitcnt lgkmcnt(0)
	v_pk_mul_f32 v[152:153], v[62:63], v[148:149] op_sel_hi:[1,0]
	v_pk_mul_f32 v[150:151], v[64:65], v[148:149] op_sel_hi:[1,0]
	v_pk_mul_f32 v[154:155], v[32:33], v[148:149] op_sel_hi:[1,0]
	v_pk_mul_f32 v[156:157], v[30:31], v[148:149] op_sel_hi:[1,0]
	v_pk_mul_f32 v[158:159], v[60:61], v[148:149] op_sel_hi:[1,0]
	v_pk_mul_f32 v[160:161], v[58:59], v[148:149] op_sel_hi:[1,0]
	v_pk_mul_f32 v[162:163], v[28:29], v[148:149] op_sel_hi:[1,0]
	v_pk_mul_f32 v[164:165], v[26:27], v[148:149] op_sel_hi:[1,0]
	v_mul_f32_e32 v148, 0xbfb8aa3b, v152
	v_mul_f32_e32 v149, 0xbfb8aa3b, v153
	v_exp_f32_e32 v148, v148
	v_exp_f32_e32 v149, v149
	v_add_f32_e32 v148, 1.0, v148
	v_add_f32_e32 v149, 1.0, v149
	v_rcp_f32_e32 v148, v148
	v_rcp_f32_e32 v149, v149
	v_mul_f32_e32 v148, v152, v148
	v_mul_f32_e32 v149, v153, v149
	v_mul_f32_e32 v148, v156, v148
	v_mul_f32_e32 v149, v157, v149
	v_cvt_pk_bf16_f32 v148, v148, v149
	v_mul_f32_e32 v149, 0xbfb8aa3b, v150
	v_exp_f32_e32 v149, v149
	v_mul_f32_e32 v152, 0xbfb8aa3b, v159
	v_exp_f32_e32 v152, v152
	v_add_f32_e32 v149, 1.0, v149
	v_rcp_f32_e32 v149, v149
	v_add_f32_e32 v152, 1.0, v152
	v_rcp_f32_e32 v152, v152
	v_mul_f32_e32 v149, v150, v149
	v_mul_f32_e32 v150, 0xbfb8aa3b, v151
	v_exp_f32_e32 v150, v150
	v_mul_f32_e32 v149, v154, v149
	v_mul_f32_e32 v152, v159, v152
	v_mul_f32_e32 v152, v163, v152
	v_add_f32_e32 v150, 1.0, v150
	v_rcp_f32_e32 v150, v150
	s_nop 0
	v_mul_f32_e32 v150, v151, v150
	v_mul_f32_e32 v150, v155, v150
	v_cvt_pk_bf16_f32 v149, v149, v150
	v_mul_f32_e32 v150, 0xbfb8aa3b, v160
	v_mul_f32_e32 v151, 0xbfb8aa3b, v161
	v_exp_f32_e32 v150, v150
	v_exp_f32_e32 v151, v151
	v_add_f32_e32 v150, 1.0, v150
	v_add_f32_e32 v151, 1.0, v151
	v_rcp_f32_e32 v150, v150
	v_rcp_f32_e32 v151, v151
	v_mul_f32_e32 v150, v160, v150
	v_mul_f32_e32 v151, v161, v151
	v_mul_f32_e32 v150, v164, v150
	v_mul_f32_e32 v151, v165, v151
	v_cvt_pk_bf16_f32 v150, v150, v151
	v_mul_f32_e32 v151, 0xbfb8aa3b, v158
	v_exp_f32_e32 v151, v151
	s_nop 0
	v_add_f32_e32 v151, 1.0, v151
	v_rcp_f32_e32 v151, v151
	s_nop 0
	v_mul_f32_e32 v151, v158, v151
	v_mul_f32_e32 v151, v162, v151
	v_cvt_pk_bf16_f32 v151, v151, v152
	v_mad_i64_i32 v[152:153], s[4:5], v147, s33, v[136:137]
	v_lshl_add_u64 v[152:153], v[152:153], 0, v[138:139]
	global_store_dwordx4 v[152:153], v[148:151], off
	ds_read_b32 v148, v145 offset:576
	v_add_u32_e32 v147, 0x90, v146
	s_waitcnt lgkmcnt(0)
; __device__ __forceinline__ unsigned pk2(float lo, float hi) { unsigned r; asm volatile("v_cvt_pk_bf16_f32 %0, %1, %2" : "=v"(r) : "v"(lo), "v"(hi)); return r; }
; __device__ __forceinline__ float siluf_(float x) { return x * __builtin_amdgcn_rcpf(1.0f + __expf(-x)); }
;     template <int mode> __device__ __forceinline__ void run(const f32x4 (&acc)[2][2][4][2], const Unit& u, int wr, int wc, int fr, int fq, const LAS float* sc) const {
;     ...
; #pragma unroll
;             for (int ai = 0; ai < 2; ++ai)
; #pragma unroll
;                 for (int m = 0; m < 4; ++m) {
;                     const int row = row0 + ai * HALF + m * 16;
;                     const float s = sc[ai * HALF + wr * 64 + m * 16 + fr];
;                     const f32x4 g0 = acc[ai][0][m][0] * s, u0 = acc[ai][1][m][0] * s, g1 = acc[ai][0][m][1] * s, u1 = acc[ai][1][m][1] * s;
;                     u32x4 w;
;                     w.x = pk2(siluf_(g0[0]) * u0[0], siluf_(g0[1]) * u0[1]); w.y = pk2(siluf_(g0[2]) * u0[2], siluf_(g0[3]) * u0[3]);
;                     w.z = pk2(siluf_(g1[0]) * u1[0], siluf_(g1[1]) * u1[1]); w.w = pk2(siluf_(g1[2]) * u1[2], siluf_(g1[3]) * u1[3]);
;                     *(u32x4*)(ob + (size_t)row * FF + col0) = w;
;                 }
	v_pk_mul_f32 v[152:153], v[54:55], v[148:149] op_sel_hi:[1,0]
	v_pk_mul_f32 v[150:151], v[56:57], v[148:149] op_sel_hi:[1,0]
	v_pk_mul_f32 v[154:155], v[24:25], v[148:149] op_sel_hi:[1,0]
	v_pk_mul_f32 v[156:157], v[22:23], v[148:149] op_sel_hi:[1,0]
	v_pk_mul_f32 v[158:159], v[52:53], v[148:149] op_sel_hi:[1,0]
	v_pk_mul_f32 v[160:161], v[50:51], v[148:149] op_sel_hi:[1,0]
	v_pk_mul_f32 v[162:163], v[20:21], v[148:149] op_sel_hi:[1,0]
	v_pk_mul_f32 v[164:165], v[18:19], v[148:149] op_sel_hi:[1,0]
	v_mul_f32_e32 v148, 0xbfb8aa3b, v152
	v_mul_f32_e32 v149, 0xbfb8aa3b, v153
	v_exp_f32_e32 v148, v148
	v_exp_f32_e32 v149, v149
	v_add_f32_e32 v148, 1.0, v148
	v_add_f32_e32 v149, 1.0, v149
	v_rcp_f32_e32 v148, v148
	v_rcp_f32_e32 v149, v149
	v_mul_f32_e32 v148, v152, v148
	v_mul_f32_e32 v149, v153, v149
	v_mul_f32_e32 v148, v156, v148
	v_mul_f32_e32 v149, v157, v149
	v_cvt_pk_bf16_f32 v148, v148, v149
	v_mul_f32_e32 v149, 0xbfb8aa3b, v150
	v_exp_f32_e32 v149, v149
	v_mul_f32_e32 v152, 0xbfb8aa3b, v159
	v_exp_f32_e32 v152, v152
	v_add_f32_e32 v149, 1.0, v149
	v_rcp_f32_e32 v149, v149
	v_add_f32_e32 v152, 1.0, v152
	v_rcp_f32_e32 v152, v152
	v_mul_f32_e32 v149, v150, v149
	v_mul_f32_e32 v150, 0xbfb8aa3b, v151
	v_exp_f32_e32 v150, v150
	v_mul_f32_e32 v149, v154, v149
	v_mul_f32_e32 v152, v159, v152
	v_mul_f32_e32 v152, v163, v152
	v_add_f32_e32 v150, 1.0, v150
	v_rcp_f32_e32 v150, v150
	s_nop 0
	v_mul_f32_e32 v150, v151, v150
	v_mul_f32_e32 v150, v155, v150
	v_cvt_pk_bf16_f32 v149, v149, v150
	v_mul_f32_e32 v150, 0xbfb8aa3b, v160
	v_mul_f32_e32 v151, 0xbfb8aa3b, v161
	v_exp_f32_e32 v150, v150
	v_exp_f32_e32 v151, v151
	v_add_f32_e32 v150, 1.0, v150
	v_add_f32_e32 v151, 1.0, v151
	v_rcp_f32_e32 v150, v150
	v_rcp_f32_e32 v151, v151
	v_mul_f32_e32 v150, v160, v150
	v_mul_f32_e32 v151, v161, v151
	v_mul_f32_e32 v150, v164, v150
	v_mul_f32_e32 v151, v165, v151
	v_cvt_pk_bf16_f32 v150, v150, v151
	v_mul_f32_e32 v151, 0xbfb8aa3b, v158
	v_exp_f32_e32 v151, v151
	s_nop 0
	v_add_f32_e32 v151, 1.0, v151
	v_rcp_f32_e32 v151, v151
	s_nop 0
	v_mul_f32_e32 v151, v158, v151
	v_mul_f32_e32 v151, v162, v151
	v_cvt_pk_bf16_f32 v151, v151, v152
	v_mad_i64_i32 v[152:153], s[4:5], v147, s33, v[136:137]
	v_lshl_add_u64 v[152:153], v[152:153], 0, v[138:139]
	global_store_dwordx4 v[152:153], v[148:151], off
	ds_read_b32 v148, v145 offset:640
	v_add_u32_e32 v147, 0xa0, v146
	s_waitcnt lgkmcnt(0)
	v_pk_mul_f32 v[152:153], v[46:47], v[148:149] op_sel_hi:[1,0]
	v_pk_mul_f32 v[150:151], v[48:49], v[148:149] op_sel_hi:[1,0]
	v_pk_mul_f32 v[154:155], v[16:17], v[148:149] op_sel_hi:[1,0]
	v_pk_mul_f32 v[156:157], v[14:15], v[148:149] op_sel_hi:[1,0]
	v_pk_mul_f32 v[158:159], v[44:45], v[148:149] op_sel_hi:[1,0]
	v_pk_mul_f32 v[160:161], v[42:43], v[148:149] op_sel_hi:[1,0]
	v_pk_mul_f32 v[162:163], v[12:13], v[148:149] op_sel_hi:[1,0]
	v_pk_mul_f32 v[164:165], v[10:11], v[148:149] op_sel_hi:[1,0]
	v_mul_f32_e32 v148, 0xbfb8aa3b, v152
	v_mul_f32_e32 v149, 0xbfb8aa3b, v153
	v_exp_f32_e32 v148, v148
	v_exp_f32_e32 v149, v149
	v_add_f32_e32 v148, 1.0, v148
	v_add_f32_e32 v149, 1.0, v149
	v_rcp_f32_e32 v148, v148
	v_rcp_f32_e32 v149, v149
	v_mul_f32_e32 v148, v152, v148
	v_mul_f32_e32 v149, v153, v149
	v_mul_f32_e32 v148, v156, v148
	v_mul_f32_e32 v149, v157, v149
	v_cvt_pk_bf16_f32 v148, v148, v149
	v_mul_f32_e32 v149, 0xbfb8aa3b, v150
	v_exp_f32_e32 v149, v149
	v_mul_f32_e32 v152, 0xbfb8aa3b, v159
	v_exp_f32_e32 v152, v152
	v_add_f32_e32 v149, 1.0, v149
	v_rcp_f32_e32 v149, v149
	v_add_f32_e32 v152, 1.0, v152
	v_rcp_f32_e32 v152, v152
	v_mul_f32_e32 v149, v150, v149
	v_mul_f32_e32 v150, 0xbfb8aa3b, v151
	v_exp_f32_e32 v150, v150
	v_mul_f32_e32 v149, v154, v149
	v_mul_f32_e32 v152, v159, v152
	v_mul_f32_e32 v152, v163, v152
	v_add_f32_e32 v150, 1.0, v150
	v_rcp_f32_e32 v150, v150
	s_nop 0
	v_mul_f32_e32 v150, v151, v150
	v_mul_f32_e32 v150, v155, v150
	v_cvt_pk_bf16_f32 v149, v149, v150
	v_mul_f32_e32 v150, 0xbfb8aa3b, v160
	v_mul_f32_e32 v151, 0xbfb8aa3b, v161
	v_exp_f32_e32 v150, v150
	v_exp_f32_e32 v151, v151
	v_add_f32_e32 v150, 1.0, v150
	v_add_f32_e32 v151, 1.0, v151
	v_rcp_f32_e32 v150, v150
	v_rcp_f32_e32 v151, v151
	v_mul_f32_e32 v150, v160, v150
	v_mul_f32_e32 v151, v161, v151
	v_mul_f32_e32 v150, v164, v150
	v_mul_f32_e32 v151, v165, v151
	v_cvt_pk_bf16_f32 v150, v150, v151
	v_mul_f32_e32 v151, 0xbfb8aa3b, v158
	v_exp_f32_e32 v151, v151
	v_add_u32_e32 v164, 0xb0, v146
	v_add_f32_e32 v151, 1.0, v151
	v_rcp_f32_e32 v151, v151
	s_nop 0
	v_mul_f32_e32 v151, v158, v151
	v_mul_f32_e32 v151, v162, v151
	v_cvt_pk_bf16_f32 v151, v151, v152
	ds_read_b32 v146, v145 offset:704
	v_mad_i64_i32 v[152:153], s[4:5], v147, s33, v[136:137]
	v_lshl_add_u64 v[152:153], v[152:153], 0, v[138:139]
	global_store_dwordx4 v[152:153], v[148:151], off
	s_waitcnt lgkmcnt(0)
; __device__ __forceinline__ unsigned pk2(float lo, float hi) { unsigned r; asm volatile("v_cvt_pk_bf16_f32 %0, %1, %2" : "=v"(r) : "v"(lo), "v"(hi)); return r; }
; __device__ __forceinline__ float siluf_(float x) { return x * __builtin_amdgcn_rcpf(1.0f + __expf(-x)); }
;     template <int mode> __device__ __forceinline__ void run(const f32x4 (&acc)[2][2][4][2], const Unit& u, int wr, int wc, int fr, int fq, const LAS float* sc) const {
;     ...
;                     const int row = row0 + ai * HALF + m * 16;
;                     const float s = sc[ai * HALF + wr * 64 + m * 16 + fr];
;                     const f32x4 g0 = acc[ai][0][m][0] * s, u0 = acc[ai][1][m][0] * s, g1 = acc[ai][0][m][1] * s, u1 = acc[ai][1][m][1] * s;
;                     u32x4 w;
;                     w.x = pk2(siluf_(g0[0]) * u0[0], siluf_(g0[1]) * u0[1]); w.y = pk2(siluf_(g0[2]) * u0[2], siluf_(g0[3]) * u0[3]);
;                     w.z = pk2(siluf_(g1[0]) * u1[0], siluf_(g1[1]) * u1[1]); w.w = pk2(siluf_(g1[2]) * u1[2], siluf_(g1[3]) * u1[3]);
;                     *(u32x4*)(ob + (size_t)row * FF + col0) = w;
; template <int MODE, class EpiT, class Sched>
; __device__ __forceinline__ void gemm_phase(LAS unsigned char* lds, const Gemm g, const Sched& S, const EpiT& E) {
;     ...
; #pragma unroll
;         for (int a = 0; a < 2; ++a)
; #pragma unroll
;             for (int b = 0; b < 2; ++b)
; #pragma unroll
;                 for (int m = 0; m < 4; ++m)
; #pragma unroll
;                     for (int n = 0; n < 2; ++n) acc[a][b][m][n] = (f32x4){0.f, 0.f, 0.f, 0.f};
;         cur = nxt; cA = nA; cB = nB; ++ui;
	v_pk_mul_f32 v[152:153], v[8:9], v[146:147] op_sel_hi:[1,0]
	v_pk_mul_f32 v[154:155], v[6:7], v[146:147] op_sel_hi:[1,0]
	v_pk_mul_f32 v[150:151], v[38:39], v[146:147] op_sel_hi:[1,0]
	v_pk_mul_f32 v[148:149], v[40:41], v[146:147] op_sel_hi:[1,0]
	v_pk_mul_f32 v[156:157], v[36:37], v[146:147] op_sel_hi:[1,0]
	v_pk_mul_f32 v[158:159], v[34:35], v[146:147] op_sel_hi:[1,0]
	v_pk_mul_f32 v[160:161], v[4:5], v[146:147] op_sel_hi:[1,0]
	v_pk_mul_f32 v[162:163], v[2:3], v[146:147] op_sel_hi:[1,0]
	v_mul_f32_e32 v145, 0xbfb8aa3b, v150
	v_mul_f32_e32 v146, 0xbfb8aa3b, v151
	v_exp_f32_e32 v145, v145
	v_exp_f32_e32 v146, v146
	v_mul_f32_e32 v147, 0xbfb8aa3b, v149
	v_exp_f32_e32 v147, v147
	v_add_f32_e32 v145, 1.0, v145
	v_add_f32_e32 v146, 1.0, v146
	v_rcp_f32_e32 v145, v145
	v_rcp_f32_e32 v146, v146
	v_add_f32_e32 v147, 1.0, v147
	v_rcp_f32_e32 v147, v147
	v_mul_f32_e32 v145, v150, v145
	v_mul_f32_e32 v146, v151, v146
	v_mul_f32_e32 v145, v154, v145
	v_mul_f32_e32 v146, v155, v146
	v_cvt_pk_bf16_f32 v146, v145, v146
	v_mul_f32_e32 v145, 0xbfb8aa3b, v148
	v_exp_f32_e32 v145, v145
	v_mul_f32_e32 v147, v149, v147
	v_mul_f32_e32 v147, v153, v147
	v_mul_f32_e32 v149, 0xbfb8aa3b, v157
	v_add_f32_e32 v145, 1.0, v145
	v_rcp_f32_e32 v145, v145
	v_exp_f32_e32 v149, v149
	v_mad_i64_i32 v[136:137], s[4:5], v164, s33, v[136:137]
	v_mul_f32_e32 v145, v148, v145
	v_mul_f32_e32 v145, v152, v145
	v_cvt_pk_bf16_f32 v147, v145, v147
	v_mul_f32_e32 v145, 0xbfb8aa3b, v158
	v_mul_f32_e32 v148, 0xbfb8aa3b, v159
	v_exp_f32_e32 v145, v145
	v_exp_f32_e32 v148, v148
	v_add_f32_e32 v149, 1.0, v149
	v_rcp_f32_e32 v149, v149
	v_add_f32_e32 v145, 1.0, v145
	v_add_f32_e32 v148, 1.0, v148
	v_rcp_f32_e32 v145, v145
	v_rcp_f32_e32 v148, v148
	v_mul_f32_e32 v149, v157, v149
	v_mul_f32_e32 v149, v161, v149
	v_mul_f32_e32 v145, v158, v145
	v_mul_f32_e32 v148, v159, v148
	v_mul_f32_e32 v145, v162, v145
	v_mul_f32_e32 v148, v163, v148
	v_cvt_pk_bf16_f32 v148, v145, v148
	v_mul_f32_e32 v145, 0xbfb8aa3b, v156
	v_exp_f32_e32 v145, v145
	v_lshl_add_u64 v[136:137], v[136:137], 0, v[138:139]
	v_add_f32_e32 v145, 1.0, v145
	v_rcp_f32_e32 v145, v145
	s_nop 0
	v_mul_f32_e32 v145, v156, v145
	v_mul_f32_e32 v145, v160, v145
	v_cvt_pk_bf16_f32 v149, v145, v149
	global_store_dwordx4 v[136:137], v[146:149], off
	s_cbranch_vccnz .LBB0_324
	v_mov_b32_e32 v2, 0
	s_mov_b32 s9, s61
	s_mov_b32 s8, s60
	s_mov_b64 s[12:13], s[28:29]
	s_mov_b64 s[10:11], s[34:35]
	s_mov_b32 s57, s2
	v_mov_b32_e32 v3, v2
	v_mov_b32_e32 v4, v2
	v_mov_b32_e32 v5, v2
	v_mov_b32_e32 v6, v2
	v_mov_b32_e32 v7, v2
	v_mov_b32_e32 v8, v2
	v_mov_b32_e32 v9, v2
	v_mov_b32_e32 v10, v2
	v_mov_b32_e32 v11, v2
	v_mov_b32_e32 v12, v2
	v_mov_b32_e32 v13, v2
	v_mov_b32_e32 v14, v2
	v_mov_b32_e32 v15, v2
	v_mov_b32_e32 v16, v2
	v_mov_b32_e32 v17, v2
	v_mov_b32_e32 v18, v2
	v_mov_b32_e32 v19, v2
	v_mov_b32_e32 v20, v2
	v_mov_b32_e32 v21, v2
	v_mov_b32_e32 v22, v2
	v_mov_b32_e32 v23, v2
	v_mov_b32_e32 v24, v2
	v_mov_b32_e32 v25, v2
	v_mov_b32_e32 v26, v2
	v_mov_b32_e32 v27, v2
	v_mov_b32_e32 v28, v2
	v_mov_b32_e32 v29, v2
	v_mov_b32_e32 v30, v2
	v_mov_b32_e32 v31, v2
	v_mov_b32_e32 v32, v2
	v_mov_b32_e32 v33, v2
	v_mov_b32_e32 v34, v2
	v_mov_b32_e32 v35, v2
	v_mov_b32_e32 v36, v2
	v_mov_b32_e32 v37, v2
	v_mov_b32_e32 v38, v2
	v_mov_b32_e32 v39, v2
	v_mov_b32_e32 v40, v2
	v_mov_b32_e32 v41, v2
	v_mov_b32_e32 v42, v2
	v_mov_b32_e32 v43, v2
	v_mov_b32_e32 v44, v2
	v_mov_b32_e32 v45, v2
	v_mov_b32_e32 v46, v2
	v_mov_b32_e32 v47, v2
	v_mov_b32_e32 v48, v2
	v_mov_b32_e32 v49, v2
	v_mov_b32_e32 v50, v2
	v_mov_b32_e32 v51, v2
	v_mov_b32_e32 v52, v2
	v_mov_b32_e32 v53, v2
	v_mov_b32_e32 v54, v2
	v_mov_b32_e32 v55, v2
	v_mov_b32_e32 v56, v2
	v_mov_b32_e32 v57, v2
	v_mov_b32_e32 v58, v2
	v_mov_b32_e32 v59, v2
	v_mov_b32_e32 v60, v2
	v_mov_b32_e32 v61, v2
	v_mov_b32_e32 v62, v2
	v_mov_b32_e32 v63, v2
	v_mov_b32_e32 v64, v2
	v_mov_b32_e32 v65, v2
	v_mov_b32_e32 v66, v2
	v_mov_b32_e32 v67, v2
	v_mov_b32_e32 v68, v2
	v_mov_b32_e32 v69, v2
	v_mov_b32_e32 v70, v2
	v_mov_b32_e32 v71, v2
	v_mov_b32_e32 v72, v2
	v_mov_b32_e32 v73, v2
	v_mov_b32_e32 v74, v2
	v_mov_b32_e32 v75, v2
	v_mov_b32_e32 v76, v2
	v_mov_b32_e32 v77, v2
	v_mov_b32_e32 v78, v2
	v_mov_b32_e32 v79, v2
	v_mov_b32_e32 v80, v2
	v_mov_b32_e32 v81, v2
	v_mov_b32_e32 v82, v2
	v_mov_b32_e32 v83, v2
	v_mov_b32_e32 v84, v2
	v_mov_b32_e32 v85, v2
	v_mov_b32_e32 v86, v2
	v_mov_b32_e32 v87, v2
	v_mov_b32_e32 v88, v2
	v_mov_b32_e32 v89, v2
	v_mov_b32_e32 v90, v2
	v_mov_b32_e32 v91, v2
	v_mov_b32_e32 v92, v2
	v_mov_b32_e32 v93, v2
	v_mov_b32_e32 v94, v2
	v_mov_b32_e32 v95, v2
	v_mov_b32_e32 v96, v2
	v_mov_b32_e32 v97, v2
	v_mov_b32_e32 v98, v2
	v_mov_b32_e32 v99, v2
	v_mov_b32_e32 v100, v2
	v_mov_b32_e32 v101, v2
	v_mov_b32_e32 v102, v2
	v_mov_b32_e32 v103, v2
	v_mov_b32_e32 v104, v2
	v_mov_b32_e32 v105, v2
	v_mov_b32_e32 v106, v2
	v_mov_b32_e32 v107, v2
	v_mov_b32_e32 v108, v2
	v_mov_b32_e32 v109, v2
	v_mov_b32_e32 v110, v2
	v_mov_b32_e32 v111, v2
	v_mov_b32_e32 v112, v2
	v_mov_b32_e32 v113, v2
	v_mov_b32_e32 v114, v2
	v_mov_b32_e32 v115, v2
	v_mov_b32_e32 v116, v2
	v_mov_b32_e32 v117, v2
	v_mov_b32_e32 v118, v2
	v_mov_b32_e32 v119, v2
	v_mov_b32_e32 v120, v2
	v_mov_b32_e32 v121, v2
	v_mov_b32_e32 v122, v2
	v_mov_b32_e32 v123, v2
	v_mov_b32_e32 v124, v2
	v_mov_b32_e32 v125, v2
	v_mov_b32_e32 v126, v2
	v_mov_b32_e32 v127, v2
	v_mov_b32_e32 v128, v2
	v_mov_b32_e32 v129, v2
	s_branch .LBB0_324
